# 4-phase GEMM loops, ph8 staging moved from the MFMA segment into the phase-4 load segment (address temp renamed to a dead pair)
# speedup vs baseline: 1.0290x; 1.0036x over previous
; #define PG8_STAGE(bufoff, gbase, voff) do { _Pragma("unroll") for (int _i = 0; _i < 2; ++_i) \
;         __builtin_amdgcn_global_load_lds((const unsigned*)((const char*)(gbase) + (voff)[_i]), (LAS unsigned*)(lds + (bufoff) + ldsw + _i * 8192), 16, 0, 0); } while (0)
; #define PG8_LDA(dst, b, h) do { _Pragma("unroll") for (int m = 0; m < 4; ++m) _Pragma("unroll") for (int k = 0; k < 2; ++k) dst[m][k] = *(const LAS bf16x8*)(lds + PG8_SA(b, h) + aoff + m * 2048 + k * 1024); } while (0)
; #define PG8_LDB(dst, b, h) do { _Pragma("unroll") for (int n = 0; n < 2; ++n) _Pragma("unroll") for (int k = 0; k < 2; ++k) dst[n][k] = *(const LAS bf16x8*)(lds + PG8_SB(b, h) + boff + n * 2048 + k * 1024); } while (0)
; #define PG8_MMA(ai, bj, At, Bt) do { __builtin_amdgcn_s_setprio(1); _Pragma("unroll") for (int m = 0; m < 4; ++m) _Pragma("unroll") for (int n = 0; n < 2; ++n) _Pragma("unroll") for (int k = 0; k < 2; ++k) \
;         acc[ai][bj][m][n] = __builtin_amdgcn_mfma_f32_16x16x32_bf16(Bt[n][k], At[m][k], acc[ai][bj][m][n], 0, 0, 0); __builtin_amdgcn_s_setprio(0); } while (0)
; #define PG8_WAIT_V(n) asm volatile("s_waitcnt vmcnt(" #n ")" ::: "memory")
; #define PG8_WAIT_L(n) asm volatile("s_waitcnt lgkmcnt(" #n ")" ::: "memory")
; template <class Epi, class Sched>
; __device__ __forceinline__ void gemm_phase(LAS unsigned char* lds, const Gemm g, const Sched& S, const Epi& E) {
;     ...
;         for (int t = 0; t < nt; t += 2) {
;             const bool last = (t == nt - 2);
;             const char* a1 = cA + (size_t)(t + 1) * kstep;
;             const char* a2 = last ? nA : cA + (size_t)(t + 2) * kstep; const char* b2 = last ? nB : cB + (size_t)(t + 2) * kstep;
;             const char* a3 = a2 + kstep; const char* b3 = b2 + kstep;
;             PG8_LDB(B0, 0, 0); PG8_SCHED; PG8_LDA(At, 0, 0); PG8_STAGE(PG8_SA(1, 1), a1 + hstep, voffA);
;             PG8_WAIT_L(8); PG8_BAR; PG8_WAIT_L(0); PG8_MMA(0, 0, At, B0); PG8_BAR; PG8_SCHED;
;             PG8_LDB(B1, 0, 1); PG8_STAGE(PG8_SB(0, 0), b2, voffB);
;             PG8_BAR; PG8_WAIT_L(0); PG8_MMA(0, 1, At, B1); PG8_BAR;
;             PG8_LDA(At, 0, 1); PG8_STAGE(PG8_SA(0, 0), a2, voffA);
;             PG8_BAR; PG8_WAIT_L(0); PG8_MMA(1, 0, At, B0); PG8_BAR; PG8_SCHED;
;             PG8_STAGE(PG8_SB(0, 1), b2 + hstep, voffB);
;             PG8_WAIT_V(6); PG8_BAR; PG8_MMA(1, 1, At, B1); PG8_BAR;
.LBB0_44:
	s_add_u32 s50, s28, 0x100
	s_addc_u32 s51, s29, 0
	s_cmpk_eq_i32 s75, 0x7c
	s_cselect_b32 s55, s27, s51
	s_cselect_b32 s54, s71, s50
	s_cselect_b32 s53, s25, s74
	s_cselect_b32 s52, s72, s73
	v_lshl_add_u64 v[156:157], s[28:29], 0, v[150:151]
	s_add_i32 m0, s9, 0xc000
	s_nop 0
	global_load_lds_dwordx4 v[156:157], off
	v_lshl_add_u64 v[156:157], s[28:29], 0, v[148:149]
	s_add_i32 m0, s9, 0xe000
	s_nop 0
	global_load_lds_dwordx4 v[156:157], off
	s_add_i32 s38, 0, 0x10000
	v_add_u32_e32 v78, s38, v163
	ds_read_b128 v[66:69], v78
	ds_read_b128 v[70:73], v78 offset:1024
	ds_read_b128 v[74:77], v78 offset:2048
	ds_read_b128 v[78:81], v78 offset:3072
	ds_read_b128 v[152:155], v165
	ds_read_b128 v[166:169], v165 offset:1024
	ds_read_b128 v[170:173], v165 offset:2048
	ds_read_b128 v[174:177], v165 offset:3072
	ds_read_b128 v[178:181], v165 offset:4096
	ds_read_b128 v[182:185], v165 offset:5120
	ds_read_b128 v[186:189], v165 offset:6144
	ds_read_b128 v[190:193], v165 offset:7168
	s_add_i32 s39, 0, 0x14000
	v_add_u32_e32 v156, s39, v163
	ds_read_b128 v[194:197], v156
	ds_read_b128 v[198:201], v156 offset:1024
	ds_read_b128 v[202:205], v156 offset:2048
	ds_read_b128 v[210:213], v156 offset:3072
	s_waitcnt lgkmcnt(0)
	s_barrier
	s_setprio 1
	v_mfma_f32_16x16x32_bf16 v[142:145], v[66:69], v[152:155], v[142:145]
	v_mfma_f32_16x16x32_bf16 v[138:141], v[74:77], v[152:155], v[138:141]
	v_mfma_f32_16x16x32_bf16 v[126:129], v[66:69], v[170:173], v[126:129]
	v_mfma_f32_16x16x32_bf16 v[122:125], v[74:77], v[170:173], v[122:125]
	v_mfma_f32_16x16x32_bf16 v[110:113], v[66:69], v[178:181], v[110:113]
	v_mfma_f32_16x16x32_bf16 v[106:109], v[74:77], v[178:181], v[106:109]
	v_mfma_f32_16x16x32_bf16 v[102:105], v[66:69], v[186:189], v[102:105]
	v_mfma_f32_16x16x32_bf16 v[98:101], v[74:77], v[186:189], v[98:101]
	v_mfma_f32_16x16x32_bf16 v[142:145], v[70:73], v[166:169], v[142:145]
	v_mfma_f32_16x16x32_bf16 v[138:141], v[78:81], v[166:169], v[138:141]
	v_mfma_f32_16x16x32_bf16 v[126:129], v[70:73], v[174:177], v[126:129]
	v_mfma_f32_16x16x32_bf16 v[122:125], v[78:81], v[174:177], v[122:125]
	v_mfma_f32_16x16x32_bf16 v[110:113], v[70:73], v[182:185], v[110:113]
	v_mfma_f32_16x16x32_bf16 v[106:109], v[78:81], v[182:185], v[106:109]
	v_mfma_f32_16x16x32_bf16 v[102:105], v[70:73], v[190:193], v[102:105]
	v_mfma_f32_16x16x32_bf16 v[98:101], v[78:81], v[190:193], v[98:101]
	v_mfma_f32_16x16x32_bf16 v[134:137], v[194:197], v[152:155], v[134:137]
	v_mfma_f32_16x16x32_bf16 v[130:133], v[202:205], v[152:155], v[130:133]
	v_mfma_f32_16x16x32_bf16 v[118:121], v[194:197], v[170:173], v[118:121]
	v_mfma_f32_16x16x32_bf16 v[114:117], v[202:205], v[170:173], v[114:117]
	v_mfma_f32_16x16x32_bf16 v[94:97], v[194:197], v[178:181], v[94:97]
	v_mfma_f32_16x16x32_bf16 v[90:93], v[202:205], v[178:181], v[90:93]
	v_mfma_f32_16x16x32_bf16 v[86:89], v[194:197], v[186:189], v[86:89]
	v_mfma_f32_16x16x32_bf16 v[82:85], v[202:205], v[186:189], v[82:85]
	v_mfma_f32_16x16x32_bf16 v[134:137], v[198:201], v[166:169], v[134:137]
	v_mfma_f32_16x16x32_bf16 v[130:133], v[210:213], v[166:169], v[130:133]
	v_mfma_f32_16x16x32_bf16 v[118:121], v[198:201], v[174:177], v[118:121]
	v_mfma_f32_16x16x32_bf16 v[114:117], v[210:213], v[174:177], v[114:117]
	v_mfma_f32_16x16x32_bf16 v[94:97], v[198:201], v[182:185], v[94:97]
	v_mfma_f32_16x16x32_bf16 v[90:93], v[210:213], v[182:185], v[90:93]
	v_mfma_f32_16x16x32_bf16 v[86:89], v[198:201], v[190:193], v[86:89]
	v_mfma_f32_16x16x32_bf16 v[82:85], v[210:213], v[190:193], v[82:85]
	s_setprio 0
	s_barrier
	s_add_i32 s28, s38, s60
	v_lshl_add_u64 v[156:157], s[52:53], 0, v[0:1]
	s_mov_b32 m0, s28
	v_lshl_add_u64 v[160:161], s[52:53], 0, v[146:147]
	global_load_lds_dwordx4 v[156:157], off
	s_add_i32 m0, s28, 0x2000
	s_nop 0
	global_load_lds_dwordx4 v[160:161], off
	s_mov_b32 m0, s9
	v_lshl_add_u64 v[206:207], s[54:55], 0, v[0:1]
	global_load_lds_dwordx4 v[206:207], off
	v_lshl_add_u64 v[214:215], s[54:55], 0, v[146:147]
	s_mov_b32 m0, s61
	s_nop 0
	global_load_lds_dwordx4 v[214:215], off
	ds_read_b128 v[152:155], v165 offset:16384
	ds_read_b128 v[166:169], v165 offset:17408
	ds_read_b128 v[170:173], v165 offset:18432
	ds_read_b128 v[174:177], v165 offset:19456
	ds_read_b128 v[178:181], v165 offset:20480
	ds_read_b128 v[182:185], v165 offset:21504
	ds_read_b128 v[186:189], v165 offset:22528
	ds_read_b128 v[190:193], v165 offset:23552
	s_waitcnt vmcnt(4)
	s_waitcnt lgkmcnt(0)
	s_barrier
	s_setprio 1
	v_mfma_f32_16x16x32_bf16 v[62:65], v[66:69], v[152:155], v[62:65]
	v_mfma_f32_16x16x32_bf16 v[58:61], v[74:77], v[152:155], v[58:61]
	v_mfma_f32_16x16x32_bf16 v[46:49], v[66:69], v[170:173], v[46:49]
	v_mfma_f32_16x16x32_bf16 v[42:45], v[74:77], v[170:173], v[42:45]
	v_mfma_f32_16x16x32_bf16 v[30:33], v[66:69], v[178:181], v[30:33]
	v_mfma_f32_16x16x32_bf16 v[26:29], v[74:77], v[178:181], v[26:29]
	v_mfma_f32_16x16x32_bf16 v[22:25], v[66:69], v[186:189], v[22:25]
	v_mfma_f32_16x16x32_bf16 v[14:17], v[74:77], v[186:189], v[14:17]
	v_mfma_f32_16x16x32_bf16 v[62:65], v[70:73], v[166:169], v[62:65]
	v_mfma_f32_16x16x32_bf16 v[58:61], v[78:81], v[166:169], v[58:61]
	v_mfma_f32_16x16x32_bf16 v[46:49], v[70:73], v[174:177], v[46:49]
	v_mfma_f32_16x16x32_bf16 v[42:45], v[78:81], v[174:177], v[42:45]
	v_mfma_f32_16x16x32_bf16 v[30:33], v[70:73], v[182:185], v[30:33]
	v_mfma_f32_16x16x32_bf16 v[26:29], v[78:81], v[182:185], v[26:29]
	v_mfma_f32_16x16x32_bf16 v[22:25], v[70:73], v[190:193], v[22:25]
	v_mfma_f32_16x16x32_bf16 v[14:17], v[78:81], v[190:193], v[14:17]
	v_mfma_f32_16x16x32_bf16 v[54:57], v[194:197], v[152:155], v[54:57]
	v_mfma_f32_16x16x32_bf16 v[50:53], v[202:205], v[152:155], v[50:53]
	v_mfma_f32_16x16x32_bf16 v[38:41], v[194:197], v[170:173], v[38:41]
	v_mfma_f32_16x16x32_bf16 v[34:37], v[202:205], v[170:173], v[34:37]
	v_mfma_f32_16x16x32_bf16 v[18:21], v[194:197], v[178:181], v[18:21]
	v_mfma_f32_16x16x32_bf16 v[10:13], v[202:205], v[178:181], v[10:13]
	v_mfma_f32_16x16x32_bf16 v[6:9], v[194:197], v[186:189], v[6:9]
	v_mfma_f32_16x16x32_bf16 v[2:5], v[202:205], v[186:189], v[2:5]
	v_mfma_f32_16x16x32_bf16 v[54:57], v[198:201], v[166:169], v[54:57]
	v_mfma_f32_16x16x32_bf16 v[50:53], v[210:213], v[166:169], v[50:53]
	v_mfma_f32_16x16x32_bf16 v[38:41], v[198:201], v[174:177], v[38:41]
	v_mfma_f32_16x16x32_bf16 v[34:37], v[210:213], v[174:177], v[34:37]
	v_mfma_f32_16x16x32_bf16 v[18:21], v[198:201], v[182:185], v[18:21]
	v_mfma_f32_16x16x32_bf16 v[10:13], v[210:213], v[182:185], v[10:13]
	v_mfma_f32_16x16x32_bf16 v[6:9], v[198:201], v[190:193], v[6:9]
	v_mfma_f32_16x16x32_bf16 v[2:5], v[210:213], v[190:193], v[2:5]
	s_setprio 0
	s_barrier
; #define PG8_STAGE(bufoff, gbase, voff) do { _Pragma("unroll") for (int _i = 0; _i < 2; ++_i) \
;         __builtin_amdgcn_global_load_lds((const unsigned*)((const char*)(gbase) + (voff)[_i]), (LAS unsigned*)(lds + (bufoff) + ldsw + _i * 8192), 16, 0, 0); } while (0)
; #define PG8_LDA(dst, b, h) do { _Pragma("unroll") for (int m = 0; m < 4; ++m) _Pragma("unroll") for (int k = 0; k < 2; ++k) dst[m][k] = *(const LAS bf16x8*)(lds + PG8_SA(b, h) + aoff + m * 2048 + k * 1024); } while (0)
; #define PG8_LDB(dst, b, h) do { _Pragma("unroll") for (int n = 0; n < 2; ++n) _Pragma("unroll") for (int k = 0; k < 2; ++k) dst[n][k] = *(const LAS bf16x8*)(lds + PG8_SB(b, h) + boff + n * 2048 + k * 1024); } while (0)
; #define PG8_MMA(ai, bj, At, Bt) do { __builtin_amdgcn_s_setprio(1); _Pragma("unroll") for (int m = 0; m < 4; ++m) _Pragma("unroll") for (int n = 0; n < 2; ++n) _Pragma("unroll") for (int k = 0; k < 2; ++k) \
;         acc[ai][bj][m][n] = __builtin_amdgcn_mfma_f32_16x16x32_bf16(Bt[n][k], At[m][k], acc[ai][bj][m][n], 0, 0, 0); __builtin_amdgcn_s_setprio(0); } while (0)
; #define PG8_WAIT_L(n) asm volatile("s_waitcnt lgkmcnt(" #n ")" ::: "memory")
; #define PG8_BAR __builtin_amdgcn_s_barrier()
; #define PG8_SCHED __builtin_amdgcn_sched_barrier(0)
; template <class Epi, class Sched>
; __device__ __forceinline__ void gemm_phase(LAS unsigned char* lds, const Gemm g, const Sched& S, const Epi& E) {
;     ...
;             PG8_LDB(B0, 1, 0); PG8_SCHED; PG8_LDA(At, 1, 0); PG8_STAGE(PG8_SA(0, 1), a2 + hstep, voffA);
;             PG8_WAIT_L(8); PG8_BAR; PG8_WAIT_L(0); PG8_MMA(0, 0, At, B0); PG8_BAR; PG8_SCHED;
;             PG8_LDB(B1, 1, 1); PG8_STAGE(PG8_SB(1, 0), b3, voffB);
;             PG8_BAR; PG8_WAIT_L(0); PG8_MMA(0, 1, At, B1); PG8_BAR;
	s_add_u32 s28, s52, 0x200000
	s_addc_u32 s29, s53, 0
	s_add_i32 s38, s39, s60
	v_lshl_add_u64 v[66:67], s[28:29], 0, v[0:1]
	s_mov_b32 m0, s38
	s_nop 0
	global_load_lds_dwordx4 v[66:67], off
	v_lshl_add_u64 v[66:67], s[28:29], 0, v[146:147]
	s_add_i32 m0, s38, 0x2000
	s_nop 0
	global_load_lds_dwordx4 v[66:67], off
	s_add_u32 s28, s54, 0x200000
	s_addc_u32 s29, s55, 0
	s_mov_b32 m0, s62
	v_lshl_add_u64 v[194:195], s[28:29], 0, v[0:1]
	global_load_lds_dwordx4 v[194:195], off
	v_lshl_add_u64 v[194:195], s[28:29], 0, v[146:147]
	s_mov_b32 m0, s63
	s_nop 0
	global_load_lds_dwordx4 v[194:195], off
	s_add_i32 s38, 0, 0x18000
	v_add_u32_e32 v78, s38, v163
	ds_read_b128 v[66:69], v78
	ds_read_b128 v[70:73], v78 offset:1024
	ds_read_b128 v[74:77], v78 offset:2048
	ds_read_b128 v[78:81], v78 offset:3072
	ds_read_b128 v[152:155], v165 offset:32768
	ds_read_b128 v[166:169], v165 offset:33792
	ds_read_b128 v[170:173], v165 offset:34816
	ds_read_b128 v[174:177], v165 offset:35840
	ds_read_b128 v[178:181], v165 offset:36864
	ds_read_b128 v[182:185], v165 offset:37888
	ds_read_b128 v[186:189], v165 offset:38912
	ds_read_b128 v[190:193], v165 offset:39936
	s_add_i32 s39, 0, 0x1c000
	v_add_u32_e32 v210, s39, v163
	ds_read_b128 v[194:197], v210
	ds_read_b128 v[198:201], v210 offset:1024
	ds_read_b128 v[202:205], v210 offset:2048
	ds_read_b128 v[210:213], v210 offset:3072
	s_waitcnt lgkmcnt(0)
	s_barrier
	s_setprio 1
	v_mfma_f32_16x16x32_bf16 v[142:145], v[66:69], v[152:155], v[142:145]
	v_mfma_f32_16x16x32_bf16 v[138:141], v[74:77], v[152:155], v[138:141]
	v_mfma_f32_16x16x32_bf16 v[126:129], v[66:69], v[170:173], v[126:129]
	v_mfma_f32_16x16x32_bf16 v[122:125], v[74:77], v[170:173], v[122:125]
	v_mfma_f32_16x16x32_bf16 v[110:113], v[66:69], v[178:181], v[110:113]
	v_mfma_f32_16x16x32_bf16 v[106:109], v[74:77], v[178:181], v[106:109]
	v_mfma_f32_16x16x32_bf16 v[102:105], v[66:69], v[186:189], v[102:105]
	v_mfma_f32_16x16x32_bf16 v[98:101], v[74:77], v[186:189], v[98:101]
	v_mfma_f32_16x16x32_bf16 v[142:145], v[70:73], v[166:169], v[142:145]
	v_mfma_f32_16x16x32_bf16 v[138:141], v[78:81], v[166:169], v[138:141]
	v_mfma_f32_16x16x32_bf16 v[126:129], v[70:73], v[174:177], v[126:129]
	v_mfma_f32_16x16x32_bf16 v[122:125], v[78:81], v[174:177], v[122:125]
	v_mfma_f32_16x16x32_bf16 v[110:113], v[70:73], v[182:185], v[110:113]
	v_mfma_f32_16x16x32_bf16 v[106:109], v[78:81], v[182:185], v[106:109]
	v_mfma_f32_16x16x32_bf16 v[102:105], v[70:73], v[190:193], v[102:105]
	v_mfma_f32_16x16x32_bf16 v[98:101], v[78:81], v[190:193], v[98:101]
	v_mfma_f32_16x16x32_bf16 v[134:137], v[194:197], v[152:155], v[134:137]
	v_mfma_f32_16x16x32_bf16 v[130:133], v[202:205], v[152:155], v[130:133]
	v_mfma_f32_16x16x32_bf16 v[118:121], v[194:197], v[170:173], v[118:121]
	v_mfma_f32_16x16x32_bf16 v[114:117], v[202:205], v[170:173], v[114:117]
	v_mfma_f32_16x16x32_bf16 v[94:97], v[194:197], v[178:181], v[94:97]
	v_mfma_f32_16x16x32_bf16 v[90:93], v[202:205], v[178:181], v[90:93]
	v_mfma_f32_16x16x32_bf16 v[86:89], v[194:197], v[186:189], v[86:89]
	v_mfma_f32_16x16x32_bf16 v[82:85], v[202:205], v[186:189], v[82:85]
	v_mfma_f32_16x16x32_bf16 v[134:137], v[198:201], v[166:169], v[134:137]
	v_mfma_f32_16x16x32_bf16 v[130:133], v[210:213], v[166:169], v[130:133]
	v_mfma_f32_16x16x32_bf16 v[118:121], v[198:201], v[174:177], v[118:121]
	v_mfma_f32_16x16x32_bf16 v[114:117], v[210:213], v[174:177], v[114:117]
	v_mfma_f32_16x16x32_bf16 v[94:97], v[198:201], v[182:185], v[94:97]
	v_mfma_f32_16x16x32_bf16 v[90:93], v[210:213], v[182:185], v[90:93]
	v_mfma_f32_16x16x32_bf16 v[86:89], v[198:201], v[190:193], v[86:89]
	v_mfma_f32_16x16x32_bf16 v[82:85], v[210:213], v[190:193], v[82:85]
	s_setprio 0
	s_barrier
; #define PG8_STAGE(bufoff, gbase, voff) do { _Pragma("unroll") for (int _i = 0; _i < 2; ++_i) \
;         __builtin_amdgcn_global_load_lds((const unsigned*)((const char*)(gbase) + (voff)[_i]), (LAS unsigned*)(lds + (bufoff) + ldsw + _i * 8192), 16, 0, 0); } while (0)
; #define PG8_LDA(dst, b, h) do { _Pragma("unroll") for (int m = 0; m < 4; ++m) _Pragma("unroll") for (int k = 0; k < 2; ++k) dst[m][k] = *(const LAS bf16x8*)(lds + PG8_SA(b, h) + aoff + m * 2048 + k * 1024); } while (0)
; #define PG8_MMA(ai, bj, At, Bt) do { __builtin_amdgcn_s_setprio(1); _Pragma("unroll") for (int m = 0; m < 4; ++m) _Pragma("unroll") for (int n = 0; n < 2; ++n) _Pragma("unroll") for (int k = 0; k < 2; ++k) \
;         acc[ai][bj][m][n] = __builtin_amdgcn_mfma_f32_16x16x32_bf16(Bt[n][k], At[m][k], acc[ai][bj][m][n], 0, 0, 0); __builtin_amdgcn_s_setprio(0); } while (0)
; #define PG8_WAIT_V(n) asm volatile("s_waitcnt vmcnt(" #n ")" ::: "memory")
; #define PG8_WAIT_L(n) asm volatile("s_waitcnt lgkmcnt(" #n ")" ::: "memory")
; #define PG8_BAR __builtin_amdgcn_s_barrier()
; #define PG8_SCHED __builtin_amdgcn_sched_barrier(0)
; template <class Epi, class Sched>
; __device__ __forceinline__ void gemm_phase(LAS unsigned char* lds, const Gemm g, const Sched& S, const Epi& E) {
;     ...
;             PG8_LDA(At, 1, 1); PG8_STAGE(PG8_SA(1, 0), a3, voffA);
;             PG8_BAR; PG8_WAIT_L(0); PG8_MMA(1, 0, At, B0); PG8_BAR; PG8_SCHED;
;             PG8_STAGE(PG8_SB(1, 1), b3 + hstep, voffB);
;             PG8_WAIT_V(6); PG8_BAR; PG8_MMA(1, 1, At, B1); PG8_BAR;
;         }
;         E(acc, cur, wr, wc, fr, fq);
;         if (!has_next) break;
	s_add_i32 s28, s38, s60
	v_lshl_add_u64 v[156:157], v[156:157], 0, s[36:37]
	s_mov_b32 m0, s28
	s_nop 0
	global_load_lds_dwordx4 v[156:157], off
	v_lshl_add_u64 v[156:157], v[160:161], 0, s[36:37]
	s_add_i32 m0, s28, 0x2000
	s_nop 0
	global_load_lds_dwordx4 v[156:157], off
	s_mov_b32 m0, s66
	v_lshl_add_u64 v[156:157], v[206:207], 0, s[36:37]
	global_load_lds_dwordx4 v[156:157], off
	v_lshl_add_u64 v[156:157], v[214:215], 0, s[36:37]
	s_mov_b32 m0, s67
	s_nop 0
	global_load_lds_dwordx4 v[156:157], off
	s_add_u32 s28, s52, 0x200080
	s_addc_u32 s29, s53, 0
	s_add_i32 s38, s39, s60
	v_lshl_add_u64 v[156:157], s[28:29], 0, v[0:1]
	s_mov_b32 m0, s38
	s_nop 0
	global_load_lds_dwordx4 v[156:157], off
	v_lshl_add_u64 v[156:157], s[28:29], 0, v[146:147]
	s_add_i32 m0, s38, 0x2000
	s_nop 0
	global_load_lds_dwordx4 v[156:157], off
	ds_read_b128 v[152:155], v165 offset:49152
	ds_read_b128 v[166:169], v165 offset:50176
	ds_read_b128 v[170:173], v165 offset:51200
	ds_read_b128 v[174:177], v165 offset:52224
	ds_read_b128 v[178:181], v165 offset:53248
	ds_read_b128 v[182:185], v165 offset:54272
	ds_read_b128 v[186:189], v165 offset:55296
	ds_read_b128 v[190:193], v165 offset:56320
	s_waitcnt vmcnt(6)
	s_waitcnt lgkmcnt(0)
	s_barrier
	s_setprio 1
	v_mfma_f32_16x16x32_bf16 v[62:65], v[66:69], v[152:155], v[62:65]
	v_mfma_f32_16x16x32_bf16 v[58:61], v[74:77], v[152:155], v[58:61]
	v_mfma_f32_16x16x32_bf16 v[46:49], v[66:69], v[170:173], v[46:49]
	v_mfma_f32_16x16x32_bf16 v[42:45], v[74:77], v[170:173], v[42:45]
	v_mfma_f32_16x16x32_bf16 v[30:33], v[66:69], v[178:181], v[30:33]
	v_mfma_f32_16x16x32_bf16 v[26:29], v[74:77], v[178:181], v[26:29]
	v_mfma_f32_16x16x32_bf16 v[22:25], v[66:69], v[186:189], v[22:25]
	v_mfma_f32_16x16x32_bf16 v[14:17], v[74:77], v[186:189], v[14:17]
	v_mfma_f32_16x16x32_bf16 v[62:65], v[70:73], v[166:169], v[62:65]
	v_mfma_f32_16x16x32_bf16 v[58:61], v[78:81], v[166:169], v[58:61]
	v_mfma_f32_16x16x32_bf16 v[46:49], v[70:73], v[174:177], v[46:49]
	v_mfma_f32_16x16x32_bf16 v[42:45], v[78:81], v[174:177], v[42:45]
	v_mfma_f32_16x16x32_bf16 v[30:33], v[70:73], v[182:185], v[30:33]
	v_mfma_f32_16x16x32_bf16 v[26:29], v[78:81], v[182:185], v[26:29]
	v_mfma_f32_16x16x32_bf16 v[22:25], v[70:73], v[190:193], v[22:25]
	v_mfma_f32_16x16x32_bf16 v[14:17], v[78:81], v[190:193], v[14:17]
	v_mfma_f32_16x16x32_bf16 v[54:57], v[194:197], v[152:155], v[54:57]
	v_mfma_f32_16x16x32_bf16 v[50:53], v[202:205], v[152:155], v[50:53]
	v_mfma_f32_16x16x32_bf16 v[38:41], v[194:197], v[170:173], v[38:41]
	v_mfma_f32_16x16x32_bf16 v[34:37], v[202:205], v[170:173], v[34:37]
	v_mfma_f32_16x16x32_bf16 v[18:21], v[194:197], v[178:181], v[18:21]
	v_mfma_f32_16x16x32_bf16 v[10:13], v[202:205], v[178:181], v[10:13]
	v_mfma_f32_16x16x32_bf16 v[6:9], v[194:197], v[186:189], v[6:9]
	v_mfma_f32_16x16x32_bf16 v[2:5], v[202:205], v[186:189], v[2:5]
	v_mfma_f32_16x16x32_bf16 v[54:57], v[198:201], v[166:169], v[54:57]
	v_mfma_f32_16x16x32_bf16 v[50:53], v[210:213], v[166:169], v[50:53]
	v_mfma_f32_16x16x32_bf16 v[38:41], v[198:201], v[174:177], v[38:41]
	v_mfma_f32_16x16x32_bf16 v[34:37], v[210:213], v[174:177], v[34:37]
	v_mfma_f32_16x16x32_bf16 v[18:21], v[198:201], v[182:185], v[18:21]
	v_mfma_f32_16x16x32_bf16 v[10:13], v[210:213], v[182:185], v[10:13]
	v_mfma_f32_16x16x32_bf16 v[6:9], v[198:201], v[190:193], v[6:9]
	v_mfma_f32_16x16x32_bf16 v[2:5], v[210:213], v[190:193], v[2:5]
	s_setprio 0
	s_add_i32 s75, s75, 2
	s_add_u32 s73, s73, 0x100
	s_addc_u32 s74, s74, 0
	s_cmpk_gt_u32 s75, 0x7d
	s_mov_b64 s[28:29], s[50:51]
	s_barrier
	s_cbranch_scc0 .LBB0_44
	s_cmp_lt_i32 s8, 64
	s_cselect_b64 s[50:51], -1, 0
	s_cmp_gt_i32 s8, 63
	s_cbranch_scc0 .LBB0_35
	s_mov_b64 s[52:53], 0x18000
	s_mov_b64 s[28:29], s[46:47]
	s_branch .LBB0_36

; #define PG8_STAGE(bufoff, gbase, voff) do { _Pragma("unroll") for (int _i = 0; _i < 2; ++_i) \
;         __builtin_amdgcn_global_load_lds((const unsigned*)((const char*)(gbase) + (voff)[_i]), (LAS unsigned*)(lds + (bufoff) + ldsw + _i * 8192), 16, 0, 0); } while (0)
; #define PG8_LDA(dst, b, h) do { _Pragma("unroll") for (int m = 0; m < 4; ++m) _Pragma("unroll") for (int k = 0; k < 2; ++k) dst[m][k] = *(const LAS bf16x8*)(lds + PG8_SA(b, h) + aoff + m * 2048 + k * 1024); } while (0)
; #define PG8_LDB(dst, b, h) do { _Pragma("unroll") for (int n = 0; n < 2; ++n) _Pragma("unroll") for (int k = 0; k < 2; ++k) dst[n][k] = *(const LAS bf16x8*)(lds + PG8_SB(b, h) + boff + n * 2048 + k * 1024); } while (0)
; #define PG8_MMA(ai, bj, At, Bt) do { __builtin_amdgcn_s_setprio(1); _Pragma("unroll") for (int m = 0; m < 4; ++m) _Pragma("unroll") for (int n = 0; n < 2; ++n) _Pragma("unroll") for (int k = 0; k < 2; ++k) \
;         acc[ai][bj][m][n] = __builtin_amdgcn_mfma_f32_16x16x32_bf16(Bt[n][k], At[m][k], acc[ai][bj][m][n], 0, 0, 0); __builtin_amdgcn_s_setprio(0); } while (0)
; #define PG8_WAIT_V(n) asm volatile("s_waitcnt vmcnt(" #n ")" ::: "memory")
; #define PG8_WAIT_L(n) asm volatile("s_waitcnt lgkmcnt(" #n ")" ::: "memory")
; template <class Epi, class Sched>
; __device__ __forceinline__ void gemm_phase(LAS unsigned char* lds, const Gemm g, const Sched& S, const Epi& E) {
;     ...
;         for (int t = 0; t < nt; t += 2) {
;             const bool last = (t == nt - 2);
;             const char* a1 = cA + (size_t)(t + 1) * kstep;
;             const char* a2 = last ? nA : cA + (size_t)(t + 2) * kstep; const char* b2 = last ? nB : cB + (size_t)(t + 2) * kstep;
;             const char* a3 = a2 + kstep; const char* b3 = b2 + kstep;
;             PG8_LDB(B0, 0, 0); PG8_SCHED; PG8_LDA(At, 0, 0); PG8_STAGE(PG8_SA(1, 1), a1 + hstep, voffA);
;             PG8_WAIT_L(8); PG8_BAR; PG8_WAIT_L(0); PG8_MMA(0, 0, At, B0); PG8_BAR; PG8_SCHED;
;             PG8_LDB(B1, 0, 1); PG8_STAGE(PG8_SB(0, 0), b2, voffB);
;             PG8_BAR; PG8_WAIT_L(0); PG8_MMA(0, 1, At, B1); PG8_BAR;
;             PG8_LDA(At, 0, 1); PG8_STAGE(PG8_SA(0, 0), a2, voffA);
;             PG8_BAR; PG8_WAIT_L(0); PG8_MMA(1, 0, At, B0); PG8_BAR; PG8_SCHED;
;             PG8_STAGE(PG8_SB(0, 1), b2 + hstep, voffB);
;             PG8_WAIT_V(6); PG8_BAR; PG8_MMA(1, 1, At, B1); PG8_BAR;
.LBB0_58:
	s_add_u32 s52, s50, 0x100
	s_addc_u32 s53, s51, 0
	s_cmp_eq_u32 s71, 28
	s_cselect_b32 s57, s11, s53
	s_cselect_b32 s56, s29, s52
	s_cselect_b32 s55, s41, s70
	s_cselect_b32 s54, s43, s69
	v_lshl_add_u64 v[156:157], s[50:51], 0, v[134:135]
	s_add_i32 m0, s25, 0xc000
	s_nop 0
	global_load_lds_dwordx4 v[156:157], off
	v_lshl_add_u64 v[156:157], s[50:51], 0, v[132:133]
	s_add_i32 m0, s25, 0xe000
	s_nop 0
	global_load_lds_dwordx4 v[156:157], off
	s_add_i32 s38, 0, 0x10000
	v_add_u32_e32 v152, s38, v137
	ds_read_b128 v[140:143], v152
	ds_read_b128 v[144:147], v152 offset:1024
	ds_read_b128 v[148:151], v152 offset:2048
	ds_read_b128 v[152:155], v152 offset:3072
	ds_read_b128 v[160:163], v139
	ds_read_b128 v[164:167], v139 offset:1024
	ds_read_b128 v[168:171], v139 offset:2048
	ds_read_b128 v[172:175], v139 offset:3072
	ds_read_b128 v[176:179], v139 offset:4096
	ds_read_b128 v[180:183], v139 offset:5120
	ds_read_b128 v[184:187], v139 offset:6144
	ds_read_b128 v[188:191], v139 offset:7168
	s_add_i32 s50, 0, 0x14000
	v_add_u32_e32 v156, s50, v137
	ds_read_b128 v[192:195], v156
	ds_read_b128 v[196:199], v156 offset:1024
	ds_read_b128 v[200:203], v156 offset:2048
	ds_read_b128 v[204:207], v156 offset:3072
	s_waitcnt lgkmcnt(0)
	s_barrier
	s_setprio 1
	v_mfma_f32_16x16x32_bf16 v[126:129], v[140:143], v[160:163], v[126:129]
	v_mfma_f32_16x16x32_bf16 v[122:125], v[148:151], v[160:163], v[122:125]
	v_mfma_f32_16x16x32_bf16 v[118:121], v[140:143], v[168:171], v[118:121]
	v_mfma_f32_16x16x32_bf16 v[114:117], v[148:151], v[168:171], v[114:117]
	v_mfma_f32_16x16x32_bf16 v[106:109], v[140:143], v[176:179], v[106:109]
	v_mfma_f32_16x16x32_bf16 v[98:101], v[148:151], v[176:179], v[98:101]
	v_mfma_f32_16x16x32_bf16 v[90:93], v[140:143], v[184:187], v[90:93]
	v_mfma_f32_16x16x32_bf16 v[82:85], v[148:151], v[184:187], v[82:85]
	v_mfma_f32_16x16x32_bf16 v[126:129], v[144:147], v[164:167], v[126:129]
	v_mfma_f32_16x16x32_bf16 v[122:125], v[152:155], v[164:167], v[122:125]
	v_mfma_f32_16x16x32_bf16 v[118:121], v[144:147], v[172:175], v[118:121]
	v_mfma_f32_16x16x32_bf16 v[114:117], v[152:155], v[172:175], v[114:117]
	v_mfma_f32_16x16x32_bf16 v[106:109], v[144:147], v[180:183], v[106:109]
	v_mfma_f32_16x16x32_bf16 v[98:101], v[152:155], v[180:183], v[98:101]
	v_mfma_f32_16x16x32_bf16 v[90:93], v[144:147], v[188:191], v[90:93]
	v_mfma_f32_16x16x32_bf16 v[82:85], v[152:155], v[188:191], v[82:85]
	v_mfma_f32_16x16x32_bf16 v[110:113], v[192:195], v[160:163], v[110:113]
	v_mfma_f32_16x16x32_bf16 v[102:105], v[200:203], v[160:163], v[102:105]
	v_mfma_f32_16x16x32_bf16 v[94:97], v[192:195], v[168:171], v[94:97]
	v_mfma_f32_16x16x32_bf16 v[86:89], v[200:203], v[168:171], v[86:89]
	v_mfma_f32_16x16x32_bf16 v[78:81], v[192:195], v[176:179], v[78:81]
	v_mfma_f32_16x16x32_bf16 v[74:77], v[200:203], v[176:179], v[74:77]
	v_mfma_f32_16x16x32_bf16 v[70:73], v[192:195], v[184:187], v[70:73]
	v_mfma_f32_16x16x32_bf16 v[66:69], v[200:203], v[184:187], v[66:69]
	v_mfma_f32_16x16x32_bf16 v[110:113], v[196:199], v[164:167], v[110:113]
	v_mfma_f32_16x16x32_bf16 v[102:105], v[204:207], v[164:167], v[102:105]
	v_mfma_f32_16x16x32_bf16 v[94:97], v[196:199], v[172:175], v[94:97]
	v_mfma_f32_16x16x32_bf16 v[86:89], v[204:207], v[172:175], v[86:89]
	v_mfma_f32_16x16x32_bf16 v[78:81], v[196:199], v[180:183], v[78:81]
	v_mfma_f32_16x16x32_bf16 v[74:77], v[204:207], v[180:183], v[74:77]
	v_mfma_f32_16x16x32_bf16 v[70:73], v[196:199], v[188:191], v[70:73]
	v_mfma_f32_16x16x32_bf16 v[66:69], v[204:207], v[188:191], v[66:69]
	s_setprio 0
	s_barrier
	s_add_i32 s38, s38, s63
	v_lshl_add_u64 v[156:157], s[54:55], 0, v[0:1]
	s_mov_b32 m0, s38
	v_lshl_add_u64 v[210:211], s[54:55], 0, v[130:131]
	global_load_lds_dwordx4 v[156:157], off
	s_add_i32 m0, s38, 0x2000
	s_nop 0
	global_load_lds_dwordx4 v[210:211], off
	s_mov_b32 m0, s25
	v_lshl_add_u64 v[212:213], s[56:57], 0, v[0:1]
	global_load_lds_dwordx4 v[212:213], off
	v_lshl_add_u64 v[214:215], s[56:57], 0, v[130:131]
	s_mov_b32 m0, s27
	s_nop 0
	global_load_lds_dwordx4 v[214:215], off
	ds_read_b128 v[160:163], v139 offset:16384
	ds_read_b128 v[164:167], v139 offset:17408
	ds_read_b128 v[168:171], v139 offset:18432
	ds_read_b128 v[172:175], v139 offset:19456
	ds_read_b128 v[176:179], v139 offset:20480
	ds_read_b128 v[180:183], v139 offset:21504
	ds_read_b128 v[184:187], v139 offset:22528
	ds_read_b128 v[188:191], v139 offset:23552
	s_waitcnt vmcnt(4)
	s_waitcnt lgkmcnt(0)
	s_barrier
	s_setprio 1
	v_mfma_f32_16x16x32_bf16 v[62:65], v[140:143], v[160:163], v[62:65]
	v_mfma_f32_16x16x32_bf16 v[58:61], v[148:151], v[160:163], v[58:61]
	v_mfma_f32_16x16x32_bf16 v[54:57], v[140:143], v[168:171], v[54:57]
	v_mfma_f32_16x16x32_bf16 v[50:53], v[148:151], v[168:171], v[50:53]
	v_mfma_f32_16x16x32_bf16 v[38:41], v[140:143], v[176:179], v[38:41]
	v_mfma_f32_16x16x32_bf16 v[34:37], v[148:151], v[176:179], v[34:37]
	v_mfma_f32_16x16x32_bf16 v[22:25], v[140:143], v[184:187], v[22:25]
	v_mfma_f32_16x16x32_bf16 v[18:21], v[148:151], v[184:187], v[18:21]
	v_mfma_f32_16x16x32_bf16 v[62:65], v[144:147], v[164:167], v[62:65]
	v_mfma_f32_16x16x32_bf16 v[58:61], v[152:155], v[164:167], v[58:61]
	v_mfma_f32_16x16x32_bf16 v[54:57], v[144:147], v[172:175], v[54:57]
	v_mfma_f32_16x16x32_bf16 v[50:53], v[152:155], v[172:175], v[50:53]
	v_mfma_f32_16x16x32_bf16 v[38:41], v[144:147], v[180:183], v[38:41]
	v_mfma_f32_16x16x32_bf16 v[34:37], v[152:155], v[180:183], v[34:37]
	v_mfma_f32_16x16x32_bf16 v[22:25], v[144:147], v[188:191], v[22:25]
	v_mfma_f32_16x16x32_bf16 v[18:21], v[152:155], v[188:191], v[18:21]
	v_mfma_f32_16x16x32_bf16 v[46:49], v[192:195], v[160:163], v[46:49]
	v_mfma_f32_16x16x32_bf16 v[42:45], v[200:203], v[160:163], v[42:45]
	v_mfma_f32_16x16x32_bf16 v[30:33], v[192:195], v[168:171], v[30:33]
	v_mfma_f32_16x16x32_bf16 v[26:29], v[200:203], v[168:171], v[26:29]
	v_mfma_f32_16x16x32_bf16 v[14:17], v[192:195], v[176:179], v[14:17]
	v_mfma_f32_16x16x32_bf16 v[10:13], v[200:203], v[176:179], v[10:13]
	v_mfma_f32_16x16x32_bf16 v[6:9], v[192:195], v[184:187], v[6:9]
	v_mfma_f32_16x16x32_bf16 v[2:5], v[200:203], v[184:187], v[2:5]
	v_mfma_f32_16x16x32_bf16 v[46:49], v[196:199], v[164:167], v[46:49]
	v_mfma_f32_16x16x32_bf16 v[42:45], v[204:207], v[164:167], v[42:45]
	v_mfma_f32_16x16x32_bf16 v[30:33], v[196:199], v[172:175], v[30:33]
	v_mfma_f32_16x16x32_bf16 v[26:29], v[204:207], v[172:175], v[26:29]
	v_mfma_f32_16x16x32_bf16 v[14:17], v[196:199], v[180:183], v[14:17]
	v_mfma_f32_16x16x32_bf16 v[10:13], v[204:207], v[180:183], v[10:13]
	v_mfma_f32_16x16x32_bf16 v[6:9], v[196:199], v[188:191], v[6:9]
	v_mfma_f32_16x16x32_bf16 v[2:5], v[204:207], v[188:191], v[2:5]
	s_setprio 0
	s_barrier
; #define PG8_STAGE(bufoff, gbase, voff) do { _Pragma("unroll") for (int _i = 0; _i < 2; ++_i) \
;         __builtin_amdgcn_global_load_lds((const unsigned*)((const char*)(gbase) + (voff)[_i]), (LAS unsigned*)(lds + (bufoff) + ldsw + _i * 8192), 16, 0, 0); } while (0)
; #define PG8_LDA(dst, b, h) do { _Pragma("unroll") for (int m = 0; m < 4; ++m) _Pragma("unroll") for (int k = 0; k < 2; ++k) dst[m][k] = *(const LAS bf16x8*)(lds + PG8_SA(b, h) + aoff + m * 2048 + k * 1024); } while (0)
; #define PG8_LDB(dst, b, h) do { _Pragma("unroll") for (int n = 0; n < 2; ++n) _Pragma("unroll") for (int k = 0; k < 2; ++k) dst[n][k] = *(const LAS bf16x8*)(lds + PG8_SB(b, h) + boff + n * 2048 + k * 1024); } while (0)
; #define PG8_MMA(ai, bj, At, Bt) do { __builtin_amdgcn_s_setprio(1); _Pragma("unroll") for (int m = 0; m < 4; ++m) _Pragma("unroll") for (int n = 0; n < 2; ++n) _Pragma("unroll") for (int k = 0; k < 2; ++k) \
;         acc[ai][bj][m][n] = __builtin_amdgcn_mfma_f32_16x16x32_bf16(Bt[n][k], At[m][k], acc[ai][bj][m][n], 0, 0, 0); __builtin_amdgcn_s_setprio(0); } while (0)
; #define PG8_WAIT_L(n) asm volatile("s_waitcnt lgkmcnt(" #n ")" ::: "memory")
; #define PG8_BAR __builtin_amdgcn_s_barrier()
; #define PG8_SCHED __builtin_amdgcn_sched_barrier(0)
; template <class Epi, class Sched>
; __device__ __forceinline__ void gemm_phase(LAS unsigned char* lds, const Gemm g, const Sched& S, const Epi& E) {
;     ...
;             PG8_LDB(B0, 1, 0); PG8_SCHED; PG8_LDA(At, 1, 0); PG8_STAGE(PG8_SA(0, 1), a2 + hstep, voffA);
;             PG8_WAIT_L(8); PG8_BAR; PG8_WAIT_L(0); PG8_MMA(0, 0, At, B0); PG8_BAR; PG8_SCHED;
;             PG8_LDB(B1, 1, 1); PG8_STAGE(PG8_SB(1, 0), b3, voffB);
;             PG8_BAR; PG8_WAIT_L(0); PG8_MMA(0, 1, At, B1); PG8_BAR;
;             PG8_LDA(At, 1, 1); PG8_STAGE(PG8_SA(1, 0), a3, voffA);
;             PG8_BAR; PG8_WAIT_L(0); PG8_MMA(1, 0, At, B0); PG8_BAR; PG8_SCHED;
	s_add_u32 s38, s54, 0x200000
	s_addc_u32 s39, s55, 0
	s_add_i32 s50, s50, s63
	v_lshl_add_u64 v[140:141], s[38:39], 0, v[0:1]
	s_mov_b32 m0, s50
	s_nop 0
	global_load_lds_dwordx4 v[140:141], off
	v_lshl_add_u64 v[140:141], s[38:39], 0, v[130:131]
	s_add_i32 m0, s50, 0x2000
	s_nop 0
	global_load_lds_dwordx4 v[140:141], off
	s_add_u32 s38, s56, 0x200000
	s_addc_u32 s39, s57, 0
	s_mov_b32 m0, s64
	v_lshl_add_u64 v[192:193], s[38:39], 0, v[0:1]
	global_load_lds_dwordx4 v[192:193], off
	v_lshl_add_u64 v[192:193], s[38:39], 0, v[130:131]
	s_mov_b32 m0, s65
	s_nop 0
	global_load_lds_dwordx4 v[192:193], off
	s_add_i32 s50, 0, 0x18000
	v_add_u32_e32 v152, s50, v137
	ds_read_b128 v[140:143], v152
	ds_read_b128 v[144:147], v152 offset:1024
	ds_read_b128 v[148:151], v152 offset:2048
	ds_read_b128 v[152:155], v152 offset:3072
	ds_read_b128 v[160:163], v139 offset:32768
	ds_read_b128 v[164:167], v139 offset:33792
	ds_read_b128 v[168:171], v139 offset:34816
	ds_read_b128 v[172:175], v139 offset:35840
	ds_read_b128 v[176:179], v139 offset:36864
	ds_read_b128 v[180:183], v139 offset:37888
	ds_read_b128 v[184:187], v139 offset:38912
	ds_read_b128 v[188:191], v139 offset:39936
	s_add_i32 s51, 0, 0x1c000
	v_add_u32_e32 v204, s51, v137
	ds_read_b128 v[192:195], v204
	ds_read_b128 v[196:199], v204 offset:1024
	ds_read_b128 v[200:203], v204 offset:2048
	ds_read_b128 v[204:207], v204 offset:3072
	s_waitcnt lgkmcnt(0)
	s_barrier
	s_setprio 1
	v_mfma_f32_16x16x32_bf16 v[126:129], v[140:143], v[160:163], v[126:129]
	v_mfma_f32_16x16x32_bf16 v[122:125], v[148:151], v[160:163], v[122:125]
	v_mfma_f32_16x16x32_bf16 v[118:121], v[140:143], v[168:171], v[118:121]
	v_mfma_f32_16x16x32_bf16 v[114:117], v[148:151], v[168:171], v[114:117]
	v_mfma_f32_16x16x32_bf16 v[106:109], v[140:143], v[176:179], v[106:109]
	v_mfma_f32_16x16x32_bf16 v[98:101], v[148:151], v[176:179], v[98:101]
	v_mfma_f32_16x16x32_bf16 v[90:93], v[140:143], v[184:187], v[90:93]
	v_mfma_f32_16x16x32_bf16 v[82:85], v[148:151], v[184:187], v[82:85]
	v_mfma_f32_16x16x32_bf16 v[126:129], v[144:147], v[164:167], v[126:129]
	v_mfma_f32_16x16x32_bf16 v[122:125], v[152:155], v[164:167], v[122:125]
	v_mfma_f32_16x16x32_bf16 v[118:121], v[144:147], v[172:175], v[118:121]
	v_mfma_f32_16x16x32_bf16 v[114:117], v[152:155], v[172:175], v[114:117]
	v_mfma_f32_16x16x32_bf16 v[106:109], v[144:147], v[180:183], v[106:109]
	v_mfma_f32_16x16x32_bf16 v[98:101], v[152:155], v[180:183], v[98:101]
	v_mfma_f32_16x16x32_bf16 v[90:93], v[144:147], v[188:191], v[90:93]
	v_mfma_f32_16x16x32_bf16 v[82:85], v[152:155], v[188:191], v[82:85]
	v_mfma_f32_16x16x32_bf16 v[110:113], v[192:195], v[160:163], v[110:113]
	v_mfma_f32_16x16x32_bf16 v[102:105], v[200:203], v[160:163], v[102:105]
	v_mfma_f32_16x16x32_bf16 v[94:97], v[192:195], v[168:171], v[94:97]
	v_mfma_f32_16x16x32_bf16 v[86:89], v[200:203], v[168:171], v[86:89]
	v_mfma_f32_16x16x32_bf16 v[78:81], v[192:195], v[176:179], v[78:81]
	v_mfma_f32_16x16x32_bf16 v[74:77], v[200:203], v[176:179], v[74:77]
	v_mfma_f32_16x16x32_bf16 v[70:73], v[192:195], v[184:187], v[70:73]
	v_mfma_f32_16x16x32_bf16 v[66:69], v[200:203], v[184:187], v[66:69]
	v_mfma_f32_16x16x32_bf16 v[110:113], v[196:199], v[164:167], v[110:113]
	v_mfma_f32_16x16x32_bf16 v[102:105], v[204:207], v[164:167], v[102:105]
	v_mfma_f32_16x16x32_bf16 v[94:97], v[196:199], v[172:175], v[94:97]
	v_mfma_f32_16x16x32_bf16 v[86:89], v[204:207], v[172:175], v[86:89]
	v_mfma_f32_16x16x32_bf16 v[78:81], v[196:199], v[180:183], v[78:81]
	v_mfma_f32_16x16x32_bf16 v[74:77], v[204:207], v[180:183], v[74:77]
	v_mfma_f32_16x16x32_bf16 v[70:73], v[196:199], v[188:191], v[70:73]
	v_mfma_f32_16x16x32_bf16 v[66:69], v[204:207], v[188:191], v[66:69]
	s_setprio 0
	s_barrier
	s_add_i32 s38, s50, s63
	v_lshl_add_u64 v[156:157], v[156:157], 0, s[36:37]
	s_mov_b32 m0, s38
	s_nop 0
	global_load_lds_dwordx4 v[156:157], off
	v_lshl_add_u64 v[156:157], v[210:211], 0, s[36:37]
	s_add_i32 m0, s38, 0x2000
	s_nop 0
	global_load_lds_dwordx4 v[156:157], off
	s_mov_b32 m0, s66
	v_lshl_add_u64 v[156:157], v[212:213], 0, s[36:37]
	global_load_lds_dwordx4 v[156:157], off
	v_lshl_add_u64 v[156:157], v[214:215], 0, s[36:37]
	s_mov_b32 m0, s67
	s_nop 0
	global_load_lds_dwordx4 v[156:157], off
	s_add_u32 s38, s54, 0x200080
	s_addc_u32 s39, s55, 0
	s_add_i32 s50, s51, s63
	v_lshl_add_u64 v[156:157], s[38:39], 0, v[0:1]
	s_mov_b32 m0, s50
	s_nop 0
	global_load_lds_dwordx4 v[156:157], off
	v_lshl_add_u64 v[156:157], s[38:39], 0, v[130:131]
	s_add_i32 m0, s50, 0x2000
	s_nop 0
	global_load_lds_dwordx4 v[156:157], off
	ds_read_b128 v[160:163], v139 offset:49152
	ds_read_b128 v[164:167], v139 offset:50176
	ds_read_b128 v[168:171], v139 offset:51200
	ds_read_b128 v[172:175], v139 offset:52224
	ds_read_b128 v[176:179], v139 offset:53248
	ds_read_b128 v[180:183], v139 offset:54272
	ds_read_b128 v[184:187], v139 offset:55296
	ds_read_b128 v[188:191], v139 offset:56320
	s_waitcnt vmcnt(6)
	s_waitcnt lgkmcnt(0)
	s_barrier
; #define PG8_STAGE(bufoff, gbase, voff) do { _Pragma("unroll") for (int _i = 0; _i < 2; ++_i) \
;         __builtin_amdgcn_global_load_lds((const unsigned*)((const char*)(gbase) + (voff)[_i]), (LAS unsigned*)(lds + (bufoff) + ldsw + _i * 8192), 16, 0, 0); } while (0)
; #define PG8_MMA(ai, bj, At, Bt) do { __builtin_amdgcn_s_setprio(1); _Pragma("unroll") for (int m = 0; m < 4; ++m) _Pragma("unroll") for (int n = 0; n < 2; ++n) _Pragma("unroll") for (int k = 0; k < 2; ++k) \
;         acc[ai][bj][m][n] = __builtin_amdgcn_mfma_f32_16x16x32_bf16(Bt[n][k], At[m][k], acc[ai][bj][m][n], 0, 0, 0); __builtin_amdgcn_s_setprio(0); } while (0)
; #define PG8_WAIT_V(n) asm volatile("s_waitcnt vmcnt(" #n ")" ::: "memory")
; #define PG8_BAR __builtin_amdgcn_s_barrier()
;     __device__ __forceinline__ void operator()(const f32x4 (&acc)[2][2][4][2], const Unit& u, int wr, int wc, int fr, int fq) const {
;         const int row0 = u.pm * BM + wr * 64 + fr, col0 = u.pn * BM + wc * 32 + 4 * fq;
;         float* base = part + (size_t)u.ks * Mp * ldc;
; #pragma unroll
;         for (int ai = 0; ai < 2; ++ai)
; #pragma unroll
;             for (int m = 0; m < 4; ++m) { float* rowp = base + (size_t)(row0 + ai * HALF + m * 16) * ldc + col0;
; #pragma unroll
;                 for (int bj = 0; bj < 2; ++bj)
; #pragma unroll
;                     for (int n = 0; n < 2; ++n) *(f32x4*)(rowp + bj * HALF + n * 16) = acc[ai][bj][m][n]; }
;     }
; template <class Epi, class Sched>
; __device__ __forceinline__ void gemm_phase(LAS unsigned char* lds, const Gemm g, const Sched& S, const Epi& E) {
;     ...
;             PG8_STAGE(PG8_SB(1, 1), b3 + hstep, voffB);
;             PG8_WAIT_V(6); PG8_BAR; PG8_MMA(1, 1, At, B1); PG8_BAR;
;         }
;         E(acc, cur, wr, wc, fr, fq);
;         if (!has_next) break;
	s_setprio 1
	v_mfma_f32_16x16x32_bf16 v[62:65], v[140:143], v[160:163], v[62:65]
	v_mfma_f32_16x16x32_bf16 v[58:61], v[148:151], v[160:163], v[58:61]
	v_mfma_f32_16x16x32_bf16 v[54:57], v[140:143], v[168:171], v[54:57]
	v_mfma_f32_16x16x32_bf16 v[50:53], v[148:151], v[168:171], v[50:53]
	v_mfma_f32_16x16x32_bf16 v[38:41], v[140:143], v[176:179], v[38:41]
	v_mfma_f32_16x16x32_bf16 v[34:37], v[148:151], v[176:179], v[34:37]
	v_mfma_f32_16x16x32_bf16 v[22:25], v[140:143], v[184:187], v[22:25]
	v_mfma_f32_16x16x32_bf16 v[18:21], v[148:151], v[184:187], v[18:21]
	v_mfma_f32_16x16x32_bf16 v[62:65], v[144:147], v[164:167], v[62:65]
	v_mfma_f32_16x16x32_bf16 v[58:61], v[152:155], v[164:167], v[58:61]
	v_mfma_f32_16x16x32_bf16 v[54:57], v[144:147], v[172:175], v[54:57]
	v_mfma_f32_16x16x32_bf16 v[50:53], v[152:155], v[172:175], v[50:53]
	v_mfma_f32_16x16x32_bf16 v[38:41], v[144:147], v[180:183], v[38:41]
	v_mfma_f32_16x16x32_bf16 v[34:37], v[152:155], v[180:183], v[34:37]
	v_mfma_f32_16x16x32_bf16 v[22:25], v[144:147], v[188:191], v[22:25]
	v_mfma_f32_16x16x32_bf16 v[18:21], v[152:155], v[188:191], v[18:21]
	v_mfma_f32_16x16x32_bf16 v[46:49], v[192:195], v[160:163], v[46:49]
	v_mfma_f32_16x16x32_bf16 v[42:45], v[200:203], v[160:163], v[42:45]
	v_mfma_f32_16x16x32_bf16 v[30:33], v[192:195], v[168:171], v[30:33]
	v_mfma_f32_16x16x32_bf16 v[26:29], v[200:203], v[168:171], v[26:29]
	v_mfma_f32_16x16x32_bf16 v[14:17], v[192:195], v[176:179], v[14:17]
	v_mfma_f32_16x16x32_bf16 v[10:13], v[200:203], v[176:179], v[10:13]
	v_mfma_f32_16x16x32_bf16 v[6:9], v[192:195], v[184:187], v[6:9]
	v_mfma_f32_16x16x32_bf16 v[2:5], v[200:203], v[184:187], v[2:5]
	v_mfma_f32_16x16x32_bf16 v[46:49], v[196:199], v[164:167], v[46:49]
	v_mfma_f32_16x16x32_bf16 v[42:45], v[204:207], v[164:167], v[42:45]
	v_mfma_f32_16x16x32_bf16 v[30:33], v[196:199], v[172:175], v[30:33]
	v_mfma_f32_16x16x32_bf16 v[26:29], v[204:207], v[172:175], v[26:29]
	v_mfma_f32_16x16x32_bf16 v[14:17], v[196:199], v[180:183], v[14:17]
	v_mfma_f32_16x16x32_bf16 v[10:13], v[204:207], v[180:183], v[10:13]
	v_mfma_f32_16x16x32_bf16 v[6:9], v[196:199], v[188:191], v[6:9]
	v_mfma_f32_16x16x32_bf16 v[2:5], v[204:207], v[188:191], v[2:5]
	s_setprio 0
	s_add_i32 s71, s71, 2
	s_add_u32 s69, s69, 0x100
	s_addc_u32 s70, s70, 0
	s_cmp_gt_u32 s71, 29
	s_mov_b64 s[50:51], s[52:53]
	s_barrier
	s_cbranch_scc0 .LBB0_58
	s_ashr_i32 s11, s10, 31
	s_lshl_b64 s[10:11], s[10:11], 24
	v_lshl_or_b32 v140, s26, 8, v138
	s_add_u32 s10, s8, s10
	v_lshl_add_u32 v142, s24, 8, v136
	s_addc_u32 s11, s9, s11
	v_ashrrev_i32_e32 v141, 31, v140
	v_ashrrev_i32_e32 v143, 31, v142
	v_lshl_add_u64 v[140:141], v[140:141], 2, s[10:11]
	v_lshlrev_b64 v[144:145], 13, v[142:143]
	v_lshl_add_u64 v[144:145], v[140:141], 0, v[144:145]
	global_store_dwordx4 v[144:145], v[126:129], off
	global_store_dwordx4 v[144:145], v[122:125], off offset:64
	global_store_dwordx4 v[144:145], v[110:113], off offset:512
	global_store_dwordx4 v[144:145], v[102:105], off offset:576
	s_mov_b64 s[10:11], 0x100000
	s_mov_b32 s26, s40
	v_or_b32_e32 v102, 16, v142
	v_ashrrev_i32_e32 v103, 31, v102
	v_lshlrev_b64 v[102:103], 13, v[102:103]
	v_lshl_add_u64 v[102:103], v[140:141], 0, v[102:103]
	global_store_dwordx4 v[102:103], v[118:121], off
	global_store_dwordx4 v[102:103], v[114:117], off offset:64
	global_store_dwordx4 v[102:103], v[94:97], off offset:512
	global_store_dwordx4 v[102:103], v[86:89], off offset:576
	s_mov_b32 s24, s42
	s_mov_b64 s[52:53], s[48:49]
	v_or_b32_e32 v86, 32, v142
	v_ashrrev_i32_e32 v87, 31, v86
	v_lshlrev_b64 v[86:87], 13, v[86:87]
	v_lshl_add_u64 v[86:87], v[140:141], 0, v[86:87]
	global_store_dwordx4 v[86:87], v[106:109], off
	global_store_dwordx4 v[86:87], v[98:101], off offset:64
	global_store_dwordx4 v[86:87], v[78:81], off offset:512
	global_store_dwordx4 v[86:87], v[74:77], off offset:576
	s_mov_b64 s[50:51], s[46:47]
	s_nop 0
	v_or_b32_e32 v74, 48, v142
	v_ashrrev_i32_e32 v75, 31, v74
	v_lshlrev_b64 v[74:75], 13, v[74:75]
	v_lshl_add_u64 v[74:75], v[140:141], 0, v[74:75]
	global_store_dwordx4 v[74:75], v[90:93], off
	global_store_dwordx4 v[74:75], v[82:85], off offset:64
	global_store_dwordx4 v[74:75], v[70:73], off offset:512
	global_store_dwordx4 v[74:75], v[66:69], off offset:576
	s_nop 1
	v_add_co_u32_e32 v68, vcc, s93, v144
	v_lshl_add_u64 v[66:67], v[144:145], 0, s[10:11]
	s_nop 0
	v_addc_co_u32_e32 v69, vcc, 0, v145, vcc
	s_mov_b64 s[10:11], 0x120000
	global_store_dwordx4 v[68:69], v[62:65], off
	global_store_dwordx4 v[66:67], v[58:61], off offset:64
	global_store_dwordx4 v[66:67], v[46:49], off offset:512
	global_store_dwordx4 v[66:67], v[42:45], off offset:576
	s_nop 1
	v_lshl_add_u64 v[42:43], v[144:145], 0, s[10:11]
	s_mov_b32 s10, 0x120000
	v_add_co_u32_e32 v44, vcc, s10, v144
	s_mov_b64 s[10:11], 0x140000
	s_nop 0
	v_addc_co_u32_e32 v45, vcc, 0, v145, vcc
	global_store_dwordx4 v[44:45], v[54:57], off
	global_store_dwordx4 v[42:43], v[50:53], off offset:64
	global_store_dwordx4 v[42:43], v[30:33], off offset:512
	global_store_dwordx4 v[42:43], v[26:29], off offset:576
	s_nop 1
	v_lshl_add_u64 v[26:27], v[144:145], 0, s[10:11]
	s_mov_b32 s10, 0x140000
	v_add_co_u32_e32 v28, vcc, s10, v144
	s_mov_b64 s[10:11], 0x160000
	s_nop 0
	v_addc_co_u32_e32 v29, vcc, 0, v145, vcc
	global_store_dwordx4 v[28:29], v[38:41], off
	global_store_dwordx4 v[26:27], v[34:37], off offset:64
	global_store_dwordx4 v[26:27], v[14:17], off offset:512
	global_store_dwordx4 v[26:27], v[10:13], off offset:576
	s_nop 1
	v_add_co_u32_e32 v12, vcc, 0x160000, v144
	v_lshl_add_u64 v[10:11], v[144:145], 0, s[10:11]
	s_nop 0
	v_addc_co_u32_e32 v13, vcc, 0, v145, vcc
	s_and_b64 vcc, exec, s[44:45]
	s_mov_b32 s10, s28
	global_store_dwordx4 v[12:13], v[22:25], off
	global_store_dwordx4 v[10:11], v[18:21], off offset:64
	global_store_dwordx4 v[10:11], v[6:9], off offset:512
	global_store_dwordx4 v[10:11], v[2:5], off offset:576
	s_cbranch_vccz .LBB0_55
	s_waitcnt vmcnt(0)
	s_cmpk_gt_u32 s60, 0xff
	s_cbranch_scc1 .LBB0_62
	s_barrier

; #define PG8_STAGE(bufoff, gbase, voff) do { _Pragma("unroll") for (int _i = 0; _i < 2; ++_i) \
;         __builtin_amdgcn_global_load_lds((const unsigned*)((const char*)(gbase) + (voff)[_i]), (LAS unsigned*)(lds + (bufoff) + ldsw + _i * 8192), 16, 0, 0); } while (0)
; #define PG8_LDA(dst, b, h) do { _Pragma("unroll") for (int m = 0; m < 4; ++m) _Pragma("unroll") for (int k = 0; k < 2; ++k) dst[m][k] = *(const LAS bf16x8*)(lds + PG8_SA(b, h) + aoff + m * 2048 + k * 1024); } while (0)
; #define PG8_LDB(dst, b, h) do { _Pragma("unroll") for (int n = 0; n < 2; ++n) _Pragma("unroll") for (int k = 0; k < 2; ++k) dst[n][k] = *(const LAS bf16x8*)(lds + PG8_SB(b, h) + boff + n * 2048 + k * 1024); } while (0)
; #define PG8_MMA(ai, bj, At, Bt) do { __builtin_amdgcn_s_setprio(1); _Pragma("unroll") for (int m = 0; m < 4; ++m) _Pragma("unroll") for (int n = 0; n < 2; ++n) _Pragma("unroll") for (int k = 0; k < 2; ++k) \
;         acc[ai][bj][m][n] = __builtin_amdgcn_mfma_f32_16x16x32_bf16(Bt[n][k], At[m][k], acc[ai][bj][m][n], 0, 0, 0); __builtin_amdgcn_s_setprio(0); } while (0)
; #define PG8_WAIT_V(n) asm volatile("s_waitcnt vmcnt(" #n ")" ::: "memory")
; #define PG8_WAIT_L(n) asm volatile("s_waitcnt lgkmcnt(" #n ")" ::: "memory")
; template <class Epi, class Sched>
; __device__ __forceinline__ void gemm_phase(LAS unsigned char* lds, const Gemm g, const Sched& S, const Epi& E) {
;     ...
;         for (int t = 0; t < nt; t += 2) {
;             const bool last = (t == nt - 2);
;             const char* a1 = cA + (size_t)(t + 1) * kstep;
;             const char* a2 = last ? nA : cA + (size_t)(t + 2) * kstep; const char* b2 = last ? nB : cB + (size_t)(t + 2) * kstep;
;             const char* a3 = a2 + kstep; const char* b3 = b2 + kstep;
;             PG8_LDB(B0, 0, 0); PG8_SCHED; PG8_LDA(At, 0, 0); PG8_STAGE(PG8_SA(1, 1), a1 + hstep, voffA);
;             PG8_WAIT_L(8); PG8_BAR; PG8_WAIT_L(0); PG8_MMA(0, 0, At, B0); PG8_BAR; PG8_SCHED;
;             PG8_LDB(B1, 0, 1); PG8_STAGE(PG8_SB(0, 0), b2, voffB);
;             PG8_BAR; PG8_WAIT_L(0); PG8_MMA(0, 1, At, B1); PG8_BAR;
;             PG8_LDA(At, 0, 1); PG8_STAGE(PG8_SA(0, 0), a2, voffA);
;             PG8_BAR; PG8_WAIT_L(0); PG8_MMA(1, 0, At, B0); PG8_BAR; PG8_SCHED;
;             PG8_STAGE(PG8_SB(0, 1), b2 + hstep, voffB);
;             PG8_WAIT_V(6); PG8_BAR; PG8_MMA(1, 1, At, B1); PG8_BAR;
.LBB0_73:
	s_add_u32 s38, s46, 0xfff80080
	s_addc_u32 s39, s47, -1
	s_cmp_eq_u32 s73, 28
	s_cselect_b32 s51, s29, s39
	s_cselect_b32 s50, s69, s38
	s_cselect_b32 s49, s27, s72
	s_cselect_b32 s48, s70, s71
	v_lshl_add_u64 v[140:141], s[46:47], 0, v[138:139]
	s_add_i32 m0, s9, 0xc000
	s_nop 0
	global_load_lds_dwordx4 v[140:141], off
	v_lshl_add_u64 v[140:141], s[46:47], 0, v[136:137]
	s_add_i32 m0, s9, 0xe000
	s_nop 0
	global_load_lds_dwordx4 v[140:141], off
	s_add_i32 s74, 0, 0x10000
	v_add_u32_e32 v140, s74, v143
	ds_read_b128 v[146:149], v140
	ds_read_b128 v[150:153], v140 offset:1024
	ds_read_b128 v[154:157], v140 offset:2048
	ds_read_b128 v[160:163], v140 offset:3072
	ds_read_b128 v[164:167], v145
	ds_read_b128 v[168:171], v145 offset:1024
	ds_read_b128 v[172:175], v145 offset:2048
	ds_read_b128 v[176:179], v145 offset:3072
	ds_read_b128 v[180:183], v145 offset:4096
	ds_read_b128 v[184:187], v145 offset:5120
	ds_read_b128 v[188:191], v145 offset:6144
	ds_read_b128 v[192:195], v145 offset:7168
	s_add_i32 s75, 0, 0x14000
	v_add_u32_e32 v140, s75, v143
	ds_read_b128 v[196:199], v140
	ds_read_b128 v[200:203], v140 offset:1024
	ds_read_b128 v[204:207], v140 offset:2048
	ds_read_b128 v[210:213], v140 offset:3072
	s_waitcnt lgkmcnt(0)
	s_barrier
	s_setprio 1
	v_mfma_f32_16x16x32_bf16 v[126:129], v[146:149], v[164:167], v[126:129]
	v_mfma_f32_16x16x32_bf16 v[122:125], v[154:157], v[164:167], v[122:125]
	v_mfma_f32_16x16x32_bf16 v[110:113], v[146:149], v[172:175], v[110:113]
	v_mfma_f32_16x16x32_bf16 v[106:109], v[154:157], v[172:175], v[106:109]
	v_mfma_f32_16x16x32_bf16 v[94:97], v[146:149], v[180:183], v[94:97]
	v_mfma_f32_16x16x32_bf16 v[90:93], v[154:157], v[180:183], v[90:93]
	v_mfma_f32_16x16x32_bf16 v[78:81], v[146:149], v[188:191], v[78:81]
	v_mfma_f32_16x16x32_bf16 v[74:77], v[154:157], v[188:191], v[74:77]
	v_mfma_f32_16x16x32_bf16 v[126:129], v[150:153], v[168:171], v[126:129]
	v_mfma_f32_16x16x32_bf16 v[122:125], v[160:163], v[168:171], v[122:125]
	v_mfma_f32_16x16x32_bf16 v[110:113], v[150:153], v[176:179], v[110:113]
	v_mfma_f32_16x16x32_bf16 v[106:109], v[160:163], v[176:179], v[106:109]
	v_mfma_f32_16x16x32_bf16 v[94:97], v[150:153], v[184:187], v[94:97]
	v_mfma_f32_16x16x32_bf16 v[90:93], v[160:163], v[184:187], v[90:93]
	v_mfma_f32_16x16x32_bf16 v[78:81], v[150:153], v[192:195], v[78:81]
	v_mfma_f32_16x16x32_bf16 v[74:77], v[160:163], v[192:195], v[74:77]
	v_mfma_f32_16x16x32_bf16 v[118:121], v[196:199], v[164:167], v[118:121]
	v_mfma_f32_16x16x32_bf16 v[114:117], v[204:207], v[164:167], v[114:117]
	v_mfma_f32_16x16x32_bf16 v[102:105], v[196:199], v[172:175], v[102:105]
	v_mfma_f32_16x16x32_bf16 v[98:101], v[204:207], v[172:175], v[98:101]
	v_mfma_f32_16x16x32_bf16 v[86:89], v[196:199], v[180:183], v[86:89]
	v_mfma_f32_16x16x32_bf16 v[82:85], v[204:207], v[180:183], v[82:85]
	v_mfma_f32_16x16x32_bf16 v[70:73], v[196:199], v[188:191], v[70:73]
	v_mfma_f32_16x16x32_bf16 v[66:69], v[204:207], v[188:191], v[66:69]
	v_mfma_f32_16x16x32_bf16 v[118:121], v[200:203], v[168:171], v[118:121]
	v_mfma_f32_16x16x32_bf16 v[114:117], v[210:213], v[168:171], v[114:117]
	v_mfma_f32_16x16x32_bf16 v[102:105], v[200:203], v[176:179], v[102:105]
	v_mfma_f32_16x16x32_bf16 v[98:101], v[210:213], v[176:179], v[98:101]
	v_mfma_f32_16x16x32_bf16 v[86:89], v[200:203], v[184:187], v[86:89]
	v_mfma_f32_16x16x32_bf16 v[82:85], v[210:213], v[184:187], v[82:85]
	v_mfma_f32_16x16x32_bf16 v[70:73], v[200:203], v[192:195], v[70:73]
	v_mfma_f32_16x16x32_bf16 v[66:69], v[210:213], v[192:195], v[66:69]
	s_setprio 0
	s_barrier
	s_add_i32 s38, s74, s56
	v_lshl_add_u64 v[140:141], s[48:49], 0, v[0:1]
	s_mov_b32 m0, s38
	v_lshl_add_u64 v[214:215], s[48:49], 0, v[130:131]
	global_load_lds_dwordx4 v[140:141], off
	s_add_i32 m0, s38, 0x2000
	s_nop 0
	global_load_lds_dwordx4 v[214:215], off
	s_mov_b32 m0, s9
	v_lshl_add_u64 v[216:217], s[50:51], 0, v[134:135]
	global_load_lds_dwordx4 v[216:217], off
	v_lshl_add_u64 v[224:225], s[50:51], 0, v[132:133]
	s_mov_b32 m0, s60
	s_nop 0
	global_load_lds_dwordx4 v[224:225], off
	ds_read_b128 v[164:167], v145 offset:16384
	ds_read_b128 v[168:171], v145 offset:17408
	ds_read_b128 v[172:175], v145 offset:18432
	ds_read_b128 v[176:179], v145 offset:19456
	ds_read_b128 v[180:183], v145 offset:20480
	ds_read_b128 v[184:187], v145 offset:21504
	ds_read_b128 v[188:191], v145 offset:22528
	ds_read_b128 v[192:195], v145 offset:23552
	s_waitcnt vmcnt(4)
	s_waitcnt lgkmcnt(0)
	s_barrier
	s_setprio 1
	v_mfma_f32_16x16x32_bf16 v[62:65], v[146:149], v[164:167], v[62:65]
	v_mfma_f32_16x16x32_bf16 v[58:61], v[154:157], v[164:167], v[58:61]
	v_mfma_f32_16x16x32_bf16 v[46:49], v[146:149], v[172:175], v[46:49]
	v_mfma_f32_16x16x32_bf16 v[42:45], v[154:157], v[172:175], v[42:45]
	v_mfma_f32_16x16x32_bf16 v[30:33], v[146:149], v[180:183], v[30:33]
	v_mfma_f32_16x16x32_bf16 v[26:29], v[154:157], v[180:183], v[26:29]
	v_mfma_f32_16x16x32_bf16 v[14:17], v[146:149], v[188:191], v[14:17]
	v_mfma_f32_16x16x32_bf16 v[10:13], v[154:157], v[188:191], v[10:13]
	v_mfma_f32_16x16x32_bf16 v[62:65], v[150:153], v[168:171], v[62:65]
	v_mfma_f32_16x16x32_bf16 v[58:61], v[160:163], v[168:171], v[58:61]
	v_mfma_f32_16x16x32_bf16 v[46:49], v[150:153], v[176:179], v[46:49]
	v_mfma_f32_16x16x32_bf16 v[42:45], v[160:163], v[176:179], v[42:45]
	v_mfma_f32_16x16x32_bf16 v[30:33], v[150:153], v[184:187], v[30:33]
	v_mfma_f32_16x16x32_bf16 v[26:29], v[160:163], v[184:187], v[26:29]
	v_mfma_f32_16x16x32_bf16 v[14:17], v[150:153], v[192:195], v[14:17]
	v_mfma_f32_16x16x32_bf16 v[10:13], v[160:163], v[192:195], v[10:13]
	v_mfma_f32_16x16x32_bf16 v[54:57], v[196:199], v[164:167], v[54:57]
	v_mfma_f32_16x16x32_bf16 v[50:53], v[204:207], v[164:167], v[50:53]
	v_mfma_f32_16x16x32_bf16 v[38:41], v[196:199], v[172:175], v[38:41]
	v_mfma_f32_16x16x32_bf16 v[34:37], v[204:207], v[172:175], v[34:37]
	v_mfma_f32_16x16x32_bf16 v[22:25], v[196:199], v[180:183], v[22:25]
	v_mfma_f32_16x16x32_bf16 v[18:21], v[204:207], v[180:183], v[18:21]
	v_mfma_f32_16x16x32_bf16 v[6:9], v[196:199], v[188:191], v[6:9]
	v_mfma_f32_16x16x32_bf16 v[2:5], v[204:207], v[188:191], v[2:5]
	v_mfma_f32_16x16x32_bf16 v[54:57], v[200:203], v[168:171], v[54:57]
	v_mfma_f32_16x16x32_bf16 v[50:53], v[210:213], v[168:171], v[50:53]
	v_mfma_f32_16x16x32_bf16 v[38:41], v[200:203], v[176:179], v[38:41]
	v_mfma_f32_16x16x32_bf16 v[34:37], v[210:213], v[176:179], v[34:37]
	v_mfma_f32_16x16x32_bf16 v[22:25], v[200:203], v[184:187], v[22:25]
	v_mfma_f32_16x16x32_bf16 v[18:21], v[210:213], v[184:187], v[18:21]
	v_mfma_f32_16x16x32_bf16 v[6:9], v[200:203], v[192:195], v[6:9]
	v_mfma_f32_16x16x32_bf16 v[2:5], v[210:213], v[192:195], v[2:5]
	s_setprio 0
	s_barrier
; #define PG8_STAGE(bufoff, gbase, voff) do { _Pragma("unroll") for (int _i = 0; _i < 2; ++_i) \
;         __builtin_amdgcn_global_load_lds((const unsigned*)((const char*)(gbase) + (voff)[_i]), (LAS unsigned*)(lds + (bufoff) + ldsw + _i * 8192), 16, 0, 0); } while (0)
; #define PG8_LDA(dst, b, h) do { _Pragma("unroll") for (int m = 0; m < 4; ++m) _Pragma("unroll") for (int k = 0; k < 2; ++k) dst[m][k] = *(const LAS bf16x8*)(lds + PG8_SA(b, h) + aoff + m * 2048 + k * 1024); } while (0)
; #define PG8_LDB(dst, b, h) do { _Pragma("unroll") for (int n = 0; n < 2; ++n) _Pragma("unroll") for (int k = 0; k < 2; ++k) dst[n][k] = *(const LAS bf16x8*)(lds + PG8_SB(b, h) + boff + n * 2048 + k * 1024); } while (0)
; #define PG8_MMA(ai, bj, At, Bt) do { __builtin_amdgcn_s_setprio(1); _Pragma("unroll") for (int m = 0; m < 4; ++m) _Pragma("unroll") for (int n = 0; n < 2; ++n) _Pragma("unroll") for (int k = 0; k < 2; ++k) \
;         acc[ai][bj][m][n] = __builtin_amdgcn_mfma_f32_16x16x32_bf16(Bt[n][k], At[m][k], acc[ai][bj][m][n], 0, 0, 0); __builtin_amdgcn_s_setprio(0); } while (0)
; #define PG8_WAIT_L(n) asm volatile("s_waitcnt lgkmcnt(" #n ")" ::: "memory")
; #define PG8_BAR __builtin_amdgcn_s_barrier()
; #define PG8_SCHED __builtin_amdgcn_sched_barrier(0)
; template <class Epi, class Sched>
; __device__ __forceinline__ void gemm_phase(LAS unsigned char* lds, const Gemm g, const Sched& S, const Epi& E) {
;     ...
;             PG8_LDB(B0, 1, 0); PG8_SCHED; PG8_LDA(At, 1, 0); PG8_STAGE(PG8_SA(0, 1), a2 + hstep, voffA);
;             PG8_WAIT_L(8); PG8_BAR; PG8_WAIT_L(0); PG8_MMA(0, 0, At, B0); PG8_BAR; PG8_SCHED;
;             PG8_LDB(B1, 1, 1); PG8_STAGE(PG8_SB(1, 0), b3, voffB);
;             PG8_BAR; PG8_WAIT_L(0); PG8_MMA(0, 1, At, B1); PG8_BAR;
;             PG8_LDA(At, 1, 1); PG8_STAGE(PG8_SA(1, 0), a3, voffA);
;             PG8_BAR; PG8_WAIT_L(0); PG8_MMA(1, 0, At, B0); PG8_BAR; PG8_SCHED;
	s_add_u32 s38, s48, 0x80000
	s_addc_u32 s39, s49, 0
	s_add_i32 s74, s75, s56
	v_lshl_add_u64 v[146:147], s[38:39], 0, v[0:1]
	s_mov_b32 m0, s74
	s_nop 0
	global_load_lds_dwordx4 v[146:147], off
	v_lshl_add_u64 v[146:147], s[38:39], 0, v[130:131]
	s_add_i32 m0, s74, 0x2000
	s_nop 0
	global_load_lds_dwordx4 v[146:147], off
	s_add_u32 s38, s50, 0x80000
	s_addc_u32 s39, s51, 0
	s_mov_b32 m0, s61
	v_lshl_add_u64 v[196:197], s[38:39], 0, v[134:135]
	global_load_lds_dwordx4 v[196:197], off
	v_lshl_add_u64 v[196:197], s[38:39], 0, v[132:133]
	s_mov_b32 m0, s62
	s_nop 0
	global_load_lds_dwordx4 v[196:197], off
	s_add_i32 s74, 0, 0x18000
	v_add_u32_e32 v160, s74, v143
	ds_read_b128 v[146:149], v160
	ds_read_b128 v[150:153], v160 offset:1024
	ds_read_b128 v[154:157], v160 offset:2048
	ds_read_b128 v[160:163], v160 offset:3072
	ds_read_b128 v[164:167], v145 offset:32768
	ds_read_b128 v[168:171], v145 offset:33792
	ds_read_b128 v[172:175], v145 offset:34816
	ds_read_b128 v[176:179], v145 offset:35840
	ds_read_b128 v[180:183], v145 offset:36864
	ds_read_b128 v[184:187], v145 offset:37888
	ds_read_b128 v[188:191], v145 offset:38912
	ds_read_b128 v[192:195], v145 offset:39936
	s_add_i32 s50, 0, 0x1c000
	v_add_u32_e32 v210, s50, v143
	ds_read_b128 v[196:199], v210
	ds_read_b128 v[200:203], v210 offset:1024
	ds_read_b128 v[204:207], v210 offset:2048
	ds_read_b128 v[210:213], v210 offset:3072
	s_waitcnt lgkmcnt(0)
	s_barrier
	s_setprio 1
	v_mfma_f32_16x16x32_bf16 v[126:129], v[146:149], v[164:167], v[126:129]
	v_mfma_f32_16x16x32_bf16 v[122:125], v[154:157], v[164:167], v[122:125]
	v_mfma_f32_16x16x32_bf16 v[110:113], v[146:149], v[172:175], v[110:113]
	v_mfma_f32_16x16x32_bf16 v[106:109], v[154:157], v[172:175], v[106:109]
	v_mfma_f32_16x16x32_bf16 v[94:97], v[146:149], v[180:183], v[94:97]
	v_mfma_f32_16x16x32_bf16 v[90:93], v[154:157], v[180:183], v[90:93]
	v_mfma_f32_16x16x32_bf16 v[78:81], v[146:149], v[188:191], v[78:81]
	v_mfma_f32_16x16x32_bf16 v[74:77], v[154:157], v[188:191], v[74:77]
	v_mfma_f32_16x16x32_bf16 v[126:129], v[150:153], v[168:171], v[126:129]
	v_mfma_f32_16x16x32_bf16 v[122:125], v[160:163], v[168:171], v[122:125]
	v_mfma_f32_16x16x32_bf16 v[110:113], v[150:153], v[176:179], v[110:113]
	v_mfma_f32_16x16x32_bf16 v[106:109], v[160:163], v[176:179], v[106:109]
	v_mfma_f32_16x16x32_bf16 v[94:97], v[150:153], v[184:187], v[94:97]
	v_mfma_f32_16x16x32_bf16 v[90:93], v[160:163], v[184:187], v[90:93]
	v_mfma_f32_16x16x32_bf16 v[78:81], v[150:153], v[192:195], v[78:81]
	v_mfma_f32_16x16x32_bf16 v[74:77], v[160:163], v[192:195], v[74:77]
	v_mfma_f32_16x16x32_bf16 v[118:121], v[196:199], v[164:167], v[118:121]
	v_mfma_f32_16x16x32_bf16 v[114:117], v[204:207], v[164:167], v[114:117]
	v_mfma_f32_16x16x32_bf16 v[102:105], v[196:199], v[172:175], v[102:105]
	v_mfma_f32_16x16x32_bf16 v[98:101], v[204:207], v[172:175], v[98:101]
	v_mfma_f32_16x16x32_bf16 v[86:89], v[196:199], v[180:183], v[86:89]
	v_mfma_f32_16x16x32_bf16 v[82:85], v[204:207], v[180:183], v[82:85]
	v_mfma_f32_16x16x32_bf16 v[70:73], v[196:199], v[188:191], v[70:73]
	v_mfma_f32_16x16x32_bf16 v[66:69], v[204:207], v[188:191], v[66:69]
	v_mfma_f32_16x16x32_bf16 v[118:121], v[200:203], v[168:171], v[118:121]
	v_mfma_f32_16x16x32_bf16 v[114:117], v[210:213], v[168:171], v[114:117]
	v_mfma_f32_16x16x32_bf16 v[102:105], v[200:203], v[176:179], v[102:105]
	v_mfma_f32_16x16x32_bf16 v[98:101], v[210:213], v[176:179], v[98:101]
	v_mfma_f32_16x16x32_bf16 v[86:89], v[200:203], v[184:187], v[86:89]
	v_mfma_f32_16x16x32_bf16 v[82:85], v[210:213], v[184:187], v[82:85]
	v_mfma_f32_16x16x32_bf16 v[70:73], v[200:203], v[192:195], v[70:73]
	v_mfma_f32_16x16x32_bf16 v[66:69], v[210:213], v[192:195], v[66:69]
	s_setprio 0
	s_barrier
	s_add_i32 s38, s74, s56
	v_lshl_add_u64 v[140:141], v[140:141], 0, s[36:37]
	s_mov_b32 m0, s38
	s_nop 0
	global_load_lds_dwordx4 v[140:141], off
	v_lshl_add_u64 v[140:141], v[214:215], 0, s[36:37]
	s_add_i32 m0, s38, 0x2000
	s_nop 0
	global_load_lds_dwordx4 v[140:141], off
	s_mov_b32 m0, s64
	v_lshl_add_u64 v[140:141], v[216:217], 0, s[36:37]
	global_load_lds_dwordx4 v[140:141], off
	v_lshl_add_u64 v[140:141], v[224:225], 0, s[36:37]
	s_mov_b32 m0, s65
	s_nop 0
	global_load_lds_dwordx4 v[140:141], off
	s_add_u32 s38, s48, 0x80080
	s_addc_u32 s39, s49, 0
	s_add_i32 s48, s50, s56
	v_lshl_add_u64 v[140:141], s[38:39], 0, v[0:1]
	s_mov_b32 m0, s48
	s_nop 0
	global_load_lds_dwordx4 v[140:141], off
	v_lshl_add_u64 v[140:141], s[38:39], 0, v[130:131]
	s_add_i32 m0, s48, 0x2000
	s_nop 0
	global_load_lds_dwordx4 v[140:141], off
	ds_read_b128 v[164:167], v145 offset:49152
	ds_read_b128 v[168:171], v145 offset:50176
	ds_read_b128 v[172:175], v145 offset:51200
	ds_read_b128 v[176:179], v145 offset:52224
	ds_read_b128 v[180:183], v145 offset:53248
	ds_read_b128 v[184:187], v145 offset:54272
	ds_read_b128 v[188:191], v145 offset:55296
	ds_read_b128 v[192:195], v145 offset:56320
	s_waitcnt vmcnt(6)
	s_waitcnt lgkmcnt(0)
	s_barrier
; __device__ __forceinline__ unsigned cvt_pk_bf16(float lo, float hi) { unsigned r; asm("v_cvt_pk_bf16_f32 %0, %1, %2" : "=v"(r) : "v"(lo), "v"(hi)); return r; }
; #define PG8_STAGE(bufoff, gbase, voff) do { _Pragma("unroll") for (int _i = 0; _i < 2; ++_i) \
;         __builtin_amdgcn_global_load_lds((const unsigned*)((const char*)(gbase) + (voff)[_i]), (LAS unsigned*)(lds + (bufoff) + ldsw + _i * 8192), 16, 0, 0); } while (0)
; #define PG8_MMA(ai, bj, At, Bt) do { __builtin_amdgcn_s_setprio(1); _Pragma("unroll") for (int m = 0; m < 4; ++m) _Pragma("unroll") for (int n = 0; n < 2; ++n) _Pragma("unroll") for (int k = 0; k < 2; ++k) \
;         acc[ai][bj][m][n] = __builtin_amdgcn_mfma_f32_16x16x32_bf16(Bt[n][k], At[m][k], acc[ai][bj][m][n], 0, 0, 0); __builtin_amdgcn_s_setprio(0); } while (0)
; #define PG8_WAIT_V(n) asm volatile("s_waitcnt vmcnt(" #n ")" ::: "memory")
; #define PG8_BAR __builtin_amdgcn_s_barrier()
;     __device__ __forceinline__ void operator()(const f32x4 (&acc)[2][2][4][2], const Unit& u, int wr, int wc, int fr, int fq) const {
;     ...
;             for (int m = 0; m < 4; ++m) { bf16_t* rowp = O + (size_t)(row0 + ai * HALF + m * 16) * ldc + col0;
; #pragma unroll
;                 for (int bj = 0; bj < 2; ++bj) { f32x4 v0 = acc[ai][bj][m][0], v1 = acc[ai][bj][m][1];
;                     if (ACT == 1) {
; #pragma unroll
;                         for (int j = 0; j < 4; ++j) { float a = fmaxf(v0[j], 0.f), b = fmaxf(v1[j], 0.f); v0[j] = a * a; v1[j] = b * b; } }
;                     u32x4 w; w.x = cvt_pk_bf16(v0[0], v0[1]); w.y = cvt_pk_bf16(v0[2], v0[3]); w.z = cvt_pk_bf16(v1[0], v1[1]); w.w = cvt_pk_bf16(v1[2], v1[3]);
;                     if (ACT == 1) __builtin_nontemporal_store(w, (u32x4*)(rowp + bj * HALF));
;                     else *(u32x4*)(rowp + bj * HALF) = w; } }
; template <class Epi, class Sched>
; __device__ __forceinline__ void gemm_phase(LAS unsigned char* lds, const Gemm g, const Sched& S, const Epi& E) {
;     ...
;             PG8_STAGE(PG8_SB(1, 1), b3 + hstep, voffB);
;             PG8_WAIT_V(6); PG8_BAR; PG8_MMA(1, 1, At, B1); PG8_BAR;
;         }
;         E(acc, cur, wr, wc, fr, fq);
;         if (!has_next) break;
	s_setprio 1
	v_mfma_f32_16x16x32_bf16 v[62:65], v[146:149], v[164:167], v[62:65]
	v_mfma_f32_16x16x32_bf16 v[58:61], v[154:157], v[164:167], v[58:61]
	v_mfma_f32_16x16x32_bf16 v[46:49], v[146:149], v[172:175], v[46:49]
	v_mfma_f32_16x16x32_bf16 v[42:45], v[154:157], v[172:175], v[42:45]
	v_mfma_f32_16x16x32_bf16 v[30:33], v[146:149], v[180:183], v[30:33]
	v_mfma_f32_16x16x32_bf16 v[26:29], v[154:157], v[180:183], v[26:29]
	v_mfma_f32_16x16x32_bf16 v[14:17], v[146:149], v[188:191], v[14:17]
	v_mfma_f32_16x16x32_bf16 v[10:13], v[154:157], v[188:191], v[10:13]
	v_mfma_f32_16x16x32_bf16 v[62:65], v[150:153], v[168:171], v[62:65]
	v_mfma_f32_16x16x32_bf16 v[58:61], v[160:163], v[168:171], v[58:61]
	v_mfma_f32_16x16x32_bf16 v[46:49], v[150:153], v[176:179], v[46:49]
	v_mfma_f32_16x16x32_bf16 v[42:45], v[160:163], v[176:179], v[42:45]
	v_mfma_f32_16x16x32_bf16 v[30:33], v[150:153], v[184:187], v[30:33]
	v_mfma_f32_16x16x32_bf16 v[26:29], v[160:163], v[184:187], v[26:29]
	v_mfma_f32_16x16x32_bf16 v[14:17], v[150:153], v[192:195], v[14:17]
	v_mfma_f32_16x16x32_bf16 v[10:13], v[160:163], v[192:195], v[10:13]
	v_mfma_f32_16x16x32_bf16 v[54:57], v[196:199], v[164:167], v[54:57]
	v_mfma_f32_16x16x32_bf16 v[50:53], v[204:207], v[164:167], v[50:53]
	v_mfma_f32_16x16x32_bf16 v[38:41], v[196:199], v[172:175], v[38:41]
	v_mfma_f32_16x16x32_bf16 v[34:37], v[204:207], v[172:175], v[34:37]
	v_mfma_f32_16x16x32_bf16 v[22:25], v[196:199], v[180:183], v[22:25]
	v_mfma_f32_16x16x32_bf16 v[18:21], v[204:207], v[180:183], v[18:21]
	v_mfma_f32_16x16x32_bf16 v[6:9], v[196:199], v[188:191], v[6:9]
	v_mfma_f32_16x16x32_bf16 v[2:5], v[204:207], v[188:191], v[2:5]
	v_mfma_f32_16x16x32_bf16 v[54:57], v[200:203], v[168:171], v[54:57]
	v_mfma_f32_16x16x32_bf16 v[50:53], v[210:213], v[168:171], v[50:53]
	v_mfma_f32_16x16x32_bf16 v[38:41], v[200:203], v[176:179], v[38:41]
	v_mfma_f32_16x16x32_bf16 v[34:37], v[210:213], v[176:179], v[34:37]
	v_mfma_f32_16x16x32_bf16 v[22:25], v[200:203], v[184:187], v[22:25]
	v_mfma_f32_16x16x32_bf16 v[18:21], v[210:213], v[184:187], v[18:21]
	v_mfma_f32_16x16x32_bf16 v[6:9], v[200:203], v[192:195], v[6:9]
	v_mfma_f32_16x16x32_bf16 v[2:5], v[210:213], v[192:195], v[2:5]
	s_setprio 0
	s_add_i32 s73, s73, 2
	s_add_u32 s71, s71, 0x100
	s_addc_u32 s72, s72, 0
	s_add_u32 s46, s46, 0x100
	s_addc_u32 s47, s47, 0
	s_cmp_gt_u32 s73, 29
	s_barrier
	s_cbranch_scc0 .LBB0_73
	v_lshl_add_u32 v146, s8, 8, v142
	v_max_f32_e32 v122, v122, v122
	v_ashrrev_i32_e32 v147, 31, v146
	v_max_f32_e32 v122, 0, v122
	v_max_f32_e32 v123, v123, v123
	v_max_f32_e32 v124, v124, v124
	v_lshl_or_b32 v140, s68, 8, v144
	v_lshlrev_b64 v[148:149], 14, v[146:147]
	v_mul_f32_e32 v147, v122, v122
	v_max_f32_e32 v122, v127, v127
	v_max_f32_e32 v123, 0, v123
	v_max_f32_e32 v124, 0, v124
	v_ashrrev_i32_e32 v141, 31, v140
	v_max_f32_e32 v126, v126, v126
	v_max_f32_e32 v122, 0, v122
	v_mul_f32_e32 v127, v123, v123
	v_max_f32_e32 v123, v128, v128
	v_mul_f32_e32 v128, v124, v124
	v_max_f32_e32 v124, v129, v129
	v_max_f32_e32 v125, v125, v125
	v_lshl_add_u64 v[148:149], s[24:25], 0, v[148:149]
	v_lshlrev_b64 v[150:151], 1, v[140:141]
	v_max_f32_e32 v126, 0, v126
	v_mul_f32_e32 v122, v122, v122
	v_max_f32_e32 v123, 0, v123
	v_max_f32_e32 v124, 0, v124
	v_max_f32_e32 v125, 0, v125
	v_max_f32_e32 v114, v114, v114
	v_lshl_add_u64 v[140:141], v[148:149], 0, v[150:151]
	v_mul_f32_e32 v126, v126, v126
	v_mul_f32_e32 v123, v123, v123
	v_mul_f32_e32 v124, v124, v124
	v_mul_f32_e32 v125, v125, v125
	v_cvt_pk_bf16_f32 v122, v126, v122
	v_max_f32_e32 v114, 0, v114
	v_max_f32_e32 v115, v115, v115
	v_max_f32_e32 v116, v116, v116
	v_cvt_pk_bf16_f32 v123, v123, v124
	v_cvt_pk_bf16_f32 v124, v147, v127
	v_cvt_pk_bf16_f32 v125, v128, v125
	global_store_dwordx4 v[140:141], v[122:125], off nt
	v_max_f32_e32 v115, 0, v115
	v_max_f32_e32 v116, 0, v116
	v_mul_f32_e32 v122, v114, v114
	v_max_f32_e32 v114, v119, v119
	v_max_f32_e32 v118, v118, v118
	v_max_f32_e32 v114, 0, v114
	v_mul_f32_e32 v119, v115, v115
	v_max_f32_e32 v115, v120, v120
	v_mul_f32_e32 v120, v116, v116
	v_max_f32_e32 v116, v121, v121
	v_max_f32_e32 v117, v117, v117
	v_max_f32_e32 v118, 0, v118
	v_mul_f32_e32 v114, v114, v114
	v_max_f32_e32 v115, 0, v115
	v_max_f32_e32 v116, 0, v116
	v_max_f32_e32 v117, 0, v117
	v_mul_f32_e32 v118, v118, v118
	v_mul_f32_e32 v115, v115, v115
	v_mul_f32_e32 v116, v116, v116
	v_mul_f32_e32 v117, v117, v117
	v_cvt_pk_bf16_f32 v114, v118, v114
	v_max_f32_e32 v106, v106, v106
	v_cvt_pk_bf16_f32 v115, v115, v116
	v_cvt_pk_bf16_f32 v116, v122, v119
	v_cvt_pk_bf16_f32 v117, v120, v117
	global_store_dwordx4 v[140:141], v[114:117], off offset:256 nt
	v_max_f32_e32 v106, 0, v106
	v_max_f32_e32 v107, v107, v107
	v_or_b32_e32 v114, 16, v146
	v_max_f32_e32 v108, v108, v108
	v_ashrrev_i32_e32 v115, 31, v114
	v_mul_f32_e32 v116, v106, v106
	v_max_f32_e32 v106, v111, v111
	v_max_f32_e32 v107, 0, v107
	v_max_f32_e32 v108, 0, v108
	v_lshlrev_b64 v[114:115], 14, v[114:115]
	v_max_f32_e32 v110, v110, v110
	v_max_f32_e32 v106, 0, v106
	v_mul_f32_e32 v111, v107, v107
	v_max_f32_e32 v107, v112, v112
	v_mul_f32_e32 v112, v108, v108
	v_max_f32_e32 v108, v113, v113
	v_max_f32_e32 v109, v109, v109
	v_lshl_add_u64 v[114:115], s[24:25], 0, v[114:115]
	v_max_f32_e32 v110, 0, v110
	v_mul_f32_e32 v106, v106, v106
	v_max_f32_e32 v107, 0, v107
	v_max_f32_e32 v108, 0, v108
	v_max_f32_e32 v109, 0, v109
	v_max_f32_e32 v98, v98, v98
	v_lshl_add_u64 v[114:115], v[114:115], 0, v[150:151]
	v_mul_f32_e32 v110, v110, v110
	v_mul_f32_e32 v107, v107, v107
	v_mul_f32_e32 v108, v108, v108
	v_mul_f32_e32 v109, v109, v109
	v_cvt_pk_bf16_f32 v106, v110, v106
; __device__ __forceinline__ unsigned cvt_pk_bf16(float lo, float hi) { unsigned r; asm("v_cvt_pk_bf16_f32 %0, %1, %2" : "=v"(r) : "v"(lo), "v"(hi)); return r; }
;     __device__ __forceinline__ void operator()(const f32x4 (&acc)[2][2][4][2], const Unit& u, int wr, int wc, int fr, int fq) const {
;     ...
;             for (int m = 0; m < 4; ++m) { bf16_t* rowp = O + (size_t)(row0 + ai * HALF + m * 16) * ldc + col0;
; #pragma unroll
;                 for (int bj = 0; bj < 2; ++bj) { f32x4 v0 = acc[ai][bj][m][0], v1 = acc[ai][bj][m][1];
;                     if (ACT == 1) {
; #pragma unroll
;                         for (int j = 0; j < 4; ++j) { float a = fmaxf(v0[j], 0.f), b = fmaxf(v1[j], 0.f); v0[j] = a * a; v1[j] = b * b; } }
;                     u32x4 w; w.x = cvt_pk_bf16(v0[0], v0[1]); w.y = cvt_pk_bf16(v0[2], v0[3]); w.z = cvt_pk_bf16(v1[0], v1[1]); w.w = cvt_pk_bf16(v1[2], v1[3]);
;                     if (ACT == 1) __builtin_nontemporal_store(w, (u32x4*)(rowp + bj * HALF));
;                     else *(u32x4*)(rowp + bj * HALF) = w; } }
	v_max_f32_e32 v98, 0, v98
	v_max_f32_e32 v99, v99, v99
	v_max_f32_e32 v100, v100, v100
	v_cvt_pk_bf16_f32 v107, v107, v108
	v_cvt_pk_bf16_f32 v108, v116, v111
	v_cvt_pk_bf16_f32 v109, v112, v109
	global_store_dwordx4 v[114:115], v[106:109], off nt
	v_max_f32_e32 v99, 0, v99
	v_max_f32_e32 v100, 0, v100
	v_mul_f32_e32 v106, v98, v98
	v_max_f32_e32 v98, v103, v103
	v_max_f32_e32 v102, v102, v102
	v_max_f32_e32 v98, 0, v98
	v_mul_f32_e32 v103, v99, v99
	v_max_f32_e32 v99, v104, v104
	v_mul_f32_e32 v104, v100, v100
	v_max_f32_e32 v100, v105, v105
	v_max_f32_e32 v101, v101, v101
	v_max_f32_e32 v102, 0, v102
	v_mul_f32_e32 v98, v98, v98
	v_max_f32_e32 v99, 0, v99
	v_max_f32_e32 v100, 0, v100
	v_max_f32_e32 v101, 0, v101
	v_mul_f32_e32 v102, v102, v102
	v_mul_f32_e32 v99, v99, v99
	v_mul_f32_e32 v100, v100, v100
	v_mul_f32_e32 v101, v101, v101
	v_cvt_pk_bf16_f32 v98, v102, v98
	v_max_f32_e32 v90, v90, v90
	v_cvt_pk_bf16_f32 v99, v99, v100
	v_cvt_pk_bf16_f32 v100, v106, v103
	v_cvt_pk_bf16_f32 v101, v104, v101
	global_store_dwordx4 v[114:115], v[98:101], off offset:256 nt
	v_max_f32_e32 v90, 0, v90
	v_max_f32_e32 v91, v91, v91
	v_or_b32_e32 v98, 32, v146
	v_max_f32_e32 v92, v92, v92
	v_ashrrev_i32_e32 v99, 31, v98
	v_mul_f32_e32 v100, v90, v90
	v_max_f32_e32 v90, v95, v95
	v_max_f32_e32 v91, 0, v91
	v_max_f32_e32 v92, 0, v92
	v_lshlrev_b64 v[98:99], 14, v[98:99]
	v_max_f32_e32 v94, v94, v94
	v_max_f32_e32 v90, 0, v90
	v_mul_f32_e32 v95, v91, v91
	v_max_f32_e32 v91, v96, v96
	v_mul_f32_e32 v96, v92, v92
	v_max_f32_e32 v92, v97, v97
	v_max_f32_e32 v93, v93, v93
	v_lshl_add_u64 v[98:99], s[24:25], 0, v[98:99]
	v_max_f32_e32 v94, 0, v94
	v_mul_f32_e32 v90, v90, v90
	v_max_f32_e32 v91, 0, v91
	v_max_f32_e32 v92, 0, v92
	v_max_f32_e32 v93, 0, v93
	v_max_f32_e32 v82, v82, v82
	v_lshl_add_u64 v[98:99], v[98:99], 0, v[150:151]
	v_mul_f32_e32 v94, v94, v94
	v_mul_f32_e32 v91, v91, v91
	v_mul_f32_e32 v92, v92, v92
	v_mul_f32_e32 v93, v93, v93
	v_cvt_pk_bf16_f32 v90, v94, v90
	v_max_f32_e32 v82, 0, v82
	v_max_f32_e32 v83, v83, v83
	v_max_f32_e32 v84, v84, v84
	v_cvt_pk_bf16_f32 v91, v91, v92
	v_cvt_pk_bf16_f32 v92, v100, v95
	v_cvt_pk_bf16_f32 v93, v96, v93
	global_store_dwordx4 v[98:99], v[90:93], off nt
	v_max_f32_e32 v83, 0, v83
	v_max_f32_e32 v84, 0, v84
	v_mul_f32_e32 v90, v82, v82
	v_max_f32_e32 v82, v87, v87
	v_max_f32_e32 v86, v86, v86
	v_max_f32_e32 v82, 0, v82
	v_mul_f32_e32 v87, v83, v83
	v_max_f32_e32 v83, v88, v88
	v_mul_f32_e32 v88, v84, v84
	v_max_f32_e32 v84, v89, v89
	v_max_f32_e32 v85, v85, v85
	v_max_f32_e32 v86, 0, v86
	v_mul_f32_e32 v82, v82, v82
	v_max_f32_e32 v83, 0, v83
	v_max_f32_e32 v84, 0, v84
	v_max_f32_e32 v85, 0, v85
	v_mul_f32_e32 v86, v86, v86
	v_mul_f32_e32 v83, v83, v83
	v_mul_f32_e32 v84, v84, v84
	v_mul_f32_e32 v85, v85, v85
	v_cvt_pk_bf16_f32 v82, v86, v82
	v_max_f32_e32 v74, v74, v74
	v_cvt_pk_bf16_f32 v83, v83, v84
	v_cvt_pk_bf16_f32 v84, v90, v87
	v_cvt_pk_bf16_f32 v85, v88, v85
	global_store_dwordx4 v[98:99], v[82:85], off offset:256 nt
	v_max_f32_e32 v74, 0, v74
	v_max_f32_e32 v75, v75, v75
	v_or_b32_e32 v82, 48, v146
	v_max_f32_e32 v76, v76, v76
	v_ashrrev_i32_e32 v83, 31, v82
	v_mul_f32_e32 v84, v74, v74
	v_max_f32_e32 v74, v79, v79
	v_max_f32_e32 v75, 0, v75
	v_max_f32_e32 v76, 0, v76
	v_lshlrev_b64 v[82:83], 14, v[82:83]
	v_max_f32_e32 v78, v78, v78
	v_max_f32_e32 v74, 0, v74
	v_mul_f32_e32 v79, v75, v75
	v_max_f32_e32 v75, v80, v80
	v_mul_f32_e32 v80, v76, v76
	v_max_f32_e32 v76, v81, v81
	v_max_f32_e32 v77, v77, v77
	v_lshl_add_u64 v[82:83], s[24:25], 0, v[82:83]
	v_max_f32_e32 v78, 0, v78
	v_mul_f32_e32 v74, v74, v74
	v_max_f32_e32 v75, 0, v75
	v_max_f32_e32 v76, 0, v76
	v_max_f32_e32 v77, 0, v77
	v_max_f32_e32 v66, v66, v66
	v_max_f32_e32 v67, v67, v67
	v_max_f32_e32 v68, v68, v68
	v_lshl_add_u64 v[82:83], v[82:83], 0, v[150:151]
	v_mul_f32_e32 v78, v78, v78
	v_mul_f32_e32 v75, v75, v75
	v_mul_f32_e32 v76, v76, v76
	v_mul_f32_e32 v77, v77, v77
	v_cvt_pk_bf16_f32 v74, v78, v74
	v_max_f32_e32 v66, 0, v66
	v_max_f32_e32 v67, 0, v67
	v_max_f32_e32 v68, 0, v68
	v_cvt_pk_bf16_f32 v75, v75, v76
	v_cvt_pk_bf16_f32 v76, v84, v79
	v_cvt_pk_bf16_f32 v77, v80, v77
	global_store_dwordx4 v[82:83], v[74:77], off nt
	v_max_f32_e32 v69, v69, v69
	v_max_f32_e32 v70, v70, v70
	v_mul_f32_e32 v74, v66, v66
	v_max_f32_e32 v66, v71, v71
	v_mul_f32_e32 v71, v67, v67
	v_max_f32_e32 v67, v72, v72
	v_mul_f32_e32 v72, v68, v68
	v_max_f32_e32 v68, v73, v73
	v_max_f32_e32 v67, 0, v67
	v_max_f32_e32 v68, 0, v68
	v_max_f32_e32 v66, 0, v66
	v_mul_f32_e32 v67, v67, v67
	v_max_f32_e32 v69, 0, v69
	v_mul_f32_e32 v68, v68, v68
	v_max_f32_e32 v58, v58, v58
	v_max_f32_e32 v70, 0, v70
	v_mul_f32_e32 v66, v66, v66
	v_mul_f32_e32 v69, v69, v69
	v_cvt_pk_bf16_f32 v67, v67, v68
	v_cvt_pk_bf16_f32 v68, v74, v71
	v_max_f32_e32 v58, 0, v58
	v_max_f32_e32 v59, v59, v59
	v_max_f32_e32 v60, v60, v60
	v_mul_f32_e32 v70, v70, v70
	v_cvt_pk_bf16_f32 v66, v70, v66
	v_cvt_pk_bf16_f32 v69, v72, v69
	global_store_dwordx4 v[82:83], v[66:69], off offset:256 nt
	v_max_f32_e32 v62, v62, v62
	v_max_f32_e32 v59, 0, v59
	v_mul_f32_e32 v68, v58, v58
	v_max_f32_e32 v58, v63, v63
	v_max_f32_e32 v60, 0, v60
	v_max_f32_e32 v62, 0, v62
	v_max_f32_e32 v58, 0, v58
	v_mul_f32_e32 v63, v59, v59
	v_max_f32_e32 v59, v64, v64
	v_mul_f32_e32 v64, v60, v60
	v_max_f32_e32 v60, v65, v65
	v_mul_f32_e32 v62, v62, v62
	v_mul_f32_e32 v58, v58, v58
	v_max_f32_e32 v59, 0, v59
	v_max_f32_e32 v60, 0, v60
	v_max_f32_e32 v61, v61, v61
	s_mov_b32 s8, 0x200000
	v_mul_f32_e32 v59, v59, v59
	v_max_f32_e32 v61, 0, v61
	v_mul_f32_e32 v60, v60, v60
	v_cvt_pk_bf16_f32 v58, v62, v58
	v_add_co_u32_e32 v62, vcc, s8, v140
; __device__ __forceinline__ unsigned cvt_pk_bf16(float lo, float hi) { unsigned r; asm("v_cvt_pk_bf16_f32 %0, %1, %2" : "=v"(r) : "v"(lo), "v"(hi)); return r; }
;     __device__ __forceinline__ void operator()(const f32x4 (&acc)[2][2][4][2], const Unit& u, int wr, int wc, int fr, int fq) const {
;     ...
;                 for (int bj = 0; bj < 2; ++bj) { f32x4 v0 = acc[ai][bj][m][0], v1 = acc[ai][bj][m][1];
;                     if (ACT == 1) {
; #pragma unroll
;                         for (int j = 0; j < 4; ++j) { float a = fmaxf(v0[j], 0.f), b = fmaxf(v1[j], 0.f); v0[j] = a * a; v1[j] = b * b; } }
;                     u32x4 w; w.x = cvt_pk_bf16(v0[0], v0[1]); w.y = cvt_pk_bf16(v0[2], v0[3]); w.z = cvt_pk_bf16(v1[0], v1[1]); w.w = cvt_pk_bf16(v1[2], v1[3]);
;                     if (ACT == 1) __builtin_nontemporal_store(w, (u32x4*)(rowp + bj * HALF));
;                     else *(u32x4*)(rowp + bj * HALF) = w; } }
; template <class Epi, class Sched>
; __device__ __forceinline__ void gemm_phase(LAS unsigned char* lds, const Gemm g, const Sched& S, const Epi& E) {
;     ...
;         E(acc, cur, wr, wc, fr, fq);
;         if (!has_next) break;
; #pragma unroll
;         for (int a = 0; a < 2; ++a)
; #pragma unroll
;             for (int b = 0; b < 2; ++b)
; #pragma unroll
;                 for (int m = 0; m < 4; ++m)
; #pragma unroll
;                     for (int n = 0; n < 2; ++n) acc[a][b][m][n] = (f32x4){0.f, 0.f, 0.f, 0.f};
;         cur = nxt; cA = nA; cB = nB; ++ui;
	v_max_f32_e32 v50, v50, v50
	v_max_f32_e32 v51, v51, v51
	v_max_f32_e32 v52, v52, v52
	v_mul_f32_e32 v61, v61, v61
	v_cvt_pk_bf16_f32 v59, v59, v60
	v_cvt_pk_bf16_f32 v60, v68, v63
	v_addc_co_u32_e32 v63, vcc, 0, v141, vcc
	v_max_f32_e32 v50, 0, v50
	v_max_f32_e32 v51, 0, v51
	v_max_f32_e32 v52, 0, v52
	v_cvt_pk_bf16_f32 v61, v64, v61
	global_store_dwordx4 v[62:63], v[58:61], off nt
	v_max_f32_e32 v53, v53, v53
	s_mov_b64 s[38:39], 0x200000
	v_mul_f32_e32 v58, v50, v50
	v_max_f32_e32 v50, v55, v55
	v_mul_f32_e32 v55, v51, v51
	v_max_f32_e32 v51, v56, v56
	v_mul_f32_e32 v56, v52, v52
	v_max_f32_e32 v52, v57, v57
	v_max_f32_e32 v51, 0, v51
	v_max_f32_e32 v52, 0, v52
	v_max_f32_e32 v54, v54, v54
	v_max_f32_e32 v50, 0, v50
	v_mul_f32_e32 v51, v51, v51
	v_max_f32_e32 v53, 0, v53
	v_mul_f32_e32 v52, v52, v52
	v_max_f32_e32 v42, v42, v42
	v_lshl_add_u64 v[66:67], v[140:141], 0, s[38:39]
	v_max_f32_e32 v54, 0, v54
	v_mul_f32_e32 v50, v50, v50
	v_mul_f32_e32 v53, v53, v53
	v_cvt_pk_bf16_f32 v51, v51, v52
	v_cvt_pk_bf16_f32 v52, v58, v55
	v_max_f32_e32 v42, 0, v42
	v_max_f32_e32 v43, v43, v43
	v_max_f32_e32 v44, v44, v44
	v_mul_f32_e32 v54, v54, v54
	v_cvt_pk_bf16_f32 v50, v54, v50
	v_cvt_pk_bf16_f32 v53, v56, v53
	global_store_dwordx4 v[66:67], v[50:53], off offset:256 nt
	v_max_f32_e32 v46, v46, v46
	v_max_f32_e32 v43, 0, v43
	v_mul_f32_e32 v52, v42, v42
	v_max_f32_e32 v42, v47, v47
	v_max_f32_e32 v44, 0, v44
	v_max_f32_e32 v46, 0, v46
	v_max_f32_e32 v42, 0, v42
	v_mul_f32_e32 v47, v43, v43
	v_max_f32_e32 v43, v48, v48
	v_mul_f32_e32 v48, v44, v44
	v_max_f32_e32 v44, v49, v49
	v_mul_f32_e32 v46, v46, v46
	v_mul_f32_e32 v42, v42, v42
	v_max_f32_e32 v43, 0, v43
	v_max_f32_e32 v44, 0, v44
	v_max_f32_e32 v45, v45, v45
	s_mov_b32 s8, 0x240000
	v_mul_f32_e32 v43, v43, v43
	v_max_f32_e32 v45, 0, v45
	v_mul_f32_e32 v44, v44, v44
	v_cvt_pk_bf16_f32 v42, v46, v42
	v_add_co_u32_e32 v46, vcc, s8, v140
	v_max_f32_e32 v34, v34, v34
	v_max_f32_e32 v35, v35, v35
	v_max_f32_e32 v36, v36, v36
	v_mul_f32_e32 v45, v45, v45
	v_cvt_pk_bf16_f32 v43, v43, v44
	v_cvt_pk_bf16_f32 v44, v52, v47
	v_addc_co_u32_e32 v47, vcc, 0, v141, vcc
	v_max_f32_e32 v34, 0, v34
	v_max_f32_e32 v35, 0, v35
	v_max_f32_e32 v36, 0, v36
	v_cvt_pk_bf16_f32 v45, v48, v45
	global_store_dwordx4 v[46:47], v[42:45], off nt
	v_max_f32_e32 v37, v37, v37
	s_mov_b64 s[38:39], 0x240000
	v_mul_f32_e32 v42, v34, v34
	v_max_f32_e32 v34, v39, v39
	v_mul_f32_e32 v39, v35, v35
	v_max_f32_e32 v35, v40, v40
	v_mul_f32_e32 v40, v36, v36
	v_max_f32_e32 v36, v41, v41
	v_max_f32_e32 v35, 0, v35
	v_max_f32_e32 v36, 0, v36
	v_max_f32_e32 v38, v38, v38
	v_max_f32_e32 v34, 0, v34
	v_mul_f32_e32 v35, v35, v35
	v_max_f32_e32 v37, 0, v37
	v_mul_f32_e32 v36, v36, v36
	v_max_f32_e32 v26, v26, v26
	v_lshl_add_u64 v[50:51], v[140:141], 0, s[38:39]
	v_max_f32_e32 v38, 0, v38
	v_mul_f32_e32 v34, v34, v34
	v_mul_f32_e32 v37, v37, v37
	v_cvt_pk_bf16_f32 v35, v35, v36
	v_cvt_pk_bf16_f32 v36, v42, v39
	v_max_f32_e32 v26, 0, v26
	v_max_f32_e32 v27, v27, v27
	v_max_f32_e32 v28, v28, v28
	v_mul_f32_e32 v38, v38, v38
	v_cvt_pk_bf16_f32 v34, v38, v34
	v_cvt_pk_bf16_f32 v37, v40, v37
	global_store_dwordx4 v[50:51], v[34:37], off offset:256 nt
	v_max_f32_e32 v30, v30, v30
	v_max_f32_e32 v27, 0, v27
	v_mul_f32_e32 v36, v26, v26
	v_max_f32_e32 v26, v31, v31
	v_max_f32_e32 v28, 0, v28
	v_max_f32_e32 v30, 0, v30
	v_max_f32_e32 v26, 0, v26
	v_mul_f32_e32 v31, v27, v27
	v_max_f32_e32 v27, v32, v32
	v_mul_f32_e32 v32, v28, v28
	v_max_f32_e32 v28, v33, v33
	v_mul_f32_e32 v30, v30, v30
	v_mul_f32_e32 v26, v26, v26
	v_max_f32_e32 v27, 0, v27
	v_max_f32_e32 v28, 0, v28
	v_max_f32_e32 v29, v29, v29
	s_mov_b32 s8, 0x280000
	v_mul_f32_e32 v27, v27, v27
	v_max_f32_e32 v29, 0, v29
	v_mul_f32_e32 v28, v28, v28
	v_cvt_pk_bf16_f32 v26, v30, v26
	v_add_co_u32_e32 v30, vcc, s8, v140
	v_max_f32_e32 v18, v18, v18
	v_max_f32_e32 v19, v19, v19
	v_max_f32_e32 v20, v20, v20
	v_mul_f32_e32 v29, v29, v29
	v_cvt_pk_bf16_f32 v27, v27, v28
	v_cvt_pk_bf16_f32 v28, v36, v31
	v_addc_co_u32_e32 v31, vcc, 0, v141, vcc
	v_max_f32_e32 v18, 0, v18
	v_max_f32_e32 v19, 0, v19
	v_max_f32_e32 v20, 0, v20
	v_cvt_pk_bf16_f32 v29, v32, v29
	global_store_dwordx4 v[30:31], v[26:29], off nt
	v_max_f32_e32 v21, v21, v21
	s_mov_b64 s[38:39], 0x280000
	v_mul_f32_e32 v26, v18, v18
	v_max_f32_e32 v18, v23, v23
	v_mul_f32_e32 v23, v19, v19
	v_max_f32_e32 v19, v24, v24
	v_mul_f32_e32 v24, v20, v20
	v_max_f32_e32 v20, v25, v25
	v_max_f32_e32 v19, 0, v19
	v_max_f32_e32 v20, 0, v20
	v_max_f32_e32 v22, v22, v22
	v_max_f32_e32 v18, 0, v18
	v_mul_f32_e32 v19, v19, v19
	v_max_f32_e32 v21, 0, v21
	v_mul_f32_e32 v20, v20, v20
	v_max_f32_e32 v10, v10, v10
	v_lshl_add_u64 v[34:35], v[140:141], 0, s[38:39]
	v_max_f32_e32 v22, 0, v22
	v_mul_f32_e32 v18, v18, v18
	v_mul_f32_e32 v21, v21, v21
	v_cvt_pk_bf16_f32 v19, v19, v20
	v_cvt_pk_bf16_f32 v20, v26, v23
	v_max_f32_e32 v10, 0, v10
	v_max_f32_e32 v11, v11, v11
	v_max_f32_e32 v12, v12, v12
	v_mul_f32_e32 v22, v22, v22
	v_cvt_pk_bf16_f32 v18, v22, v18
	v_cvt_pk_bf16_f32 v21, v24, v21
	global_store_dwordx4 v[34:35], v[18:21], off offset:256 nt
	v_max_f32_e32 v14, v14, v14
	v_max_f32_e32 v11, 0, v11
	v_mul_f32_e32 v20, v10, v10
	v_max_f32_e32 v10, v15, v15
	v_max_f32_e32 v12, 0, v12
	v_max_f32_e32 v14, 0, v14
	v_max_f32_e32 v10, 0, v10
	v_mul_f32_e32 v15, v11, v11
	v_max_f32_e32 v11, v16, v16
	v_mul_f32_e32 v16, v12, v12
	v_max_f32_e32 v12, v17, v17
	v_mul_f32_e32 v14, v14, v14
	v_mul_f32_e32 v10, v10, v10
	v_max_f32_e32 v11, 0, v11
	v_max_f32_e32 v12, 0, v12
	v_max_f32_e32 v13, v13, v13
	s_mov_b32 s8, 0x2c0000
	v_mul_f32_e32 v11, v11, v11
	v_max_f32_e32 v13, 0, v13
	v_mul_f32_e32 v12, v12, v12
	v_cvt_pk_bf16_f32 v10, v14, v10
	v_add_co_u32_e32 v14, vcc, s8, v140
	v_max_f32_e32 v2, v2, v2
	v_max_f32_e32 v3, v3, v3
	v_max_f32_e32 v4, v4, v4
	v_mul_f32_e32 v13, v13, v13
	v_cvt_pk_bf16_f32 v11, v11, v12
	v_cvt_pk_bf16_f32 v12, v20, v15
	v_addc_co_u32_e32 v15, vcc, 0, v141, vcc
	v_max_f32_e32 v2, 0, v2
	v_max_f32_e32 v3, 0, v3
	v_max_f32_e32 v4, 0, v4
	v_cvt_pk_bf16_f32 v13, v16, v13
	global_store_dwordx4 v[14:15], v[10:13], off nt
	v_max_f32_e32 v5, v5, v5
	s_mov_b64 s[38:39], 0x2c0000
	v_mul_f32_e32 v10, v2, v2
	v_max_f32_e32 v2, v7, v7
	v_mul_f32_e32 v7, v3, v3
	v_max_f32_e32 v3, v8, v8
	v_mul_f32_e32 v8, v4, v4
	v_max_f32_e32 v4, v9, v9
	v_max_f32_e32 v6, v6, v6
	v_max_f32_e32 v2, 0, v2
	v_max_f32_e32 v3, 0, v3
	v_max_f32_e32 v4, 0, v4
	v_max_f32_e32 v5, 0, v5
	v_lshl_add_u64 v[18:19], v[140:141], 0, s[38:39]
	v_max_f32_e32 v6, 0, v6
	v_mul_f32_e32 v2, v2, v2
	v_mul_f32_e32 v3, v3, v3
	v_mul_f32_e32 v4, v4, v4
	v_mul_f32_e32 v5, v5, v5
	s_and_b64 vcc, exec, s[40:41]
	s_mov_b32 s68, s26
	s_mov_b32 s8, s28
	s_mov_b64 s[46:47], s[44:45]
	s_mov_b64 s[48:49], s[42:43]
	v_mul_f32_e32 v6, v6, v6
	v_cvt_pk_bf16_f32 v2, v6, v2
	v_cvt_pk_bf16_f32 v3, v3, v4
	v_cvt_pk_bf16_f32 v4, v10, v7
	v_cvt_pk_bf16_f32 v5, v8, v5
	global_store_dwordx4 v[18:19], v[2:5], off offset:256 nt
	s_cbranch_vccz .LBB0_70
; #define PG8_WAIT_V(n) asm volatile("s_waitcnt vmcnt(" #n ")" ::: "memory")
; #define PG8_BAR __builtin_amdgcn_s_barrier()
; template <class Epi, class Sched>
; __device__ __forceinline__ void gemm_phase(LAS unsigned char* lds, const Gemm g, const Sched& S, const Epi& E) {
;     ...
;     PG8_WAIT_V(0);
;     if (wr == 0) PG8_BAR;
;     PG8_BAR;
	s_waitcnt vmcnt(0)
	s_cmpk_gt_u32 s52, 0xff
	s_cbranch_scc1 .LBB0_77
	s_barrier

; #define PG8_STAGE(bufoff, gbase, voff) do { _Pragma("unroll") for (int _i = 0; _i < 2; ++_i) \
;         __builtin_amdgcn_global_load_lds((const unsigned*)((const char*)(gbase) + (voff)[_i]), (LAS unsigned*)(lds + (bufoff) + ldsw + _i * 8192), 16, 0, 0); } while (0)
; #define PG8_LDA(dst, b, h) do { _Pragma("unroll") for (int m = 0; m < 4; ++m) _Pragma("unroll") for (int k = 0; k < 2; ++k) dst[m][k] = *(const LAS bf16x8*)(lds + PG8_SA(b, h) + aoff + m * 2048 + k * 1024); } while (0)
; #define PG8_LDB(dst, b, h) do { _Pragma("unroll") for (int n = 0; n < 2; ++n) _Pragma("unroll") for (int k = 0; k < 2; ++k) dst[n][k] = *(const LAS bf16x8*)(lds + PG8_SB(b, h) + boff + n * 2048 + k * 1024); } while (0)
; #define PG8_MMA(ai, bj, At, Bt) do { __builtin_amdgcn_s_setprio(1); _Pragma("unroll") for (int m = 0; m < 4; ++m) _Pragma("unroll") for (int n = 0; n < 2; ++n) _Pragma("unroll") for (int k = 0; k < 2; ++k) \
;         acc[ai][bj][m][n] = __builtin_amdgcn_mfma_f32_16x16x32_bf16(Bt[n][k], At[m][k], acc[ai][bj][m][n], 0, 0, 0); __builtin_amdgcn_s_setprio(0); } while (0)
; #define PG8_WAIT_V(n) asm volatile("s_waitcnt vmcnt(" #n ")" ::: "memory")
; #define PG8_WAIT_L(n) asm volatile("s_waitcnt lgkmcnt(" #n ")" ::: "memory")
; template <class Epi, class Sched>
; __device__ __forceinline__ void gemm_phase(LAS unsigned char* lds, const Gemm g, const Sched& S, const Epi& E) {
;     ...
;         for (int t = 0; t < nt; t += 2) {
;             const bool last = (t == nt - 2);
;             const char* a1 = cA + (size_t)(t + 1) * kstep;
;             const char* a2 = last ? nA : cA + (size_t)(t + 2) * kstep; const char* b2 = last ? nB : cB + (size_t)(t + 2) * kstep;
;             const char* a3 = a2 + kstep; const char* b3 = b2 + kstep;
;             PG8_LDB(B0, 0, 0); PG8_SCHED; PG8_LDA(At, 0, 0); PG8_STAGE(PG8_SA(1, 1), a1 + hstep, voffA);
;             PG8_WAIT_L(8); PG8_BAR; PG8_WAIT_L(0); PG8_MMA(0, 0, At, B0); PG8_BAR; PG8_SCHED;
;             PG8_LDB(B1, 0, 1); PG8_STAGE(PG8_SB(0, 0), b2, voffB);
;             PG8_BAR; PG8_WAIT_L(0); PG8_MMA(0, 1, At, B1); PG8_BAR;
;             PG8_LDA(At, 0, 1); PG8_STAGE(PG8_SA(0, 0), a2, voffA);
;             PG8_BAR; PG8_WAIT_L(0); PG8_MMA(1, 0, At, B0); PG8_BAR; PG8_SCHED;
;             PG8_STAGE(PG8_SB(0, 1), b2 + hstep, voffB);
;             PG8_WAIT_V(6); PG8_BAR; PG8_MMA(1, 1, At, B1); PG8_BAR;
.LBB0_99:
	s_add_u32 s56, s28, 0x100
	s_addc_u32 s57, s29, 0
	s_cmp_eq_u32 s81, 28
	s_cselect_b32 s61, s51, s57
	s_cselect_b32 s60, s77, s56
	s_cselect_b32 s59, s49, s80
	s_cselect_b32 s58, s78, s79
	v_lshl_add_u64 v[156:157], s[28:29], 0, v[150:151]
	s_add_i32 m0, s9, 0xc000
	s_nop 0
	global_load_lds_dwordx4 v[156:157], off
	v_lshl_add_u64 v[156:157], s[28:29], 0, v[148:149]
	s_add_i32 m0, s9, 0xe000
	s_nop 0
	global_load_lds_dwordx4 v[156:157], off
	s_add_i32 s38, 0, 0x10000
	v_add_u32_e32 v110, s38, v169
	ds_read_b128 v[98:101], v110
	ds_read_b128 v[102:105], v110 offset:1024
	ds_read_b128 v[106:109], v110 offset:2048
	ds_read_b128 v[110:113], v110 offset:3072
	ds_read_b128 v[152:155], v171
	ds_read_b128 v[160:163], v171 offset:1024
	ds_read_b128 v[164:167], v171 offset:2048
	ds_read_b128 v[172:175], v171 offset:3072
	ds_read_b128 v[176:179], v171 offset:4096
	ds_read_b128 v[180:183], v171 offset:5120
	ds_read_b128 v[184:187], v171 offset:6144
	ds_read_b128 v[188:191], v171 offset:7168
	s_add_i32 s39, 0, 0x14000
	v_add_u32_e32 v156, s39, v169
	ds_read_b128 v[192:195], v156
	ds_read_b128 v[196:199], v156 offset:1024
	ds_read_b128 v[200:203], v156 offset:2048
	ds_read_b128 v[204:207], v156 offset:3072
	s_waitcnt lgkmcnt(0)
	s_barrier
	s_setprio 1
	v_mfma_f32_16x16x32_bf16 v[142:145], v[98:101], v[152:155], v[142:145]
	v_mfma_f32_16x16x32_bf16 v[138:141], v[106:109], v[152:155], v[138:141]
	v_mfma_f32_16x16x32_bf16 v[126:129], v[98:101], v[164:167], v[126:129]
	v_mfma_f32_16x16x32_bf16 v[122:125], v[106:109], v[164:167], v[122:125]
	v_mfma_f32_16x16x32_bf16 v[94:97], v[98:101], v[176:179], v[94:97]
	v_mfma_f32_16x16x32_bf16 v[90:93], v[106:109], v[176:179], v[90:93]
	v_mfma_f32_16x16x32_bf16 v[86:89], v[98:101], v[184:187], v[86:89]
	v_mfma_f32_16x16x32_bf16 v[82:85], v[106:109], v[184:187], v[82:85]
	v_mfma_f32_16x16x32_bf16 v[142:145], v[102:105], v[160:163], v[142:145]
	v_mfma_f32_16x16x32_bf16 v[138:141], v[110:113], v[160:163], v[138:141]
	v_mfma_f32_16x16x32_bf16 v[126:129], v[102:105], v[172:175], v[126:129]
	v_mfma_f32_16x16x32_bf16 v[122:125], v[110:113], v[172:175], v[122:125]
	v_mfma_f32_16x16x32_bf16 v[94:97], v[102:105], v[180:183], v[94:97]
	v_mfma_f32_16x16x32_bf16 v[90:93], v[110:113], v[180:183], v[90:93]
	v_mfma_f32_16x16x32_bf16 v[86:89], v[102:105], v[188:191], v[86:89]
	v_mfma_f32_16x16x32_bf16 v[82:85], v[110:113], v[188:191], v[82:85]
	v_mfma_f32_16x16x32_bf16 v[134:137], v[192:195], v[152:155], v[134:137]
	v_mfma_f32_16x16x32_bf16 v[130:133], v[200:203], v[152:155], v[130:133]
	v_mfma_f32_16x16x32_bf16 v[118:121], v[192:195], v[164:167], v[118:121]
	v_mfma_f32_16x16x32_bf16 v[114:117], v[200:203], v[164:167], v[114:117]
	v_mfma_f32_16x16x32_bf16 v[78:81], v[192:195], v[176:179], v[78:81]
	v_mfma_f32_16x16x32_bf16 v[74:77], v[200:203], v[176:179], v[74:77]
	v_mfma_f32_16x16x32_bf16 v[70:73], v[192:195], v[184:187], v[70:73]
	v_mfma_f32_16x16x32_bf16 v[66:69], v[200:203], v[184:187], v[66:69]
	v_mfma_f32_16x16x32_bf16 v[134:137], v[196:199], v[160:163], v[134:137]
	v_mfma_f32_16x16x32_bf16 v[130:133], v[204:207], v[160:163], v[130:133]
	v_mfma_f32_16x16x32_bf16 v[118:121], v[196:199], v[172:175], v[118:121]
	v_mfma_f32_16x16x32_bf16 v[114:117], v[204:207], v[172:175], v[114:117]
	v_mfma_f32_16x16x32_bf16 v[78:81], v[196:199], v[180:183], v[78:81]
	v_mfma_f32_16x16x32_bf16 v[74:77], v[204:207], v[180:183], v[74:77]
	v_mfma_f32_16x16x32_bf16 v[70:73], v[196:199], v[188:191], v[70:73]
	v_mfma_f32_16x16x32_bf16 v[66:69], v[204:207], v[188:191], v[66:69]
	s_setprio 0
	s_barrier
	s_add_i32 s28, s38, s67
	v_lshl_add_u64 v[156:157], s[58:59], 0, v[0:1]
	s_mov_b32 m0, s28
	v_lshl_add_u64 v[210:211], s[58:59], 0, v[146:147]
	global_load_lds_dwordx4 v[156:157], off
	s_add_i32 m0, s28, 0x2000
	s_nop 0
	global_load_lds_dwordx4 v[210:211], off
	s_mov_b32 m0, s9
	v_lshl_add_u64 v[212:213], s[60:61], 0, v[0:1]
	global_load_lds_dwordx4 v[212:213], off
	v_lshl_add_u64 v[214:215], s[60:61], 0, v[146:147]
	s_mov_b32 m0, s68
	s_nop 0
	global_load_lds_dwordx4 v[214:215], off
	ds_read_b128 v[152:155], v171 offset:16384
	ds_read_b128 v[160:163], v171 offset:17408
	ds_read_b128 v[164:167], v171 offset:18432
	ds_read_b128 v[172:175], v171 offset:19456
	ds_read_b128 v[176:179], v171 offset:20480
	ds_read_b128 v[180:183], v171 offset:21504
	ds_read_b128 v[184:187], v171 offset:22528
	ds_read_b128 v[188:191], v171 offset:23552
	s_waitcnt vmcnt(4)
	s_waitcnt lgkmcnt(0)
	s_barrier
	s_setprio 1
	v_mfma_f32_16x16x32_bf16 v[62:65], v[98:101], v[152:155], v[62:65]
	v_mfma_f32_16x16x32_bf16 v[58:61], v[106:109], v[152:155], v[58:61]
	v_mfma_f32_16x16x32_bf16 v[46:49], v[98:101], v[164:167], v[46:49]
	v_mfma_f32_16x16x32_bf16 v[42:45], v[106:109], v[164:167], v[42:45]
	v_mfma_f32_16x16x32_bf16 v[30:33], v[98:101], v[176:179], v[30:33]
	v_mfma_f32_16x16x32_bf16 v[26:29], v[106:109], v[176:179], v[26:29]
	v_mfma_f32_16x16x32_bf16 v[22:25], v[98:101], v[184:187], v[22:25]
	v_mfma_f32_16x16x32_bf16 v[18:21], v[106:109], v[184:187], v[18:21]
	v_mfma_f32_16x16x32_bf16 v[62:65], v[102:105], v[160:163], v[62:65]
	v_mfma_f32_16x16x32_bf16 v[58:61], v[110:113], v[160:163], v[58:61]
	v_mfma_f32_16x16x32_bf16 v[46:49], v[102:105], v[172:175], v[46:49]
	v_mfma_f32_16x16x32_bf16 v[42:45], v[110:113], v[172:175], v[42:45]
	v_mfma_f32_16x16x32_bf16 v[30:33], v[102:105], v[180:183], v[30:33]
	v_mfma_f32_16x16x32_bf16 v[26:29], v[110:113], v[180:183], v[26:29]
	v_mfma_f32_16x16x32_bf16 v[22:25], v[102:105], v[188:191], v[22:25]
	v_mfma_f32_16x16x32_bf16 v[18:21], v[110:113], v[188:191], v[18:21]
	v_mfma_f32_16x16x32_bf16 v[54:57], v[192:195], v[152:155], v[54:57]
	v_mfma_f32_16x16x32_bf16 v[50:53], v[200:203], v[152:155], v[50:53]
	v_mfma_f32_16x16x32_bf16 v[38:41], v[192:195], v[164:167], v[38:41]
	v_mfma_f32_16x16x32_bf16 v[34:37], v[200:203], v[164:167], v[34:37]
	v_mfma_f32_16x16x32_bf16 v[14:17], v[192:195], v[176:179], v[14:17]
	v_mfma_f32_16x16x32_bf16 v[10:13], v[200:203], v[176:179], v[10:13]
	v_mfma_f32_16x16x32_bf16 v[6:9], v[192:195], v[184:187], v[6:9]
	v_mfma_f32_16x16x32_bf16 v[2:5], v[200:203], v[184:187], v[2:5]
	v_mfma_f32_16x16x32_bf16 v[54:57], v[196:199], v[160:163], v[54:57]
	v_mfma_f32_16x16x32_bf16 v[50:53], v[204:207], v[160:163], v[50:53]
	v_mfma_f32_16x16x32_bf16 v[38:41], v[196:199], v[172:175], v[38:41]
	v_mfma_f32_16x16x32_bf16 v[34:37], v[204:207], v[172:175], v[34:37]
	v_mfma_f32_16x16x32_bf16 v[14:17], v[196:199], v[180:183], v[14:17]
	v_mfma_f32_16x16x32_bf16 v[10:13], v[204:207], v[180:183], v[10:13]
	v_mfma_f32_16x16x32_bf16 v[6:9], v[196:199], v[188:191], v[6:9]
	v_mfma_f32_16x16x32_bf16 v[2:5], v[204:207], v[188:191], v[2:5]
	s_setprio 0
	s_barrier
; #define PG8_STAGE(bufoff, gbase, voff) do { _Pragma("unroll") for (int _i = 0; _i < 2; ++_i) \
;         __builtin_amdgcn_global_load_lds((const unsigned*)((const char*)(gbase) + (voff)[_i]), (LAS unsigned*)(lds + (bufoff) + ldsw + _i * 8192), 16, 0, 0); } while (0)
; #define PG8_LDA(dst, b, h) do { _Pragma("unroll") for (int m = 0; m < 4; ++m) _Pragma("unroll") for (int k = 0; k < 2; ++k) dst[m][k] = *(const LAS bf16x8*)(lds + PG8_SA(b, h) + aoff + m * 2048 + k * 1024); } while (0)
; #define PG8_LDB(dst, b, h) do { _Pragma("unroll") for (int n = 0; n < 2; ++n) _Pragma("unroll") for (int k = 0; k < 2; ++k) dst[n][k] = *(const LAS bf16x8*)(lds + PG8_SB(b, h) + boff + n * 2048 + k * 1024); } while (0)
; #define PG8_MMA(ai, bj, At, Bt) do { __builtin_amdgcn_s_setprio(1); _Pragma("unroll") for (int m = 0; m < 4; ++m) _Pragma("unroll") for (int n = 0; n < 2; ++n) _Pragma("unroll") for (int k = 0; k < 2; ++k) \
;         acc[ai][bj][m][n] = __builtin_amdgcn_mfma_f32_16x16x32_bf16(Bt[n][k], At[m][k], acc[ai][bj][m][n], 0, 0, 0); __builtin_amdgcn_s_setprio(0); } while (0)
; #define PG8_WAIT_L(n) asm volatile("s_waitcnt lgkmcnt(" #n ")" ::: "memory")
; #define PG8_BAR __builtin_amdgcn_s_barrier()
; #define PG8_SCHED __builtin_amdgcn_sched_barrier(0)
; template <class Epi, class Sched>
; __device__ __forceinline__ void gemm_phase(LAS unsigned char* lds, const Gemm g, const Sched& S, const Epi& E) {
;     ...
;             PG8_LDB(B0, 1, 0); PG8_SCHED; PG8_LDA(At, 1, 0); PG8_STAGE(PG8_SA(0, 1), a2 + hstep, voffA);
;             PG8_WAIT_L(8); PG8_BAR; PG8_WAIT_L(0); PG8_MMA(0, 0, At, B0); PG8_BAR; PG8_SCHED;
;             PG8_LDB(B1, 1, 1); PG8_STAGE(PG8_SB(1, 0), b3, voffB);
;             PG8_BAR; PG8_WAIT_L(0); PG8_MMA(0, 1, At, B1); PG8_BAR;
;             PG8_LDA(At, 1, 1); PG8_STAGE(PG8_SA(1, 0), a3, voffA);
;             PG8_BAR; PG8_WAIT_L(0); PG8_MMA(1, 0, At, B0); PG8_BAR; PG8_SCHED;
	s_add_u32 s28, s58, 0x80000
	s_addc_u32 s29, s59, 0
	s_add_i32 s38, s39, s67
	v_lshl_add_u64 v[98:99], s[28:29], 0, v[0:1]
	s_mov_b32 m0, s38
	s_nop 0
	global_load_lds_dwordx4 v[98:99], off
	v_lshl_add_u64 v[98:99], s[28:29], 0, v[146:147]
	s_add_i32 m0, s38, 0x2000
	s_nop 0
	global_load_lds_dwordx4 v[98:99], off
	s_add_u32 s28, s60, 0x80000
	s_addc_u32 s29, s61, 0
	s_mov_b32 m0, s69
	v_lshl_add_u64 v[192:193], s[28:29], 0, v[0:1]
	global_load_lds_dwordx4 v[192:193], off
	v_lshl_add_u64 v[192:193], s[28:29], 0, v[146:147]
	s_mov_b32 m0, s70
	s_nop 0
	global_load_lds_dwordx4 v[192:193], off
	s_add_i32 s38, 0, 0x18000
	v_add_u32_e32 v110, s38, v169
	ds_read_b128 v[98:101], v110
	ds_read_b128 v[102:105], v110 offset:1024
	ds_read_b128 v[106:109], v110 offset:2048
	ds_read_b128 v[110:113], v110 offset:3072
	ds_read_b128 v[152:155], v171 offset:32768
	ds_read_b128 v[160:163], v171 offset:33792
	ds_read_b128 v[164:167], v171 offset:34816
	ds_read_b128 v[172:175], v171 offset:35840
	ds_read_b128 v[176:179], v171 offset:36864
	ds_read_b128 v[180:183], v171 offset:37888
	ds_read_b128 v[184:187], v171 offset:38912
	ds_read_b128 v[188:191], v171 offset:39936
	s_add_i32 s39, 0, 0x1c000
	v_add_u32_e32 v204, s39, v169
	ds_read_b128 v[192:195], v204
	ds_read_b128 v[196:199], v204 offset:1024
	ds_read_b128 v[200:203], v204 offset:2048
	ds_read_b128 v[204:207], v204 offset:3072
	s_waitcnt lgkmcnt(0)
	s_barrier
	s_setprio 1
	v_mfma_f32_16x16x32_bf16 v[142:145], v[98:101], v[152:155], v[142:145]
	v_mfma_f32_16x16x32_bf16 v[138:141], v[106:109], v[152:155], v[138:141]
	v_mfma_f32_16x16x32_bf16 v[126:129], v[98:101], v[164:167], v[126:129]
	v_mfma_f32_16x16x32_bf16 v[122:125], v[106:109], v[164:167], v[122:125]
	v_mfma_f32_16x16x32_bf16 v[94:97], v[98:101], v[176:179], v[94:97]
	v_mfma_f32_16x16x32_bf16 v[90:93], v[106:109], v[176:179], v[90:93]
	v_mfma_f32_16x16x32_bf16 v[86:89], v[98:101], v[184:187], v[86:89]
	v_mfma_f32_16x16x32_bf16 v[82:85], v[106:109], v[184:187], v[82:85]
	v_mfma_f32_16x16x32_bf16 v[142:145], v[102:105], v[160:163], v[142:145]
	v_mfma_f32_16x16x32_bf16 v[138:141], v[110:113], v[160:163], v[138:141]
	v_mfma_f32_16x16x32_bf16 v[126:129], v[102:105], v[172:175], v[126:129]
	v_mfma_f32_16x16x32_bf16 v[122:125], v[110:113], v[172:175], v[122:125]
	v_mfma_f32_16x16x32_bf16 v[94:97], v[102:105], v[180:183], v[94:97]
	v_mfma_f32_16x16x32_bf16 v[90:93], v[110:113], v[180:183], v[90:93]
	v_mfma_f32_16x16x32_bf16 v[86:89], v[102:105], v[188:191], v[86:89]
	v_mfma_f32_16x16x32_bf16 v[82:85], v[110:113], v[188:191], v[82:85]
	v_mfma_f32_16x16x32_bf16 v[134:137], v[192:195], v[152:155], v[134:137]
	v_mfma_f32_16x16x32_bf16 v[130:133], v[200:203], v[152:155], v[130:133]
	v_mfma_f32_16x16x32_bf16 v[118:121], v[192:195], v[164:167], v[118:121]
	v_mfma_f32_16x16x32_bf16 v[114:117], v[200:203], v[164:167], v[114:117]
	v_mfma_f32_16x16x32_bf16 v[78:81], v[192:195], v[176:179], v[78:81]
	v_mfma_f32_16x16x32_bf16 v[74:77], v[200:203], v[176:179], v[74:77]
	v_mfma_f32_16x16x32_bf16 v[70:73], v[192:195], v[184:187], v[70:73]
	v_mfma_f32_16x16x32_bf16 v[66:69], v[200:203], v[184:187], v[66:69]
	v_mfma_f32_16x16x32_bf16 v[134:137], v[196:199], v[160:163], v[134:137]
	v_mfma_f32_16x16x32_bf16 v[130:133], v[204:207], v[160:163], v[130:133]
	v_mfma_f32_16x16x32_bf16 v[118:121], v[196:199], v[172:175], v[118:121]
	v_mfma_f32_16x16x32_bf16 v[114:117], v[204:207], v[172:175], v[114:117]
	v_mfma_f32_16x16x32_bf16 v[78:81], v[196:199], v[180:183], v[78:81]
	v_mfma_f32_16x16x32_bf16 v[74:77], v[204:207], v[180:183], v[74:77]
	v_mfma_f32_16x16x32_bf16 v[70:73], v[196:199], v[188:191], v[70:73]
	v_mfma_f32_16x16x32_bf16 v[66:69], v[204:207], v[188:191], v[66:69]
	s_setprio 0
	s_barrier
; #define PG8_STAGE(bufoff, gbase, voff) do { _Pragma("unroll") for (int _i = 0; _i < 2; ++_i) \
;         __builtin_amdgcn_global_load_lds((const unsigned*)((const char*)(gbase) + (voff)[_i]), (LAS unsigned*)(lds + (bufoff) + ldsw + _i * 8192), 16, 0, 0); } while (0)
; #define PG8_LDA(dst, b, h) do { _Pragma("unroll") for (int m = 0; m < 4; ++m) _Pragma("unroll") for (int k = 0; k < 2; ++k) dst[m][k] = *(const LAS bf16x8*)(lds + PG8_SA(b, h) + aoff + m * 2048 + k * 1024); } while (0)
; #define PG8_LDB(dst, b, h) do { _Pragma("unroll") for (int n = 0; n < 2; ++n) _Pragma("unroll") for (int k = 0; k < 2; ++k) dst[n][k] = *(const LAS bf16x8*)(lds + PG8_SB(b, h) + boff + n * 2048 + k * 1024); } while (0)
; #define PG8_MMA(ai, bj, At, Bt) do { __builtin_amdgcn_s_setprio(1); _Pragma("unroll") for (int m = 0; m < 4; ++m) _Pragma("unroll") for (int n = 0; n < 2; ++n) _Pragma("unroll") for (int k = 0; k < 2; ++k) \
;         acc[ai][bj][m][n] = __builtin_amdgcn_mfma_f32_16x16x32_bf16(Bt[n][k], At[m][k], acc[ai][bj][m][n], 0, 0, 0); __builtin_amdgcn_s_setprio(0); } while (0)
; #define PG8_WAIT_V(n) asm volatile("s_waitcnt vmcnt(" #n ")" ::: "memory")
; #define PG8_WAIT_L(n) asm volatile("s_waitcnt lgkmcnt(" #n ")" ::: "memory")
; #define PG8_BAR __builtin_amdgcn_s_barrier()
; #define PG8_SCHED __builtin_amdgcn_sched_barrier(0)
;     __device__ __forceinline__ void operator()(const f32x4 (&acc)[2][2][4][2], const Unit& u, int wr, int wc, int fr, int fq) const {
;         const bool lat = u.pm < 64; const int r = lat ? (u.pm >> 3) : 8;
;         const float* s = lat ? src_lat : src_ctx; float* d = lat ? dst_lat : dst_ctx;
;         const int row0 = (lat ? u.pm : u.pm - 64) * BM + wr * 64 + fr, col0 = u.pn * BM + wc * 32 + 4 * fq;
; template <class Epi, class Sched>
; __device__ __forceinline__ void gemm_phase(LAS unsigned char* lds, const Gemm g, const Sched& S, const Epi& E) {
;     ...
;             PG8_LDB(B1, 1, 1); PG8_STAGE(PG8_SB(1, 0), b3, voffB);
;             PG8_BAR; PG8_WAIT_L(0); PG8_MMA(0, 1, At, B1); PG8_BAR;
;             PG8_LDA(At, 1, 1); PG8_STAGE(PG8_SA(1, 0), a3, voffA);
;             PG8_BAR; PG8_WAIT_L(0); PG8_MMA(1, 0, At, B0); PG8_BAR; PG8_SCHED;
;             PG8_STAGE(PG8_SB(1, 1), b3 + hstep, voffB);
;             PG8_WAIT_V(6); PG8_BAR; PG8_MMA(1, 1, At, B1); PG8_BAR;
;         }
	s_add_i32 s28, s38, s67
	v_lshl_add_u64 v[156:157], v[156:157], 0, s[36:37]
	s_mov_b32 m0, s28
	s_nop 0
	global_load_lds_dwordx4 v[156:157], off
	v_lshl_add_u64 v[156:157], v[210:211], 0, s[36:37]
	s_add_i32 m0, s28, 0x2000
	s_nop 0
	global_load_lds_dwordx4 v[156:157], off
	s_mov_b32 m0, s72
	v_lshl_add_u64 v[156:157], v[212:213], 0, s[36:37]
	global_load_lds_dwordx4 v[156:157], off
	v_lshl_add_u64 v[156:157], v[214:215], 0, s[36:37]
	s_mov_b32 m0, s73
	s_nop 0
	global_load_lds_dwordx4 v[156:157], off
	s_add_u32 s28, s58, 0x80080
	s_addc_u32 s29, s59, 0
	s_add_i32 s38, s39, s67
	v_lshl_add_u64 v[156:157], s[28:29], 0, v[0:1]
	s_mov_b32 m0, s38
	s_nop 0
	global_load_lds_dwordx4 v[156:157], off
	v_lshl_add_u64 v[156:157], s[28:29], 0, v[146:147]
	s_add_i32 m0, s38, 0x2000
	s_nop 0
	global_load_lds_dwordx4 v[156:157], off
	ds_read_b128 v[152:155], v171 offset:49152
	ds_read_b128 v[160:163], v171 offset:50176
	ds_read_b128 v[164:167], v171 offset:51200
	ds_read_b128 v[172:175], v171 offset:52224
	ds_read_b128 v[176:179], v171 offset:53248
	ds_read_b128 v[180:183], v171 offset:54272
	ds_read_b128 v[184:187], v171 offset:55296
	ds_read_b128 v[188:191], v171 offset:56320
	s_waitcnt vmcnt(6)
	s_waitcnt lgkmcnt(0)
	s_barrier
	s_setprio 1
	v_mfma_f32_16x16x32_bf16 v[62:65], v[98:101], v[152:155], v[62:65]
	v_mfma_f32_16x16x32_bf16 v[58:61], v[106:109], v[152:155], v[58:61]
	v_mfma_f32_16x16x32_bf16 v[46:49], v[98:101], v[164:167], v[46:49]
	v_mfma_f32_16x16x32_bf16 v[42:45], v[106:109], v[164:167], v[42:45]
	v_mfma_f32_16x16x32_bf16 v[30:33], v[98:101], v[176:179], v[30:33]
	v_mfma_f32_16x16x32_bf16 v[26:29], v[106:109], v[176:179], v[26:29]
	v_mfma_f32_16x16x32_bf16 v[22:25], v[98:101], v[184:187], v[22:25]
	v_mfma_f32_16x16x32_bf16 v[18:21], v[106:109], v[184:187], v[18:21]
	v_mfma_f32_16x16x32_bf16 v[62:65], v[102:105], v[160:163], v[62:65]
	v_mfma_f32_16x16x32_bf16 v[58:61], v[110:113], v[160:163], v[58:61]
	v_mfma_f32_16x16x32_bf16 v[46:49], v[102:105], v[172:175], v[46:49]
	v_mfma_f32_16x16x32_bf16 v[42:45], v[110:113], v[172:175], v[42:45]
	v_mfma_f32_16x16x32_bf16 v[30:33], v[102:105], v[180:183], v[30:33]
	v_mfma_f32_16x16x32_bf16 v[26:29], v[110:113], v[180:183], v[26:29]
	v_mfma_f32_16x16x32_bf16 v[22:25], v[102:105], v[188:191], v[22:25]
	v_mfma_f32_16x16x32_bf16 v[18:21], v[110:113], v[188:191], v[18:21]
	v_mfma_f32_16x16x32_bf16 v[54:57], v[192:195], v[152:155], v[54:57]
	v_mfma_f32_16x16x32_bf16 v[50:53], v[200:203], v[152:155], v[50:53]
	v_mfma_f32_16x16x32_bf16 v[38:41], v[192:195], v[164:167], v[38:41]
	v_mfma_f32_16x16x32_bf16 v[34:37], v[200:203], v[164:167], v[34:37]
	v_mfma_f32_16x16x32_bf16 v[14:17], v[192:195], v[176:179], v[14:17]
	v_mfma_f32_16x16x32_bf16 v[10:13], v[200:203], v[176:179], v[10:13]
	v_mfma_f32_16x16x32_bf16 v[6:9], v[192:195], v[184:187], v[6:9]
	v_mfma_f32_16x16x32_bf16 v[2:5], v[200:203], v[184:187], v[2:5]
	v_mfma_f32_16x16x32_bf16 v[54:57], v[196:199], v[160:163], v[54:57]
	v_mfma_f32_16x16x32_bf16 v[50:53], v[204:207], v[160:163], v[50:53]
	v_mfma_f32_16x16x32_bf16 v[38:41], v[196:199], v[172:175], v[38:41]
	v_mfma_f32_16x16x32_bf16 v[34:37], v[204:207], v[172:175], v[34:37]
	v_mfma_f32_16x16x32_bf16 v[14:17], v[196:199], v[180:183], v[14:17]
	v_mfma_f32_16x16x32_bf16 v[10:13], v[204:207], v[180:183], v[10:13]
	v_mfma_f32_16x16x32_bf16 v[6:9], v[196:199], v[188:191], v[6:9]
	v_mfma_f32_16x16x32_bf16 v[2:5], v[204:207], v[188:191], v[2:5]
	s_setprio 0
	s_add_i32 s81, s81, 2
	s_add_u32 s79, s79, 0x100
	s_addc_u32 s80, s80, 0
	s_cmp_gt_u32 s81, 29
	s_mov_b64 s[28:29], s[56:57]
	s_barrier
	s_cbranch_scc0 .LBB0_99
	s_cmp_lt_i32 s8, 64
	s_cselect_b64 s[58:59], -1, 0
	s_cmp_gt_i32 s8, 63
	s_cbranch_scc0 .LBB0_90
	s_mov_b64 s[60:61], 0x18000
	s_mov_b64 s[28:29], s[46:47]
	s_mov_b64 s[56:57], s[24:25]
	s_branch .LBB0_91

; #define PG8_STAGE(bufoff, gbase, voff) do { _Pragma("unroll") for (int _i = 0; _i < 2; ++_i) \
;         __builtin_amdgcn_global_load_lds((const unsigned*)((const char*)(gbase) + (voff)[_i]), (LAS unsigned*)(lds + (bufoff) + ldsw + _i * 8192), 16, 0, 0); } while (0)
; #define PG8_LDA(dst, b, h) do { _Pragma("unroll") for (int m = 0; m < 4; ++m) _Pragma("unroll") for (int k = 0; k < 2; ++k) dst[m][k] = *(const LAS bf16x8*)(lds + PG8_SA(b, h) + aoff + m * 2048 + k * 1024); } while (0)
; #define PG8_LDB(dst, b, h) do { _Pragma("unroll") for (int n = 0; n < 2; ++n) _Pragma("unroll") for (int k = 0; k < 2; ++k) dst[n][k] = *(const LAS bf16x8*)(lds + PG8_SB(b, h) + boff + n * 2048 + k * 1024); } while (0)
; #define PG8_MMA(ai, bj, At, Bt) do { __builtin_amdgcn_s_setprio(1); _Pragma("unroll") for (int m = 0; m < 4; ++m) _Pragma("unroll") for (int n = 0; n < 2; ++n) _Pragma("unroll") for (int k = 0; k < 2; ++k) \
;         acc[ai][bj][m][n] = __builtin_amdgcn_mfma_f32_16x16x32_bf16(Bt[n][k], At[m][k], acc[ai][bj][m][n], 0, 0, 0); __builtin_amdgcn_s_setprio(0); } while (0)
; #define PG8_WAIT_V(n) asm volatile("s_waitcnt vmcnt(" #n ")" ::: "memory")
; #define PG8_WAIT_L(n) asm volatile("s_waitcnt lgkmcnt(" #n ")" ::: "memory")
; template <class Epi, class Sched>
; __device__ __forceinline__ void gemm_phase(LAS unsigned char* lds, const Gemm g, const Sched& S, const Epi& E) {
;     ...
;         for (int t = 0; t < nt; t += 2) {
;             const bool last = (t == nt - 2);
;             const char* a1 = cA + (size_t)(t + 1) * kstep;
;             const char* a2 = last ? nA : cA + (size_t)(t + 2) * kstep; const char* b2 = last ? nB : cB + (size_t)(t + 2) * kstep;
;             const char* a3 = a2 + kstep; const char* b3 = b2 + kstep;
;             PG8_LDB(B0, 0, 0); PG8_SCHED; PG8_LDA(At, 0, 0); PG8_STAGE(PG8_SA(1, 1), a1 + hstep, voffA);
;             PG8_WAIT_L(8); PG8_BAR; PG8_WAIT_L(0); PG8_MMA(0, 0, At, B0); PG8_BAR; PG8_SCHED;
;             PG8_LDB(B1, 0, 1); PG8_STAGE(PG8_SB(0, 0), b2, voffB);
;             PG8_BAR; PG8_WAIT_L(0); PG8_MMA(0, 1, At, B1); PG8_BAR;
;             PG8_LDA(At, 0, 1); PG8_STAGE(PG8_SA(0, 0), a2, voffA);
;             PG8_BAR; PG8_WAIT_L(0); PG8_MMA(1, 0, At, B0); PG8_BAR; PG8_SCHED;
;             PG8_STAGE(PG8_SB(0, 1), b2 + hstep, voffB);
;             PG8_WAIT_V(6); PG8_BAR; PG8_MMA(1, 1, At, B1); PG8_BAR;
.LBB0_113:
	s_add_u32 s54, s52, 0x100
	s_addc_u32 s55, s53, 0
	s_cmp_eq_u32 s73, 4
	s_cselect_b32 s59, s11, s55
	s_cselect_b32 s58, s29, s54
	s_cselect_b32 s57, s41, s72
	s_cselect_b32 s56, s45, s71
	v_lshl_add_u64 v[156:157], s[52:53], 0, v[134:135]
	s_add_i32 m0, s25, 0xc000
	s_nop 0
	global_load_lds_dwordx4 v[156:157], off
	v_lshl_add_u64 v[156:157], s[52:53], 0, v[132:133]
	s_add_i32 m0, s25, 0xe000
	s_nop 0
	global_load_lds_dwordx4 v[156:157], off
	s_add_i32 s38, 0, 0x10000
	v_add_u32_e32 v152, s38, v137
	ds_read_b128 v[140:143], v152
	ds_read_b128 v[144:147], v152 offset:1024
	ds_read_b128 v[148:151], v152 offset:2048
	ds_read_b128 v[152:155], v152 offset:3072
	ds_read_b128 v[160:163], v139
	ds_read_b128 v[164:167], v139 offset:1024
	ds_read_b128 v[168:171], v139 offset:2048
	ds_read_b128 v[172:175], v139 offset:3072
	ds_read_b128 v[176:179], v139 offset:4096
	ds_read_b128 v[180:183], v139 offset:5120
	ds_read_b128 v[184:187], v139 offset:6144
	ds_read_b128 v[188:191], v139 offset:7168
	s_add_i32 s52, 0, 0x14000
	v_add_u32_e32 v156, s52, v137
	ds_read_b128 v[192:195], v156
	ds_read_b128 v[196:199], v156 offset:1024
	ds_read_b128 v[200:203], v156 offset:2048
	ds_read_b128 v[204:207], v156 offset:3072
	s_waitcnt lgkmcnt(0)
	s_barrier
	s_setprio 1
	v_mfma_f32_16x16x32_bf16 v[126:129], v[140:143], v[160:163], v[126:129]
	v_mfma_f32_16x16x32_bf16 v[122:125], v[148:151], v[160:163], v[122:125]
	v_mfma_f32_16x16x32_bf16 v[118:121], v[140:143], v[168:171], v[118:121]
	v_mfma_f32_16x16x32_bf16 v[114:117], v[148:151], v[168:171], v[114:117]
	v_mfma_f32_16x16x32_bf16 v[106:109], v[140:143], v[176:179], v[106:109]
	v_mfma_f32_16x16x32_bf16 v[98:101], v[148:151], v[176:179], v[98:101]
	v_mfma_f32_16x16x32_bf16 v[90:93], v[140:143], v[184:187], v[90:93]
	v_mfma_f32_16x16x32_bf16 v[82:85], v[148:151], v[184:187], v[82:85]
	v_mfma_f32_16x16x32_bf16 v[126:129], v[144:147], v[164:167], v[126:129]
	v_mfma_f32_16x16x32_bf16 v[122:125], v[152:155], v[164:167], v[122:125]
	v_mfma_f32_16x16x32_bf16 v[118:121], v[144:147], v[172:175], v[118:121]
	v_mfma_f32_16x16x32_bf16 v[114:117], v[152:155], v[172:175], v[114:117]
	v_mfma_f32_16x16x32_bf16 v[106:109], v[144:147], v[180:183], v[106:109]
	v_mfma_f32_16x16x32_bf16 v[98:101], v[152:155], v[180:183], v[98:101]
	v_mfma_f32_16x16x32_bf16 v[90:93], v[144:147], v[188:191], v[90:93]
	v_mfma_f32_16x16x32_bf16 v[82:85], v[152:155], v[188:191], v[82:85]
	v_mfma_f32_16x16x32_bf16 v[110:113], v[192:195], v[160:163], v[110:113]
	v_mfma_f32_16x16x32_bf16 v[102:105], v[200:203], v[160:163], v[102:105]
	v_mfma_f32_16x16x32_bf16 v[94:97], v[192:195], v[168:171], v[94:97]
	v_mfma_f32_16x16x32_bf16 v[86:89], v[200:203], v[168:171], v[86:89]
	v_mfma_f32_16x16x32_bf16 v[78:81], v[192:195], v[176:179], v[78:81]
	v_mfma_f32_16x16x32_bf16 v[74:77], v[200:203], v[176:179], v[74:77]
	v_mfma_f32_16x16x32_bf16 v[70:73], v[192:195], v[184:187], v[70:73]
	v_mfma_f32_16x16x32_bf16 v[66:69], v[200:203], v[184:187], v[66:69]
	v_mfma_f32_16x16x32_bf16 v[110:113], v[196:199], v[164:167], v[110:113]
	v_mfma_f32_16x16x32_bf16 v[102:105], v[204:207], v[164:167], v[102:105]
	v_mfma_f32_16x16x32_bf16 v[94:97], v[196:199], v[172:175], v[94:97]
	v_mfma_f32_16x16x32_bf16 v[86:89], v[204:207], v[172:175], v[86:89]
	v_mfma_f32_16x16x32_bf16 v[78:81], v[196:199], v[180:183], v[78:81]
	v_mfma_f32_16x16x32_bf16 v[74:77], v[204:207], v[180:183], v[74:77]
	v_mfma_f32_16x16x32_bf16 v[70:73], v[196:199], v[188:191], v[70:73]
	v_mfma_f32_16x16x32_bf16 v[66:69], v[204:207], v[188:191], v[66:69]
	s_setprio 0
	s_barrier
	s_add_i32 s38, s38, s65
	v_lshl_add_u64 v[156:157], s[56:57], 0, v[0:1]
	s_mov_b32 m0, s38
	v_lshl_add_u64 v[210:211], s[56:57], 0, v[130:131]
	global_load_lds_dwordx4 v[156:157], off
	s_add_i32 m0, s38, 0x2000
	s_nop 0
	global_load_lds_dwordx4 v[210:211], off
	s_mov_b32 m0, s25
	v_lshl_add_u64 v[212:213], s[58:59], 0, v[0:1]
	global_load_lds_dwordx4 v[212:213], off
	v_lshl_add_u64 v[214:215], s[58:59], 0, v[130:131]
	s_mov_b32 m0, s27
	s_nop 0
	global_load_lds_dwordx4 v[214:215], off
	ds_read_b128 v[160:163], v139 offset:16384
	ds_read_b128 v[164:167], v139 offset:17408
	ds_read_b128 v[168:171], v139 offset:18432
	ds_read_b128 v[172:175], v139 offset:19456
	ds_read_b128 v[176:179], v139 offset:20480
	ds_read_b128 v[180:183], v139 offset:21504
	ds_read_b128 v[184:187], v139 offset:22528
	ds_read_b128 v[188:191], v139 offset:23552
	s_waitcnt vmcnt(4)
	s_waitcnt lgkmcnt(0)
	s_barrier
	s_setprio 1
	v_mfma_f32_16x16x32_bf16 v[62:65], v[140:143], v[160:163], v[62:65]
	v_mfma_f32_16x16x32_bf16 v[58:61], v[148:151], v[160:163], v[58:61]
	v_mfma_f32_16x16x32_bf16 v[54:57], v[140:143], v[168:171], v[54:57]
	v_mfma_f32_16x16x32_bf16 v[50:53], v[148:151], v[168:171], v[50:53]
	v_mfma_f32_16x16x32_bf16 v[38:41], v[140:143], v[176:179], v[38:41]
	v_mfma_f32_16x16x32_bf16 v[34:37], v[148:151], v[176:179], v[34:37]
	v_mfma_f32_16x16x32_bf16 v[22:25], v[140:143], v[184:187], v[22:25]
	v_mfma_f32_16x16x32_bf16 v[18:21], v[148:151], v[184:187], v[18:21]
	v_mfma_f32_16x16x32_bf16 v[62:65], v[144:147], v[164:167], v[62:65]
	v_mfma_f32_16x16x32_bf16 v[58:61], v[152:155], v[164:167], v[58:61]
	v_mfma_f32_16x16x32_bf16 v[54:57], v[144:147], v[172:175], v[54:57]
	v_mfma_f32_16x16x32_bf16 v[50:53], v[152:155], v[172:175], v[50:53]
	v_mfma_f32_16x16x32_bf16 v[38:41], v[144:147], v[180:183], v[38:41]
	v_mfma_f32_16x16x32_bf16 v[34:37], v[152:155], v[180:183], v[34:37]
	v_mfma_f32_16x16x32_bf16 v[22:25], v[144:147], v[188:191], v[22:25]
	v_mfma_f32_16x16x32_bf16 v[18:21], v[152:155], v[188:191], v[18:21]
	v_mfma_f32_16x16x32_bf16 v[46:49], v[192:195], v[160:163], v[46:49]
	v_mfma_f32_16x16x32_bf16 v[42:45], v[200:203], v[160:163], v[42:45]
	v_mfma_f32_16x16x32_bf16 v[30:33], v[192:195], v[168:171], v[30:33]
	v_mfma_f32_16x16x32_bf16 v[26:29], v[200:203], v[168:171], v[26:29]
	v_mfma_f32_16x16x32_bf16 v[14:17], v[192:195], v[176:179], v[14:17]
	v_mfma_f32_16x16x32_bf16 v[10:13], v[200:203], v[176:179], v[10:13]
	v_mfma_f32_16x16x32_bf16 v[6:9], v[192:195], v[184:187], v[6:9]
	v_mfma_f32_16x16x32_bf16 v[2:5], v[200:203], v[184:187], v[2:5]
	v_mfma_f32_16x16x32_bf16 v[46:49], v[196:199], v[164:167], v[46:49]
	v_mfma_f32_16x16x32_bf16 v[42:45], v[204:207], v[164:167], v[42:45]
	v_mfma_f32_16x16x32_bf16 v[30:33], v[196:199], v[172:175], v[30:33]
	v_mfma_f32_16x16x32_bf16 v[26:29], v[204:207], v[172:175], v[26:29]
	v_mfma_f32_16x16x32_bf16 v[14:17], v[196:199], v[180:183], v[14:17]
	v_mfma_f32_16x16x32_bf16 v[10:13], v[204:207], v[180:183], v[10:13]
	v_mfma_f32_16x16x32_bf16 v[6:9], v[196:199], v[188:191], v[6:9]
	v_mfma_f32_16x16x32_bf16 v[2:5], v[204:207], v[188:191], v[2:5]
	s_setprio 0
	s_barrier
; #define PG8_STAGE(bufoff, gbase, voff) do { _Pragma("unroll") for (int _i = 0; _i < 2; ++_i) \
;         __builtin_amdgcn_global_load_lds((const unsigned*)((const char*)(gbase) + (voff)[_i]), (LAS unsigned*)(lds + (bufoff) + ldsw + _i * 8192), 16, 0, 0); } while (0)
; #define PG8_LDA(dst, b, h) do { _Pragma("unroll") for (int m = 0; m < 4; ++m) _Pragma("unroll") for (int k = 0; k < 2; ++k) dst[m][k] = *(const LAS bf16x8*)(lds + PG8_SA(b, h) + aoff + m * 2048 + k * 1024); } while (0)
; #define PG8_LDB(dst, b, h) do { _Pragma("unroll") for (int n = 0; n < 2; ++n) _Pragma("unroll") for (int k = 0; k < 2; ++k) dst[n][k] = *(const LAS bf16x8*)(lds + PG8_SB(b, h) + boff + n * 2048 + k * 1024); } while (0)
; #define PG8_MMA(ai, bj, At, Bt) do { __builtin_amdgcn_s_setprio(1); _Pragma("unroll") for (int m = 0; m < 4; ++m) _Pragma("unroll") for (int n = 0; n < 2; ++n) _Pragma("unroll") for (int k = 0; k < 2; ++k) \
;         acc[ai][bj][m][n] = __builtin_amdgcn_mfma_f32_16x16x32_bf16(Bt[n][k], At[m][k], acc[ai][bj][m][n], 0, 0, 0); __builtin_amdgcn_s_setprio(0); } while (0)
; #define PG8_WAIT_V(n) asm volatile("s_waitcnt vmcnt(" #n ")" ::: "memory")
; #define PG8_WAIT_L(n) asm volatile("s_waitcnt lgkmcnt(" #n ")" ::: "memory")
; #define PG8_BAR __builtin_amdgcn_s_barrier()
; #define PG8_SCHED __builtin_amdgcn_sched_barrier(0)
; template <class Epi, class Sched>
; __device__ __forceinline__ void gemm_phase(LAS unsigned char* lds, const Gemm g, const Sched& S, const Epi& E) {
;     ...
;             PG8_LDB(B0, 1, 0); PG8_SCHED; PG8_LDA(At, 1, 0); PG8_STAGE(PG8_SA(0, 1), a2 + hstep, voffA);
;             PG8_WAIT_L(8); PG8_BAR; PG8_WAIT_L(0); PG8_MMA(0, 0, At, B0); PG8_BAR; PG8_SCHED;
;             PG8_LDB(B1, 1, 1); PG8_STAGE(PG8_SB(1, 0), b3, voffB);
;             PG8_BAR; PG8_WAIT_L(0); PG8_MMA(0, 1, At, B1); PG8_BAR;
;             PG8_LDA(At, 1, 1); PG8_STAGE(PG8_SA(1, 0), a3, voffA);
;             PG8_BAR; PG8_WAIT_L(0); PG8_MMA(1, 0, At, B0); PG8_BAR; PG8_SCHED;
;             PG8_STAGE(PG8_SB(1, 1), b3 + hstep, voffB);
;             PG8_WAIT_V(6); PG8_BAR; PG8_MMA(1, 1, At, B1); PG8_BAR;
	s_add_u32 s38, s56, 0x80000
	s_addc_u32 s39, s57, 0
	s_add_i32 s52, s52, s65
	v_lshl_add_u64 v[140:141], s[38:39], 0, v[0:1]
	s_mov_b32 m0, s52
	s_nop 0
	global_load_lds_dwordx4 v[140:141], off
	v_lshl_add_u64 v[140:141], s[38:39], 0, v[130:131]
	s_add_i32 m0, s52, 0x2000
	s_nop 0
	global_load_lds_dwordx4 v[140:141], off
	s_add_u32 s38, s58, 0x80000
	s_addc_u32 s39, s59, 0
	s_mov_b32 m0, s66
	v_lshl_add_u64 v[192:193], s[38:39], 0, v[0:1]
	global_load_lds_dwordx4 v[192:193], off
	v_lshl_add_u64 v[192:193], s[38:39], 0, v[130:131]
	s_mov_b32 m0, s67
	s_nop 0
	global_load_lds_dwordx4 v[192:193], off
	s_add_i32 s52, 0, 0x18000
	v_add_u32_e32 v152, s52, v137
	ds_read_b128 v[140:143], v152
	ds_read_b128 v[144:147], v152 offset:1024
	ds_read_b128 v[148:151], v152 offset:2048
	ds_read_b128 v[152:155], v152 offset:3072
	ds_read_b128 v[160:163], v139 offset:32768
	ds_read_b128 v[164:167], v139 offset:33792
	ds_read_b128 v[168:171], v139 offset:34816
	ds_read_b128 v[172:175], v139 offset:35840
	ds_read_b128 v[176:179], v139 offset:36864
	ds_read_b128 v[180:183], v139 offset:37888
	ds_read_b128 v[184:187], v139 offset:38912
	ds_read_b128 v[188:191], v139 offset:39936
	s_add_i32 s53, 0, 0x1c000
	v_add_u32_e32 v204, s53, v137
	ds_read_b128 v[192:195], v204
	ds_read_b128 v[196:199], v204 offset:1024
	ds_read_b128 v[200:203], v204 offset:2048
	ds_read_b128 v[204:207], v204 offset:3072
	s_waitcnt lgkmcnt(0)
	s_barrier
	s_setprio 1
	v_mfma_f32_16x16x32_bf16 v[126:129], v[140:143], v[160:163], v[126:129]
	v_mfma_f32_16x16x32_bf16 v[122:125], v[148:151], v[160:163], v[122:125]
	v_mfma_f32_16x16x32_bf16 v[118:121], v[140:143], v[168:171], v[118:121]
	v_mfma_f32_16x16x32_bf16 v[114:117], v[148:151], v[168:171], v[114:117]
	v_mfma_f32_16x16x32_bf16 v[106:109], v[140:143], v[176:179], v[106:109]
	v_mfma_f32_16x16x32_bf16 v[98:101], v[148:151], v[176:179], v[98:101]
	v_mfma_f32_16x16x32_bf16 v[90:93], v[140:143], v[184:187], v[90:93]
	v_mfma_f32_16x16x32_bf16 v[82:85], v[148:151], v[184:187], v[82:85]
	v_mfma_f32_16x16x32_bf16 v[126:129], v[144:147], v[164:167], v[126:129]
	v_mfma_f32_16x16x32_bf16 v[122:125], v[152:155], v[164:167], v[122:125]
	v_mfma_f32_16x16x32_bf16 v[118:121], v[144:147], v[172:175], v[118:121]
	v_mfma_f32_16x16x32_bf16 v[114:117], v[152:155], v[172:175], v[114:117]
	v_mfma_f32_16x16x32_bf16 v[106:109], v[144:147], v[180:183], v[106:109]
	v_mfma_f32_16x16x32_bf16 v[98:101], v[152:155], v[180:183], v[98:101]
	v_mfma_f32_16x16x32_bf16 v[90:93], v[144:147], v[188:191], v[90:93]
	v_mfma_f32_16x16x32_bf16 v[82:85], v[152:155], v[188:191], v[82:85]
	v_mfma_f32_16x16x32_bf16 v[110:113], v[192:195], v[160:163], v[110:113]
	v_mfma_f32_16x16x32_bf16 v[102:105], v[200:203], v[160:163], v[102:105]
	v_mfma_f32_16x16x32_bf16 v[94:97], v[192:195], v[168:171], v[94:97]
	v_mfma_f32_16x16x32_bf16 v[86:89], v[200:203], v[168:171], v[86:89]
	v_mfma_f32_16x16x32_bf16 v[78:81], v[192:195], v[176:179], v[78:81]
	v_mfma_f32_16x16x32_bf16 v[74:77], v[200:203], v[176:179], v[74:77]
	v_mfma_f32_16x16x32_bf16 v[70:73], v[192:195], v[184:187], v[70:73]
	v_mfma_f32_16x16x32_bf16 v[66:69], v[200:203], v[184:187], v[66:69]
	v_mfma_f32_16x16x32_bf16 v[110:113], v[196:199], v[164:167], v[110:113]
	v_mfma_f32_16x16x32_bf16 v[102:105], v[204:207], v[164:167], v[102:105]
	v_mfma_f32_16x16x32_bf16 v[94:97], v[196:199], v[172:175], v[94:97]
	v_mfma_f32_16x16x32_bf16 v[86:89], v[204:207], v[172:175], v[86:89]
	v_mfma_f32_16x16x32_bf16 v[78:81], v[196:199], v[180:183], v[78:81]
	v_mfma_f32_16x16x32_bf16 v[74:77], v[204:207], v[180:183], v[74:77]
	v_mfma_f32_16x16x32_bf16 v[70:73], v[196:199], v[188:191], v[70:73]
	v_mfma_f32_16x16x32_bf16 v[66:69], v[204:207], v[188:191], v[66:69]
	s_setprio 0
	s_barrier
	s_add_i32 s38, s52, s65
	v_lshl_add_u64 v[156:157], v[156:157], 0, s[36:37]
	s_mov_b32 m0, s38
	s_nop 0
	global_load_lds_dwordx4 v[156:157], off
	v_lshl_add_u64 v[156:157], v[210:211], 0, s[36:37]
	s_add_i32 m0, s38, 0x2000
	s_nop 0
	global_load_lds_dwordx4 v[156:157], off
	s_mov_b32 m0, s68
	v_lshl_add_u64 v[156:157], v[212:213], 0, s[36:37]
	global_load_lds_dwordx4 v[156:157], off
	v_lshl_add_u64 v[156:157], v[214:215], 0, s[36:37]
	s_mov_b32 m0, s69
	s_nop 0
	global_load_lds_dwordx4 v[156:157], off
	s_add_u32 s38, s56, 0x80080
	s_addc_u32 s39, s57, 0
	s_add_i32 s52, s53, s65
	v_lshl_add_u64 v[156:157], s[38:39], 0, v[0:1]
	s_mov_b32 m0, s52
	s_nop 0
	global_load_lds_dwordx4 v[156:157], off
	v_lshl_add_u64 v[156:157], s[38:39], 0, v[130:131]
	s_add_i32 m0, s52, 0x2000
	s_nop 0
	global_load_lds_dwordx4 v[156:157], off
	ds_read_b128 v[160:163], v139 offset:49152
	ds_read_b128 v[164:167], v139 offset:50176
	ds_read_b128 v[168:171], v139 offset:51200
	ds_read_b128 v[172:175], v139 offset:52224
	ds_read_b128 v[176:179], v139 offset:53248
	ds_read_b128 v[180:183], v139 offset:54272
	ds_read_b128 v[184:187], v139 offset:55296
	ds_read_b128 v[188:191], v139 offset:56320
	s_waitcnt vmcnt(6)
	s_waitcnt lgkmcnt(0)
	s_barrier
; #define PG8_MMA(ai, bj, At, Bt) do { __builtin_amdgcn_s_setprio(1); _Pragma("unroll") for (int m = 0; m < 4; ++m) _Pragma("unroll") for (int n = 0; n < 2; ++n) _Pragma("unroll") for (int k = 0; k < 2; ++k) \
;         acc[ai][bj][m][n] = __builtin_amdgcn_mfma_f32_16x16x32_bf16(Bt[n][k], At[m][k], acc[ai][bj][m][n], 0, 0, 0); __builtin_amdgcn_s_setprio(0); } while (0)
; #define PG8_WAIT_V(n) asm volatile("s_waitcnt vmcnt(" #n ")" ::: "memory")
; #define PG8_BAR __builtin_amdgcn_s_barrier()
;     __device__ __forceinline__ void operator()(const f32x4 (&acc)[2][2][4][2], const Unit& u, int wr, int wc, int fr, int fq) const {
;         const int row0 = u.pm * BM + wr * 64 + fr, col0 = u.pn * BM + wc * 32 + 4 * fq;
;         float* base = part + (size_t)u.ks * Mp * ldc;
; #pragma unroll
;         for (int ai = 0; ai < 2; ++ai)
; #pragma unroll
;             for (int m = 0; m < 4; ++m) { float* rowp = base + (size_t)(row0 + ai * HALF + m * 16) * ldc + col0;
; #pragma unroll
;                 for (int bj = 0; bj < 2; ++bj)
; #pragma unroll
;                     for (int n = 0; n < 2; ++n) *(f32x4*)(rowp + bj * HALF + n * 16) = acc[ai][bj][m][n]; }
; template <class Epi, class Sched>
; __device__ __forceinline__ void gemm_phase(LAS unsigned char* lds, const Gemm g, const Sched& S, const Epi& E) {
;     ...
;             PG8_WAIT_V(6); PG8_BAR; PG8_MMA(1, 1, At, B1); PG8_BAR;
;         }
;         E(acc, cur, wr, wc, fr, fq);
	s_setprio 1
	v_mfma_f32_16x16x32_bf16 v[62:65], v[140:143], v[160:163], v[62:65]
	v_mfma_f32_16x16x32_bf16 v[58:61], v[148:151], v[160:163], v[58:61]
	v_mfma_f32_16x16x32_bf16 v[54:57], v[140:143], v[168:171], v[54:57]
	v_mfma_f32_16x16x32_bf16 v[50:53], v[148:151], v[168:171], v[50:53]
	v_mfma_f32_16x16x32_bf16 v[38:41], v[140:143], v[176:179], v[38:41]
	v_mfma_f32_16x16x32_bf16 v[34:37], v[148:151], v[176:179], v[34:37]
	v_mfma_f32_16x16x32_bf16 v[22:25], v[140:143], v[184:187], v[22:25]
	v_mfma_f32_16x16x32_bf16 v[18:21], v[148:151], v[184:187], v[18:21]
	v_mfma_f32_16x16x32_bf16 v[62:65], v[144:147], v[164:167], v[62:65]
	v_mfma_f32_16x16x32_bf16 v[58:61], v[152:155], v[164:167], v[58:61]
	v_mfma_f32_16x16x32_bf16 v[54:57], v[144:147], v[172:175], v[54:57]
	v_mfma_f32_16x16x32_bf16 v[50:53], v[152:155], v[172:175], v[50:53]
	v_mfma_f32_16x16x32_bf16 v[38:41], v[144:147], v[180:183], v[38:41]
	v_mfma_f32_16x16x32_bf16 v[34:37], v[152:155], v[180:183], v[34:37]
	v_mfma_f32_16x16x32_bf16 v[22:25], v[144:147], v[188:191], v[22:25]
	v_mfma_f32_16x16x32_bf16 v[18:21], v[152:155], v[188:191], v[18:21]
	v_mfma_f32_16x16x32_bf16 v[46:49], v[192:195], v[160:163], v[46:49]
	v_mfma_f32_16x16x32_bf16 v[42:45], v[200:203], v[160:163], v[42:45]
	v_mfma_f32_16x16x32_bf16 v[30:33], v[192:195], v[168:171], v[30:33]
	v_mfma_f32_16x16x32_bf16 v[26:29], v[200:203], v[168:171], v[26:29]
	v_mfma_f32_16x16x32_bf16 v[14:17], v[192:195], v[176:179], v[14:17]
	v_mfma_f32_16x16x32_bf16 v[10:13], v[200:203], v[176:179], v[10:13]
	v_mfma_f32_16x16x32_bf16 v[6:9], v[192:195], v[184:187], v[6:9]
	v_mfma_f32_16x16x32_bf16 v[2:5], v[200:203], v[184:187], v[2:5]
	v_mfma_f32_16x16x32_bf16 v[46:49], v[196:199], v[164:167], v[46:49]
	v_mfma_f32_16x16x32_bf16 v[42:45], v[204:207], v[164:167], v[42:45]
	v_mfma_f32_16x16x32_bf16 v[30:33], v[196:199], v[172:175], v[30:33]
	v_mfma_f32_16x16x32_bf16 v[26:29], v[204:207], v[172:175], v[26:29]
	v_mfma_f32_16x16x32_bf16 v[14:17], v[196:199], v[180:183], v[14:17]
	v_mfma_f32_16x16x32_bf16 v[10:13], v[204:207], v[180:183], v[10:13]
	v_mfma_f32_16x16x32_bf16 v[6:9], v[196:199], v[188:191], v[6:9]
	v_mfma_f32_16x16x32_bf16 v[2:5], v[204:207], v[188:191], v[2:5]
	s_setprio 0
	s_add_i32 s73, s73, 2
	s_add_u32 s71, s71, 0x100
	s_addc_u32 s72, s72, 0
	s_cmp_gt_u32 s73, 5
	s_mov_b64 s[52:53], s[54:55]
	s_barrier
	s_cbranch_scc0 .LBB0_113
	s_ashr_i32 s11, s10, 31
	s_lshl_b64 s[10:11], s[10:11], 24
	v_lshl_or_b32 v140, s26, 8, v138
	s_add_u32 s10, s8, s10
	v_lshl_add_u32 v142, s24, 8, v136
	s_addc_u32 s11, s9, s11
	v_ashrrev_i32_e32 v141, 31, v140
	v_ashrrev_i32_e32 v143, 31, v142
	v_lshl_add_u64 v[140:141], v[140:141], 2, s[10:11]
	v_lshlrev_b64 v[144:145], 13, v[142:143]
	v_lshl_add_u64 v[144:145], v[140:141], 0, v[144:145]
	global_store_dwordx4 v[144:145], v[126:129], off
	global_store_dwordx4 v[144:145], v[122:125], off offset:64
	global_store_dwordx4 v[144:145], v[110:113], off offset:512
	global_store_dwordx4 v[144:145], v[102:105], off offset:576
	s_mov_b64 s[10:11], 0x100000
	s_mov_b32 s26, s40
	v_or_b32_e32 v102, 16, v142
	v_ashrrev_i32_e32 v103, 31, v102
	v_lshlrev_b64 v[102:103], 13, v[102:103]
	v_lshl_add_u64 v[102:103], v[140:141], 0, v[102:103]
	global_store_dwordx4 v[102:103], v[118:121], off
	global_store_dwordx4 v[102:103], v[114:117], off offset:64
	global_store_dwordx4 v[102:103], v[94:97], off offset:512
	global_store_dwordx4 v[102:103], v[86:89], off offset:576
	s_mov_b32 s24, s44
	s_mov_b64 s[54:55], s[50:51]
	v_or_b32_e32 v86, 32, v142
	v_ashrrev_i32_e32 v87, 31, v86
	v_lshlrev_b64 v[86:87], 13, v[86:87]
	v_lshl_add_u64 v[86:87], v[140:141], 0, v[86:87]
	global_store_dwordx4 v[86:87], v[106:109], off
	global_store_dwordx4 v[86:87], v[98:101], off offset:64
	global_store_dwordx4 v[86:87], v[78:81], off offset:512
	global_store_dwordx4 v[86:87], v[74:77], off offset:576
	s_mov_b64 s[52:53], s[48:49]
	s_nop 0
	v_or_b32_e32 v74, 48, v142
	v_ashrrev_i32_e32 v75, 31, v74
	v_lshlrev_b64 v[74:75], 13, v[74:75]
	v_lshl_add_u64 v[74:75], v[140:141], 0, v[74:75]
	global_store_dwordx4 v[74:75], v[90:93], off
	global_store_dwordx4 v[74:75], v[82:85], off offset:64
	global_store_dwordx4 v[74:75], v[70:73], off offset:512
	global_store_dwordx4 v[74:75], v[66:69], off offset:576
	s_nop 1
	v_add_co_u32_e32 v68, vcc, s93, v144
	v_lshl_add_u64 v[66:67], v[144:145], 0, s[10:11]
	s_nop 0
	v_addc_co_u32_e32 v69, vcc, 0, v145, vcc
	s_mov_b64 s[10:11], 0x120000
	global_store_dwordx4 v[68:69], v[62:65], off
	global_store_dwordx4 v[66:67], v[58:61], off offset:64
	global_store_dwordx4 v[66:67], v[46:49], off offset:512
	global_store_dwordx4 v[66:67], v[42:45], off offset:576
	s_nop 1
	v_lshl_add_u64 v[42:43], v[144:145], 0, s[10:11]
	s_mov_b32 s10, 0x120000
	v_add_co_u32_e32 v44, vcc, s10, v144
	s_mov_b64 s[10:11], 0x140000
	s_nop 0
	v_addc_co_u32_e32 v45, vcc, 0, v145, vcc
	global_store_dwordx4 v[44:45], v[54:57], off
	global_store_dwordx4 v[42:43], v[50:53], off offset:64
	global_store_dwordx4 v[42:43], v[30:33], off offset:512
	global_store_dwordx4 v[42:43], v[26:29], off offset:576
	s_nop 1
	v_lshl_add_u64 v[26:27], v[144:145], 0, s[10:11]
	s_mov_b32 s10, 0x140000
	v_add_co_u32_e32 v28, vcc, s10, v144
	s_mov_b64 s[10:11], 0x160000
	s_nop 0
	v_addc_co_u32_e32 v29, vcc, 0, v145, vcc
	global_store_dwordx4 v[28:29], v[38:41], off
	global_store_dwordx4 v[26:27], v[34:37], off offset:64
	global_store_dwordx4 v[26:27], v[14:17], off offset:512
	global_store_dwordx4 v[26:27], v[10:13], off offset:576
	s_nop 1
	v_add_co_u32_e32 v12, vcc, 0x160000, v144
	v_lshl_add_u64 v[10:11], v[144:145], 0, s[10:11]
	s_nop 0
	v_addc_co_u32_e32 v13, vcc, 0, v145, vcc
	s_and_b64 vcc, exec, s[46:47]
	s_mov_b32 s10, s28
	global_store_dwordx4 v[12:13], v[22:25], off
	global_store_dwordx4 v[10:11], v[18:21], off offset:64
	global_store_dwordx4 v[10:11], v[6:9], off offset:512
	global_store_dwordx4 v[10:11], v[2:5], off offset:576
	s_cbranch_vccz .LBB0_110
	s_waitcnt vmcnt(0)
	s_cmpk_gt_u32 s60, 0xff
	s_cbranch_scc1 .LBB0_117
	s_barrier

; #define PG8_STAGE(bufoff, gbase, voff) do { _Pragma("unroll") for (int _i = 0; _i < 2; ++_i) \
;         __builtin_amdgcn_global_load_lds((const unsigned*)((const char*)(gbase) + (voff)[_i]), (LAS unsigned*)(lds + (bufoff) + ldsw + _i * 8192), 16, 0, 0); } while (0)
; #define PG8_LDA(dst, b, h) do { _Pragma("unroll") for (int m = 0; m < 4; ++m) _Pragma("unroll") for (int k = 0; k < 2; ++k) dst[m][k] = *(const LAS bf16x8*)(lds + PG8_SA(b, h) + aoff + m * 2048 + k * 1024); } while (0)
; #define PG8_LDB(dst, b, h) do { _Pragma("unroll") for (int n = 0; n < 2; ++n) _Pragma("unroll") for (int k = 0; k < 2; ++k) dst[n][k] = *(const LAS bf16x8*)(lds + PG8_SB(b, h) + boff + n * 2048 + k * 1024); } while (0)
; #define PG8_MMA(ai, bj, At, Bt) do { __builtin_amdgcn_s_setprio(1); _Pragma("unroll") for (int m = 0; m < 4; ++m) _Pragma("unroll") for (int n = 0; n < 2; ++n) _Pragma("unroll") for (int k = 0; k < 2; ++k) \
;         acc[ai][bj][m][n] = __builtin_amdgcn_mfma_f32_16x16x32_bf16(Bt[n][k], At[m][k], acc[ai][bj][m][n], 0, 0, 0); __builtin_amdgcn_s_setprio(0); } while (0)
; #define PG8_WAIT_V(n) asm volatile("s_waitcnt vmcnt(" #n ")" ::: "memory")
; #define PG8_WAIT_L(n) asm volatile("s_waitcnt lgkmcnt(" #n ")" ::: "memory")
; template <class Epi, class Sched>
; __device__ __forceinline__ void gemm_phase(LAS unsigned char* lds, const Gemm g, const Sched& S, const Epi& E) {
;     ...
;         for (int t = 0; t < nt; t += 2) {
;             const bool last = (t == nt - 2);
;             const char* a1 = cA + (size_t)(t + 1) * kstep;
;             const char* a2 = last ? nA : cA + (size_t)(t + 2) * kstep; const char* b2 = last ? nB : cB + (size_t)(t + 2) * kstep;
;             const char* a3 = a2 + kstep; const char* b3 = b2 + kstep;
;             PG8_LDB(B0, 0, 0); PG8_SCHED; PG8_LDA(At, 0, 0); PG8_STAGE(PG8_SA(1, 1), a1 + hstep, voffA);
;             PG8_WAIT_L(8); PG8_BAR; PG8_WAIT_L(0); PG8_MMA(0, 0, At, B0); PG8_BAR; PG8_SCHED;
;             PG8_LDB(B1, 0, 1); PG8_STAGE(PG8_SB(0, 0), b2, voffB);
;             PG8_BAR; PG8_WAIT_L(0); PG8_MMA(0, 1, At, B1); PG8_BAR;
;             PG8_LDA(At, 0, 1); PG8_STAGE(PG8_SA(0, 0), a2, voffA);
;             PG8_BAR; PG8_WAIT_L(0); PG8_MMA(1, 0, At, B0); PG8_BAR; PG8_SCHED;
;             PG8_STAGE(PG8_SB(0, 1), b2 + hstep, voffB);
;             PG8_WAIT_V(6); PG8_BAR; PG8_MMA(1, 1, At, B1); PG8_BAR;
.LBB0_354:
	s_add_u32 s38, s50, 0xfff80080
	s_addc_u32 s39, s51, -1
	s_cmp_eq_u32 s70, 28
	s_cselect_b32 s55, s9, s39
	s_cselect_b32 s54, s66, s38
	s_cselect_b32 s53, s43, s69
	s_cselect_b32 s52, s67, s68
	v_lshl_add_u64 v[156:157], s[50:51], 0, v[138:139]
	s_add_i32 m0, s29, 0xc000
	s_nop 0
	global_load_lds_dwordx4 v[156:157], off
	v_lshl_add_u64 v[156:157], s[50:51], 0, v[136:137]
	s_add_i32 m0, s29, 0xe000
	s_nop 0
	global_load_lds_dwordx4 v[156:157], off
	s_add_i32 s71, 0, 0x10000
	v_add_u32_e32 v156, s71, v145
	ds_read_b128 v[140:143], v156
	ds_read_b128 v[148:151], v156 offset:1024
	ds_read_b128 v[152:155], v156 offset:2048
	ds_read_b128 v[160:163], v156 offset:3072
	ds_read_b128 v[164:167], v147
	ds_read_b128 v[168:171], v147 offset:1024
	ds_read_b128 v[172:175], v147 offset:2048
	ds_read_b128 v[176:179], v147 offset:3072
	ds_read_b128 v[180:183], v147 offset:4096
	ds_read_b128 v[184:187], v147 offset:5120
	ds_read_b128 v[188:191], v147 offset:6144
	ds_read_b128 v[192:195], v147 offset:7168
	s_add_i32 s38, 0, 0x14000
	v_add_u32_e32 v156, s38, v145
	ds_read_b128 v[196:199], v156
	ds_read_b128 v[200:203], v156 offset:1024
	ds_read_b128 v[204:207], v156 offset:2048
	ds_read_b128 v[210:213], v156 offset:3072
	s_waitcnt lgkmcnt(0)
	s_barrier
	s_setprio 1
	v_mfma_f32_16x16x32_bf16 v[126:129], v[140:143], v[164:167], v[126:129]
	v_mfma_f32_16x16x32_bf16 v[122:125], v[152:155], v[164:167], v[122:125]
	v_mfma_f32_16x16x32_bf16 v[118:121], v[140:143], v[172:175], v[118:121]
	v_mfma_f32_16x16x32_bf16 v[110:113], v[152:155], v[172:175], v[110:113]
	v_mfma_f32_16x16x32_bf16 v[102:105], v[140:143], v[180:183], v[102:105]
	v_mfma_f32_16x16x32_bf16 v[94:97], v[152:155], v[180:183], v[94:97]
	v_mfma_f32_16x16x32_bf16 v[86:89], v[140:143], v[188:191], v[86:89]
	v_mfma_f32_16x16x32_bf16 v[78:81], v[152:155], v[188:191], v[78:81]
	v_mfma_f32_16x16x32_bf16 v[126:129], v[148:151], v[168:171], v[126:129]
	v_mfma_f32_16x16x32_bf16 v[122:125], v[160:163], v[168:171], v[122:125]
	v_mfma_f32_16x16x32_bf16 v[118:121], v[148:151], v[176:179], v[118:121]
	v_mfma_f32_16x16x32_bf16 v[110:113], v[160:163], v[176:179], v[110:113]
	v_mfma_f32_16x16x32_bf16 v[102:105], v[148:151], v[184:187], v[102:105]
	v_mfma_f32_16x16x32_bf16 v[94:97], v[160:163], v[184:187], v[94:97]
	v_mfma_f32_16x16x32_bf16 v[86:89], v[148:151], v[192:195], v[86:89]
	v_mfma_f32_16x16x32_bf16 v[78:81], v[160:163], v[192:195], v[78:81]
	v_mfma_f32_16x16x32_bf16 v[114:117], v[196:199], v[164:167], v[114:117]
	v_mfma_f32_16x16x32_bf16 v[106:109], v[204:207], v[164:167], v[106:109]
	v_mfma_f32_16x16x32_bf16 v[98:101], v[196:199], v[172:175], v[98:101]
	v_mfma_f32_16x16x32_bf16 v[90:93], v[204:207], v[172:175], v[90:93]
	v_mfma_f32_16x16x32_bf16 v[82:85], v[196:199], v[180:183], v[82:85]
	v_mfma_f32_16x16x32_bf16 v[74:77], v[204:207], v[180:183], v[74:77]
	v_mfma_f32_16x16x32_bf16 v[70:73], v[196:199], v[188:191], v[70:73]
	v_mfma_f32_16x16x32_bf16 v[66:69], v[204:207], v[188:191], v[66:69]
	v_mfma_f32_16x16x32_bf16 v[114:117], v[200:203], v[168:171], v[114:117]
	v_mfma_f32_16x16x32_bf16 v[106:109], v[210:213], v[168:171], v[106:109]
	v_mfma_f32_16x16x32_bf16 v[98:101], v[200:203], v[176:179], v[98:101]
	v_mfma_f32_16x16x32_bf16 v[90:93], v[210:213], v[176:179], v[90:93]
	v_mfma_f32_16x16x32_bf16 v[82:85], v[200:203], v[184:187], v[82:85]
	v_mfma_f32_16x16x32_bf16 v[74:77], v[210:213], v[184:187], v[74:77]
	v_mfma_f32_16x16x32_bf16 v[70:73], v[200:203], v[192:195], v[70:73]
	v_mfma_f32_16x16x32_bf16 v[66:69], v[210:213], v[192:195], v[66:69]
	s_setprio 0
	s_barrier
	s_add_i32 s39, s71, s56
	v_lshl_add_u64 v[156:157], s[52:53], 0, v[0:1]
	s_mov_b32 m0, s39
	v_lshl_add_u64 v[214:215], s[52:53], 0, v[134:135]
	global_load_lds_dwordx4 v[156:157], off
	s_add_i32 m0, s39, 0x2000
	s_nop 0
	global_load_lds_dwordx4 v[214:215], off
	s_mov_b32 m0, s29
	v_lshl_add_u64 v[216:217], s[54:55], 0, v[130:131]
	global_load_lds_dwordx4 v[216:217], off
	v_lshl_add_u64 v[224:225], s[54:55], 0, v[132:133]
	s_mov_b32 m0, s41
	s_nop 0
	global_load_lds_dwordx4 v[224:225], off
	ds_read_b128 v[164:167], v147 offset:16384
	ds_read_b128 v[168:171], v147 offset:17408
	ds_read_b128 v[172:175], v147 offset:18432
	ds_read_b128 v[176:179], v147 offset:19456
	ds_read_b128 v[180:183], v147 offset:20480
	ds_read_b128 v[184:187], v147 offset:21504
	ds_read_b128 v[188:191], v147 offset:22528
	ds_read_b128 v[192:195], v147 offset:23552
	s_waitcnt vmcnt(4)
	s_waitcnt lgkmcnt(0)
	s_barrier
	s_setprio 1
	v_mfma_f32_16x16x32_bf16 v[62:65], v[140:143], v[164:167], v[62:65]
	v_mfma_f32_16x16x32_bf16 v[58:61], v[152:155], v[164:167], v[58:61]
	v_mfma_f32_16x16x32_bf16 v[54:57], v[140:143], v[172:175], v[54:57]
	v_mfma_f32_16x16x32_bf16 v[46:49], v[152:155], v[172:175], v[46:49]
	v_mfma_f32_16x16x32_bf16 v[38:41], v[140:143], v[180:183], v[38:41]
	v_mfma_f32_16x16x32_bf16 v[30:33], v[152:155], v[180:183], v[30:33]
	v_mfma_f32_16x16x32_bf16 v[22:25], v[140:143], v[188:191], v[22:25]
	v_mfma_f32_16x16x32_bf16 v[14:17], v[152:155], v[188:191], v[14:17]
	v_mfma_f32_16x16x32_bf16 v[62:65], v[148:151], v[168:171], v[62:65]
	v_mfma_f32_16x16x32_bf16 v[58:61], v[160:163], v[168:171], v[58:61]
	v_mfma_f32_16x16x32_bf16 v[54:57], v[148:151], v[176:179], v[54:57]
	v_mfma_f32_16x16x32_bf16 v[46:49], v[160:163], v[176:179], v[46:49]
	v_mfma_f32_16x16x32_bf16 v[38:41], v[148:151], v[184:187], v[38:41]
	v_mfma_f32_16x16x32_bf16 v[30:33], v[160:163], v[184:187], v[30:33]
	v_mfma_f32_16x16x32_bf16 v[22:25], v[148:151], v[192:195], v[22:25]
	v_mfma_f32_16x16x32_bf16 v[14:17], v[160:163], v[192:195], v[14:17]
	v_mfma_f32_16x16x32_bf16 v[50:53], v[196:199], v[164:167], v[50:53]
	v_mfma_f32_16x16x32_bf16 v[42:45], v[204:207], v[164:167], v[42:45]
	v_mfma_f32_16x16x32_bf16 v[34:37], v[196:199], v[172:175], v[34:37]
	v_mfma_f32_16x16x32_bf16 v[26:29], v[204:207], v[172:175], v[26:29]
	v_mfma_f32_16x16x32_bf16 v[18:21], v[196:199], v[180:183], v[18:21]
	v_mfma_f32_16x16x32_bf16 v[10:13], v[204:207], v[180:183], v[10:13]
	v_mfma_f32_16x16x32_bf16 v[6:9], v[196:199], v[188:191], v[6:9]
	v_mfma_f32_16x16x32_bf16 v[2:5], v[204:207], v[188:191], v[2:5]
	v_mfma_f32_16x16x32_bf16 v[50:53], v[200:203], v[168:171], v[50:53]
	v_mfma_f32_16x16x32_bf16 v[42:45], v[210:213], v[168:171], v[42:45]
	v_mfma_f32_16x16x32_bf16 v[34:37], v[200:203], v[176:179], v[34:37]
	v_mfma_f32_16x16x32_bf16 v[26:29], v[210:213], v[176:179], v[26:29]
	v_mfma_f32_16x16x32_bf16 v[18:21], v[200:203], v[184:187], v[18:21]
	v_mfma_f32_16x16x32_bf16 v[10:13], v[210:213], v[184:187], v[10:13]
	v_mfma_f32_16x16x32_bf16 v[6:9], v[200:203], v[192:195], v[6:9]
	v_mfma_f32_16x16x32_bf16 v[2:5], v[210:213], v[192:195], v[2:5]
	s_setprio 0
	s_barrier
; #define PG8_STAGE(bufoff, gbase, voff) do { _Pragma("unroll") for (int _i = 0; _i < 2; ++_i) \
;         __builtin_amdgcn_global_load_lds((const unsigned*)((const char*)(gbase) + (voff)[_i]), (LAS unsigned*)(lds + (bufoff) + ldsw + _i * 8192), 16, 0, 0); } while (0)
; #define PG8_LDA(dst, b, h) do { _Pragma("unroll") for (int m = 0; m < 4; ++m) _Pragma("unroll") for (int k = 0; k < 2; ++k) dst[m][k] = *(const LAS bf16x8*)(lds + PG8_SA(b, h) + aoff + m * 2048 + k * 1024); } while (0)
; #define PG8_LDB(dst, b, h) do { _Pragma("unroll") for (int n = 0; n < 2; ++n) _Pragma("unroll") for (int k = 0; k < 2; ++k) dst[n][k] = *(const LAS bf16x8*)(lds + PG8_SB(b, h) + boff + n * 2048 + k * 1024); } while (0)
; #define PG8_MMA(ai, bj, At, Bt) do { __builtin_amdgcn_s_setprio(1); _Pragma("unroll") for (int m = 0; m < 4; ++m) _Pragma("unroll") for (int n = 0; n < 2; ++n) _Pragma("unroll") for (int k = 0; k < 2; ++k) \
;         acc[ai][bj][m][n] = __builtin_amdgcn_mfma_f32_16x16x32_bf16(Bt[n][k], At[m][k], acc[ai][bj][m][n], 0, 0, 0); __builtin_amdgcn_s_setprio(0); } while (0)
; #define PG8_WAIT_V(n) asm volatile("s_waitcnt vmcnt(" #n ")" ::: "memory")
; #define PG8_WAIT_L(n) asm volatile("s_waitcnt lgkmcnt(" #n ")" ::: "memory")
; #define PG8_BAR __builtin_amdgcn_s_barrier()
; #define PG8_SCHED __builtin_amdgcn_sched_barrier(0)
; template <class Epi, class Sched>
; __device__ __forceinline__ void gemm_phase(LAS unsigned char* lds, const Gemm g, const Sched& S, const Epi& E) {
;     ...
;             PG8_LDB(B0, 1, 0); PG8_SCHED; PG8_LDA(At, 1, 0); PG8_STAGE(PG8_SA(0, 1), a2 + hstep, voffA);
;             PG8_WAIT_L(8); PG8_BAR; PG8_WAIT_L(0); PG8_MMA(0, 0, At, B0); PG8_BAR; PG8_SCHED;
;             PG8_LDB(B1, 1, 1); PG8_STAGE(PG8_SB(1, 0), b3, voffB);
;             PG8_BAR; PG8_WAIT_L(0); PG8_MMA(0, 1, At, B1); PG8_BAR;
;             PG8_LDA(At, 1, 1); PG8_STAGE(PG8_SA(1, 0), a3, voffA);
;             PG8_BAR; PG8_WAIT_L(0); PG8_MMA(1, 0, At, B0); PG8_BAR; PG8_SCHED;
;             PG8_STAGE(PG8_SB(1, 1), b3 + hstep, voffB);
;             PG8_WAIT_V(6); PG8_BAR; PG8_MMA(1, 1, At, B1); PG8_BAR;
	s_add_u32 s72, s52, 0x80000
	s_addc_u32 s73, s53, 0
	s_add_i32 s38, s38, s56
	v_lshl_add_u64 v[140:141], s[72:73], 0, v[0:1]
	s_mov_b32 m0, s38
	s_nop 0
	global_load_lds_dwordx4 v[140:141], off
	v_lshl_add_u64 v[140:141], s[72:73], 0, v[134:135]
	s_add_i32 m0, s38, 0x2000
	s_nop 0
	global_load_lds_dwordx4 v[140:141], off
	s_add_u32 s54, s54, 0x80000
	s_addc_u32 s55, s55, 0
	s_mov_b32 m0, s57
	v_lshl_add_u64 v[196:197], s[54:55], 0, v[130:131]
	global_load_lds_dwordx4 v[196:197], off
	v_lshl_add_u64 v[196:197], s[54:55], 0, v[132:133]
	s_mov_b32 m0, s58
	s_nop 0
	global_load_lds_dwordx4 v[196:197], off
	s_add_i32 s38, 0, 0x18000
	v_add_u32_e32 v160, s38, v145
	ds_read_b128 v[140:143], v160
	ds_read_b128 v[148:151], v160 offset:1024
	ds_read_b128 v[152:155], v160 offset:2048
	ds_read_b128 v[160:163], v160 offset:3072
	ds_read_b128 v[164:167], v147 offset:32768
	ds_read_b128 v[168:171], v147 offset:33792
	ds_read_b128 v[172:175], v147 offset:34816
	ds_read_b128 v[176:179], v147 offset:35840
	ds_read_b128 v[180:183], v147 offset:36864
	ds_read_b128 v[184:187], v147 offset:37888
	ds_read_b128 v[188:191], v147 offset:38912
	ds_read_b128 v[192:195], v147 offset:39936
	s_add_i32 s39, 0, 0x1c000
	v_add_u32_e32 v210, s39, v145
	ds_read_b128 v[196:199], v210
	ds_read_b128 v[200:203], v210 offset:1024
	ds_read_b128 v[204:207], v210 offset:2048
	ds_read_b128 v[210:213], v210 offset:3072
	s_waitcnt lgkmcnt(0)
	s_barrier
	s_setprio 1
	v_mfma_f32_16x16x32_bf16 v[126:129], v[140:143], v[164:167], v[126:129]
	v_mfma_f32_16x16x32_bf16 v[122:125], v[152:155], v[164:167], v[122:125]
	v_mfma_f32_16x16x32_bf16 v[118:121], v[140:143], v[172:175], v[118:121]
	v_mfma_f32_16x16x32_bf16 v[110:113], v[152:155], v[172:175], v[110:113]
	v_mfma_f32_16x16x32_bf16 v[102:105], v[140:143], v[180:183], v[102:105]
	v_mfma_f32_16x16x32_bf16 v[94:97], v[152:155], v[180:183], v[94:97]
	v_mfma_f32_16x16x32_bf16 v[86:89], v[140:143], v[188:191], v[86:89]
	v_mfma_f32_16x16x32_bf16 v[78:81], v[152:155], v[188:191], v[78:81]
	v_mfma_f32_16x16x32_bf16 v[126:129], v[148:151], v[168:171], v[126:129]
	v_mfma_f32_16x16x32_bf16 v[122:125], v[160:163], v[168:171], v[122:125]
	v_mfma_f32_16x16x32_bf16 v[118:121], v[148:151], v[176:179], v[118:121]
	v_mfma_f32_16x16x32_bf16 v[110:113], v[160:163], v[176:179], v[110:113]
	v_mfma_f32_16x16x32_bf16 v[102:105], v[148:151], v[184:187], v[102:105]
	v_mfma_f32_16x16x32_bf16 v[94:97], v[160:163], v[184:187], v[94:97]
	v_mfma_f32_16x16x32_bf16 v[86:89], v[148:151], v[192:195], v[86:89]
	v_mfma_f32_16x16x32_bf16 v[78:81], v[160:163], v[192:195], v[78:81]
	v_mfma_f32_16x16x32_bf16 v[114:117], v[196:199], v[164:167], v[114:117]
	v_mfma_f32_16x16x32_bf16 v[106:109], v[204:207], v[164:167], v[106:109]
	v_mfma_f32_16x16x32_bf16 v[98:101], v[196:199], v[172:175], v[98:101]
	v_mfma_f32_16x16x32_bf16 v[90:93], v[204:207], v[172:175], v[90:93]
	v_mfma_f32_16x16x32_bf16 v[82:85], v[196:199], v[180:183], v[82:85]
	v_mfma_f32_16x16x32_bf16 v[74:77], v[204:207], v[180:183], v[74:77]
	v_mfma_f32_16x16x32_bf16 v[70:73], v[196:199], v[188:191], v[70:73]
	v_mfma_f32_16x16x32_bf16 v[66:69], v[204:207], v[188:191], v[66:69]
	v_mfma_f32_16x16x32_bf16 v[114:117], v[200:203], v[168:171], v[114:117]
	v_mfma_f32_16x16x32_bf16 v[106:109], v[210:213], v[168:171], v[106:109]
	v_mfma_f32_16x16x32_bf16 v[98:101], v[200:203], v[176:179], v[98:101]
	v_mfma_f32_16x16x32_bf16 v[90:93], v[210:213], v[176:179], v[90:93]
	v_mfma_f32_16x16x32_bf16 v[82:85], v[200:203], v[184:187], v[82:85]
	v_mfma_f32_16x16x32_bf16 v[74:77], v[210:213], v[184:187], v[74:77]
	v_mfma_f32_16x16x32_bf16 v[70:73], v[200:203], v[192:195], v[70:73]
	v_mfma_f32_16x16x32_bf16 v[66:69], v[210:213], v[192:195], v[66:69]
	s_setprio 0
	s_barrier
	s_add_i32 s38, s38, s56
	v_lshl_add_u64 v[156:157], v[156:157], 0, s[36:37]
	s_mov_b32 m0, s38
	s_nop 0
	global_load_lds_dwordx4 v[156:157], off
	v_lshl_add_u64 v[156:157], v[214:215], 0, s[36:37]
	s_add_i32 m0, s38, 0x2000
	s_nop 0
	global_load_lds_dwordx4 v[156:157], off
	s_mov_b32 m0, s59
	v_lshl_add_u64 v[156:157], v[216:217], 0, s[36:37]
	global_load_lds_dwordx4 v[156:157], off
	v_lshl_add_u64 v[156:157], v[224:225], 0, s[36:37]
	s_mov_b32 m0, s60
	s_nop 0
	global_load_lds_dwordx4 v[156:157], off
	s_add_u32 s52, s52, 0x80080
	s_addc_u32 s53, s53, 0
	s_add_i32 s38, s39, s56
	v_lshl_add_u64 v[156:157], s[52:53], 0, v[0:1]
	s_mov_b32 m0, s38
	s_nop 0
	global_load_lds_dwordx4 v[156:157], off
	v_lshl_add_u64 v[156:157], s[52:53], 0, v[134:135]
	s_add_i32 m0, s38, 0x2000
	s_nop 0
	global_load_lds_dwordx4 v[156:157], off
	ds_read_b128 v[164:167], v147 offset:49152
	ds_read_b128 v[168:171], v147 offset:50176
	ds_read_b128 v[172:175], v147 offset:51200
	ds_read_b128 v[176:179], v147 offset:52224
	ds_read_b128 v[180:183], v147 offset:53248
	ds_read_b128 v[184:187], v147 offset:54272
	ds_read_b128 v[188:191], v147 offset:55296
	ds_read_b128 v[192:195], v147 offset:56320
	s_waitcnt vmcnt(6)
	s_waitcnt lgkmcnt(0)
	s_barrier
; __device__ __forceinline__ unsigned cvt_pk_bf16(float lo, float hi) { unsigned r; asm("v_cvt_pk_bf16_f32 %0, %1, %2" : "=v"(r) : "v"(lo), "v"(hi)); return r; }
; #define PG8_MMA(ai, bj, At, Bt) do { __builtin_amdgcn_s_setprio(1); _Pragma("unroll") for (int m = 0; m < 4; ++m) _Pragma("unroll") for (int n = 0; n < 2; ++n) _Pragma("unroll") for (int k = 0; k < 2; ++k) \
;         acc[ai][bj][m][n] = __builtin_amdgcn_mfma_f32_16x16x32_bf16(Bt[n][k], At[m][k], acc[ai][bj][m][n], 0, 0, 0); __builtin_amdgcn_s_setprio(0); } while (0)
; #define PG8_WAIT_V(n) asm volatile("s_waitcnt vmcnt(" #n ")" ::: "memory")
; #define PG8_BAR __builtin_amdgcn_s_barrier()
;     __device__ __forceinline__ void operator()(const f32x4 (&acc)[2][2][4][2], const Unit& u, int wr, int wc, int fr, int fq) const {
;         const int row0 = u.pm * BM + wr * 64 + fr, col0 = u.pn * BM + wc * 32 + 8 * fq;
; #pragma unroll
;         for (int ai = 0; ai < 2; ++ai)
; #pragma unroll
;             for (int m = 0; m < 4; ++m) { bf16_t* rowp = O + (size_t)(row0 + ai * HALF + m * 16) * ldc + col0;
; #pragma unroll
;                 for (int bj = 0; bj < 2; ++bj) { f32x4 v0 = acc[ai][bj][m][0], v1 = acc[ai][bj][m][1];
;                     if (ACT == 1) {
; #pragma unroll
;                         for (int j = 0; j < 4; ++j) { float a = fmaxf(v0[j], 0.f), b = fmaxf(v1[j], 0.f); v0[j] = a * a; v1[j] = b * b; } }
;                     u32x4 w; w.x = cvt_pk_bf16(v0[0], v0[1]); w.y = cvt_pk_bf16(v0[2], v0[3]); w.z = cvt_pk_bf16(v1[0], v1[1]); w.w = cvt_pk_bf16(v1[2], v1[3]);
;                     if (ACT == 1) __builtin_nontemporal_store(w, (u32x4*)(rowp + bj * HALF));
;                     else *(u32x4*)(rowp + bj * HALF) = w; } }
; template <class Epi, class Sched>
; __device__ __forceinline__ void gemm_phase(LAS unsigned char* lds, const Gemm g, const Sched& S, const Epi& E) {
;     ...
;             PG8_WAIT_V(6); PG8_BAR; PG8_MMA(1, 1, At, B1); PG8_BAR;
;         }
;         E(acc, cur, wr, wc, fr, fq);
	s_setprio 1
	v_mfma_f32_16x16x32_bf16 v[62:65], v[140:143], v[164:167], v[62:65]
	v_mfma_f32_16x16x32_bf16 v[58:61], v[152:155], v[164:167], v[58:61]
	v_mfma_f32_16x16x32_bf16 v[54:57], v[140:143], v[172:175], v[54:57]
	v_mfma_f32_16x16x32_bf16 v[46:49], v[152:155], v[172:175], v[46:49]
	v_mfma_f32_16x16x32_bf16 v[38:41], v[140:143], v[180:183], v[38:41]
	v_mfma_f32_16x16x32_bf16 v[30:33], v[152:155], v[180:183], v[30:33]
	v_mfma_f32_16x16x32_bf16 v[22:25], v[140:143], v[188:191], v[22:25]
	v_mfma_f32_16x16x32_bf16 v[14:17], v[152:155], v[188:191], v[14:17]
	v_mfma_f32_16x16x32_bf16 v[62:65], v[148:151], v[168:171], v[62:65]
	v_mfma_f32_16x16x32_bf16 v[58:61], v[160:163], v[168:171], v[58:61]
	v_mfma_f32_16x16x32_bf16 v[54:57], v[148:151], v[176:179], v[54:57]
	v_mfma_f32_16x16x32_bf16 v[46:49], v[160:163], v[176:179], v[46:49]
	v_mfma_f32_16x16x32_bf16 v[38:41], v[148:151], v[184:187], v[38:41]
	v_mfma_f32_16x16x32_bf16 v[30:33], v[160:163], v[184:187], v[30:33]
	v_mfma_f32_16x16x32_bf16 v[22:25], v[148:151], v[192:195], v[22:25]
	v_mfma_f32_16x16x32_bf16 v[14:17], v[160:163], v[192:195], v[14:17]
	v_mfma_f32_16x16x32_bf16 v[50:53], v[196:199], v[164:167], v[50:53]
	v_mfma_f32_16x16x32_bf16 v[42:45], v[204:207], v[164:167], v[42:45]
	v_mfma_f32_16x16x32_bf16 v[34:37], v[196:199], v[172:175], v[34:37]
	v_mfma_f32_16x16x32_bf16 v[26:29], v[204:207], v[172:175], v[26:29]
	v_mfma_f32_16x16x32_bf16 v[18:21], v[196:199], v[180:183], v[18:21]
	v_mfma_f32_16x16x32_bf16 v[10:13], v[204:207], v[180:183], v[10:13]
	v_mfma_f32_16x16x32_bf16 v[6:9], v[196:199], v[188:191], v[6:9]
	v_mfma_f32_16x16x32_bf16 v[2:5], v[204:207], v[188:191], v[2:5]
	v_mfma_f32_16x16x32_bf16 v[50:53], v[200:203], v[168:171], v[50:53]
	v_mfma_f32_16x16x32_bf16 v[42:45], v[210:213], v[168:171], v[42:45]
	v_mfma_f32_16x16x32_bf16 v[34:37], v[200:203], v[176:179], v[34:37]
	v_mfma_f32_16x16x32_bf16 v[26:29], v[210:213], v[176:179], v[26:29]
	v_mfma_f32_16x16x32_bf16 v[18:21], v[200:203], v[184:187], v[18:21]
	v_mfma_f32_16x16x32_bf16 v[10:13], v[210:213], v[184:187], v[10:13]
	v_mfma_f32_16x16x32_bf16 v[6:9], v[200:203], v[192:195], v[6:9]
	v_mfma_f32_16x16x32_bf16 v[2:5], v[210:213], v[192:195], v[2:5]
	s_setprio 0
	s_add_i32 s70, s70, 2
	s_add_u32 s68, s68, 0x100
	s_addc_u32 s69, s69, 0
	s_add_u32 s50, s50, 0x100
	s_addc_u32 s51, s51, 0
	s_cmp_gt_u32 s70, 29
	s_barrier
	s_cbranch_scc0 .LBB0_354
	s_load_dwordx2 s[50:51], s[0:1], 0xc0
	v_lshl_add_u32 v150, s28, 8, v144
	v_lshl_or_b32 v142, s40, 8, v146
	v_ashrrev_i32_e32 v143, 31, v142
	v_cvt_pk_bf16_f32 v70, v70, v71
	s_waitcnt lgkmcnt(0)
	v_mov_b64_e32 v[140:141], s[50:51]
	v_cvt_pk_bf16_f32 v71, v72, v73
	v_cvt_pk_bf16_f32 v72, v66, v67
	v_add_u32_e32 v66, 0x80, v150
	v_mad_i64_i32 v[148:149], s[50:51], v150, s17, v[140:141]
	v_lshlrev_b64 v[142:143], 1, v[142:143]
	v_cvt_pk_bf16_f32 v114, v114, v115
	v_cvt_pk_bf16_f32 v115, v116, v117
	v_cvt_pk_bf16_f32 v116, v106, v107
	v_or_b32_e32 v106, 16, v150
	v_mad_i64_i32 v[66:67], s[50:51], v66, s17, v[140:141]
	v_cvt_pk_bf16_f32 v50, v50, v51
	v_cvt_pk_bf16_f32 v51, v52, v53
	v_cvt_pk_bf16_f32 v52, v42, v43
	v_add_u32_e32 v42, 0x90, v150
	v_lshl_add_u64 v[148:149], v[148:149], 0, v[142:143]
	v_mad_i64_i32 v[106:107], s[50:51], v106, s17, v[140:141]
	v_cvt_pk_bf16_f32 v98, v98, v99
	v_cvt_pk_bf16_f32 v99, v100, v101
	v_cvt_pk_bf16_f32 v100, v90, v91
	v_or_b32_e32 v90, 32, v150
	v_lshl_add_u64 v[66:67], v[66:67], 0, v[142:143]
	v_mad_i64_i32 v[42:43], s[50:51], v42, s17, v[140:141]
	v_cvt_pk_bf16_f32 v34, v34, v35
	v_cvt_pk_bf16_f32 v35, v36, v37
	v_cvt_pk_bf16_f32 v36, v26, v27
	v_add_u32_e32 v26, 0xa0, v150
	v_cvt_pk_bf16_f32 v117, v108, v109
	global_store_dwordx4 v[148:149], v[114:117], off offset:256
	v_mad_i64_i32 v[90:91], s[50:51], v90, s17, v[140:141]
	s_nop 0
	v_lshl_add_u64 v[114:115], v[106:107], 0, v[142:143]
	v_cvt_pk_bf16_f32 v82, v82, v83
	v_cvt_pk_bf16_f32 v83, v84, v85
	v_cvt_pk_bf16_f32 v84, v74, v75
	v_or_b32_e32 v74, 48, v150
	v_cvt_pk_bf16_f32 v53, v44, v45
	global_store_dwordx4 v[66:67], v[50:53], off offset:256
	v_mad_i64_i32 v[26:27], s[50:51], v26, s17, v[140:141]
	s_nop 0
	v_lshl_add_u64 v[50:51], v[42:43], 0, v[142:143]
	v_cvt_pk_bf16_f32 v18, v18, v19
	v_cvt_pk_bf16_f32 v19, v20, v21
	v_cvt_pk_bf16_f32 v20, v10, v11
	v_add_u32_e32 v10, 0xb0, v150
	v_cvt_pk_bf16_f32 v101, v92, v93
	global_store_dwordx4 v[114:115], v[98:101], off offset:256
	v_mad_i64_i32 v[74:75], s[50:51], v74, s17, v[140:141]
	s_nop 0
	v_lshl_add_u64 v[98:99], v[90:91], 0, v[142:143]
	v_cvt_pk_bf16_f32 v37, v28, v29
	global_store_dwordx4 v[50:51], v[34:37], off offset:256
	v_mad_i64_i32 v[10:11], s[50:51], v10, s17, v[140:141]
	s_nop 0
	v_lshl_add_u64 v[34:35], v[26:27], 0, v[142:143]
	v_cvt_pk_bf16_f32 v85, v76, v77
	global_store_dwordx4 v[98:99], v[82:85], off offset:256
	v_cvt_pk_bf16_f32 v21, v12, v13
	global_store_dwordx4 v[34:35], v[18:21], off offset:256
	s_and_b64 vcc, exec, s[46:47]
	v_lshl_add_u64 v[82:83], v[74:75], 0, v[142:143]
	v_lshl_add_u64 v[18:19], v[10:11], 0, v[142:143]
	s_mov_b32 s40, s42
	s_mov_b32 s28, s8
	s_mov_b32 s43, s42
	s_mov_b32 s46, s8
	s_mov_b64 s[50:51], s[48:49]
	s_mov_b64 s[52:53], s[44:45]
	v_cvt_pk_bf16_f32 v126, v126, v127
	v_cvt_pk_bf16_f32 v127, v128, v129
	v_cvt_pk_bf16_f32 v128, v122, v123
	v_cvt_pk_bf16_f32 v129, v124, v125
	global_store_dwordx4 v[148:149], v[126:129], off
	v_cvt_pk_bf16_f32 v106, v118, v119
	v_cvt_pk_bf16_f32 v107, v120, v121
	v_cvt_pk_bf16_f32 v108, v110, v111
	v_cvt_pk_bf16_f32 v109, v112, v113
	global_store_dwordx4 v[114:115], v[106:109], off
	v_cvt_pk_bf16_f32 v90, v102, v103
	v_cvt_pk_bf16_f32 v91, v104, v105
	v_cvt_pk_bf16_f32 v92, v94, v95
	v_cvt_pk_bf16_f32 v93, v96, v97
	global_store_dwordx4 v[98:99], v[90:93], off
	v_cvt_pk_bf16_f32 v74, v86, v87
	v_cvt_pk_bf16_f32 v75, v88, v89
	v_cvt_pk_bf16_f32 v76, v78, v79
	v_cvt_pk_bf16_f32 v77, v80, v81
	global_store_dwordx4 v[82:83], v[74:77], off
	v_cvt_pk_bf16_f32 v73, v68, v69
	global_store_dwordx4 v[82:83], v[70:73], off offset:256
	v_cvt_pk_bf16_f32 v62, v62, v63
	v_cvt_pk_bf16_f32 v63, v64, v65
	v_cvt_pk_bf16_f32 v64, v58, v59
	v_cvt_pk_bf16_f32 v65, v60, v61
	global_store_dwordx4 v[66:67], v[62:65], off
	v_cvt_pk_bf16_f32 v42, v54, v55
	v_cvt_pk_bf16_f32 v43, v56, v57
	v_cvt_pk_bf16_f32 v44, v46, v47
	v_cvt_pk_bf16_f32 v45, v48, v49
	global_store_dwordx4 v[50:51], v[42:45], off
	v_cvt_pk_bf16_f32 v26, v38, v39
	v_cvt_pk_bf16_f32 v27, v40, v41
	v_cvt_pk_bf16_f32 v28, v30, v31
	v_cvt_pk_bf16_f32 v29, v32, v33
	global_store_dwordx4 v[34:35], v[26:29], off
	v_cvt_pk_bf16_f32 v10, v22, v23
	v_cvt_pk_bf16_f32 v11, v24, v25
	v_cvt_pk_bf16_f32 v12, v14, v15
	v_cvt_pk_bf16_f32 v13, v16, v17
	global_store_dwordx4 v[18:19], v[10:13], off
	v_cvt_pk_bf16_f32 v6, v6, v7
	v_cvt_pk_bf16_f32 v7, v8, v9
	v_cvt_pk_bf16_f32 v8, v2, v3
	v_cvt_pk_bf16_f32 v9, v4, v5
	global_store_dwordx4 v[18:19], v[6:9], off offset:256
	s_cbranch_vccz .LBB0_346
	s_waitcnt vmcnt(0)
	s_cmpk_gt_u32 s25, 0xff
	s_cbranch_scc1 .LBB0_358
	s_barrier
